# adds: SSD latent units at setprio 3, attention KV loop with batched LDS fragment reads, IEEE div sequences in silu/sigmoid epilogues replaced by v_rcp_f32 (f32, 1 ulp)
# speedup vs baseline: 1.0294x; 1.0294x over previous
.LBB0_740:
	v_ashrrev_i32_e32 v6, 3, v5
	v_cmp_lt_u32_e32 vcc, 7, v5
	s_movk_i32 s40, 0x81
	s_or_b64 s[28:29], s[22:23], vcc
	v_cmp_ne_u32_e32 vcc, s40, v6
	s_or_b64 s[40:41], s[24:25], vcc
	v_and_b32_e32 v7, 56, v4
	s_and_b64 s[40:41], s[28:29], s[40:41]
	v_mov_b32_e32 v0, 0
	v_mov_b32_e32 v1, 0
	v_mov_b32_e32 v2, 0
	v_mov_b32_e32 v3, 0
	s_and_saveexec_b64 s[28:29], s[40:41]
	s_cbranch_execz .LBB0_739
	v_add_u32_e32 v2, s39, v6
	v_mov_b64_e32 v[0:1], s[4:5]
	v_mad_i64_i32 v[0:1], s[40:41], v2, s33, v[0:1]
	v_lshl_add_u64 v[0:1], s[18:19], 1, v[0:1]
	v_lshlrev_b32_e32 v128, 1, v7
	v_lshl_add_u64 v[0:1], v[0:1], 0, v[128:129]
	v_add_co_u32_e32 v0, vcc, 0x1000, v0
	s_nop 1
	s_nop 0
	v_addc_co_u32_e32 v1, vcc, 0, v1, vcc
	global_load_dwordx4 v[0:3], v[0:1], off offset:1024
	s_branch .LBB0_739
.LBB0_742:
	s_or_b64 exec, exec, s[20:21]
	s_cmp_gt_i32 s2, 15
	s_waitcnt lgkmcnt(0)
	s_barrier
	s_cbranch_scc0 .LBB0_744
	v_or_b32_e32 v128, s18, v44
	v_add_u32_e32 v0, s18, v53
	v_add_u32_e32 v2, s18, v54
	v_lshlrev_b64 v[4:5], 2, v[128:129]
	v_mov_b32_e32 v1, v129
	v_mov_b32_e32 v3, v129
	v_lshl_add_u64 v[6:7], s[10:11], 0, v[4:5]
	v_lshl_add_u64 v[8:9], v[0:1], 2, s[10:11]
	v_lshl_add_u64 v[12:13], v[2:3], 2, s[10:11]
	v_lshl_add_u64 v[28:29], s[14:15], 0, v[4:5]
	ds_read_b128 v[32:35], v59
	ds_read_b128 v[36:39], v59 offset:144
	ds_read_b128 v[40:43], v59 offset:288
	global_load_dwordx4 v[0:3], v[6:7], off offset:16
	global_load_dwordx4 v[16:19], v[6:7], off
	s_nop 0
	global_load_dwordx4 v[4:7], v[8:9], off offset:16
	global_load_dwordx4 v[20:23], v[8:9], off
	s_nop 0
	global_load_dwordx4 v[8:11], v[12:13], off offset:16
	global_load_dwordx4 v[24:27], v[12:13], off
	s_nop 0
	global_load_dwordx4 v[12:15], v[28:29], off offset:16
	s_nop 0
	global_load_dwordx4 v[28:31], v[28:29], off
	s_mov_b32 s19, s3
	s_waitcnt lgkmcnt(2)
	v_lshlrev_b32_e32 v50, 16, v32
	s_waitcnt lgkmcnt(1)
	v_lshlrev_b32_e32 v66, 16, v36
	v_and_b32_e32 v67, 0xffff0000, v36
	v_and_b32_e32 v51, 0xffff0000, v32
	s_waitcnt lgkmcnt(0)
	v_lshlrev_b32_e32 v68, 16, v40
	v_and_b32_e32 v69, 0xffff0000, v40
	s_lshl_b64 s[20:21], s[18:19], 1
	s_add_u32 s20, s8, s20
	s_addc_u32 s21, s9, s21
	v_lshlrev_b32_e32 v128, 1, v44
	s_waitcnt vmcnt(4)
	v_pk_mul_f32 v[66:67], v[20:21], v[66:67]
	s_nop 0
	v_pk_fma_f32 v[50:51], v[16:17], v[50:51], v[66:67]
	s_waitcnt vmcnt(2)
	v_pk_fma_f32 v[50:51], v[24:25], v[68:69], v[50:51]
	s_waitcnt vmcnt(0)
	v_pk_add_f32 v[50:51], v[28:29], v[50:51]
	s_nop 0
	v_mul_f32_e32 v32, 0xbfb8aa3b, v50
	v_exp_f32_e32 v66, v32
	v_mul_f32_e32 v32, 0xbfb8aa3b, v51
	v_exp_f32_e32 v67, v32
	s_nop 0
	v_pk_add_f32 v[66:67], v[66:67], 1.0 op_sel_hi:[1,0]
	s_nop 0
	s_nop 0
	v_rcp_f32_e32 v32, v67
	s_nop 0
	v_mul_f32_e32 v51, v51, v32
	s_nop 0
	v_lshlrev_b32_e32 v36, 16, v37
	v_and_b32_e32 v37, 0xffff0000, v37
	v_rcp_f32_e32 v32, v66
	s_nop 0
	v_mul_f32_e32 v50, v50, v32
	v_lshlrev_b32_e32 v32, 16, v33
	v_and_b32_e32 v33, 0xffff0000, v33
	v_pk_mul_f32 v[36:37], v[22:23], v[36:37]
	v_lshlrev_b32_e32 v40, 16, v41
	v_and_b32_e32 v41, 0xffff0000, v41
	v_pk_fma_f32 v[32:33], v[18:19], v[32:33], v[36:37]
	s_nop 0
	v_pk_fma_f32 v[32:33], v[26:27], v[40:41], v[32:33]
	s_nop 0
	v_pk_add_f32 v[32:33], v[30:31], v[32:33]
	s_nop 0
	v_mul_f32_e32 v36, 0xbfb8aa3b, v32
	v_mul_f32_e32 v37, 0xbfb8aa3b, v33
	v_exp_f32_e32 v36, v36
	v_exp_f32_e32 v37, v37
	s_nop 0
	v_pk_add_f32 v[36:37], v[36:37], 1.0 op_sel_hi:[1,0]
	s_nop 0
	s_nop 0
	v_rcp_f32_e32 v40, v37
	s_nop 0
	v_mul_f32_e32 v65, v33, v40
	s_nop 0
	v_rcp_f32_e32 v33, v36
	s_nop 0
	v_mul_f32_e32 v66, v32, v33
	v_lshlrev_b32_e32 v36, 16, v38
	v_and_b32_e32 v37, 0xffff0000, v38
	v_lshlrev_b32_e32 v32, 16, v34
	v_and_b32_e32 v33, 0xffff0000, v34
	v_pk_mul_f32 v[36:37], v[4:5], v[36:37]
	v_lshlrev_b32_e32 v40, 16, v42
	v_and_b32_e32 v41, 0xffff0000, v42
	v_pk_fma_f32 v[32:33], v[0:1], v[32:33], v[36:37]
	s_nop 0
	v_pk_fma_f32 v[32:33], v[8:9], v[40:41], v[32:33]
	s_nop 0
	v_pk_add_f32 v[32:33], v[12:13], v[32:33]
	s_nop 0
	v_mul_f32_e32 v34, 0xbfb8aa3b, v32
	v_exp_f32_e32 v36, v34
	v_mul_f32_e32 v34, 0xbfb8aa3b, v33
	v_exp_f32_e32 v37, v34
	s_nop 0
	v_pk_add_f32 v[36:37], v[36:37], 1.0 op_sel_hi:[1,0]
	s_nop 0
	s_nop 0
	v_rcp_f32_e32 v34, v37
	s_nop 0
	v_mul_f32_e32 v38, v33, v34
	s_nop 0
	v_rcp_f32_e32 v33, v36
	s_nop 0
	v_mul_f32_e32 v40, v32, v33
	v_lshlrev_b32_e32 v32, 16, v35
	v_and_b32_e32 v33, 0xffff0000, v35
	v_lshlrev_b32_e32 v34, 16, v39
	v_and_b32_e32 v35, 0xffff0000, v39
	v_pk_mul_f32 v[34:35], v[6:7], v[34:35]
	v_lshlrev_b32_e32 v36, 16, v43
	v_and_b32_e32 v37, 0xffff0000, v43
	v_pk_fma_f32 v[32:33], v[2:3], v[32:33], v[34:35]
	s_nop 0
	v_pk_fma_f32 v[32:33], v[10:11], v[36:37], v[32:33]
	s_nop 0
	v_pk_add_f32 v[32:33], v[14:15], v[32:33]
	s_nop 0
	v_mul_f32_e32 v34, 0xbfb8aa3b, v32
	v_mul_f32_e32 v35, 0xbfb8aa3b, v33
	v_exp_f32_e32 v34, v34
	v_exp_f32_e32 v35, v35
	s_nop 0
	v_pk_add_f32 v[34:35], v[34:35], 1.0 op_sel_hi:[1,0]
	s_nop 0
	s_nop 0
	v_rcp_f32_e32 v36, v35
	s_nop 0
	v_mul_f32_e32 v35, v33, v36
	s_nop 0
	v_rcp_f32_e32 v33, v34
	s_nop 0
	v_mul_f32_e32 v36, v32, v33
	v_cvt_pk_bf16_f32 v32, v50, v51
	v_add_u32_e32 v50, s17, v55
	v_ashrrev_i32_e32 v51, 31, v50
	v_cvt_pk_bf16_f32 v35, v36, v35
	v_lshlrev_b64 v[36:37], 10, v[50:51]
	v_lshl_add_u64 v[36:37], s[20:21], 0, v[36:37]
	v_lshl_add_u64 v[36:37], v[36:37], 0, v[128:129]
	s_mov_b32 s17, 0x12d1f000
	v_add_co_u32_e32 v36, vcc, s17, v36
	v_cvt_pk_bf16_f32 v33, v66, v65
	v_cvt_pk_bf16_f32 v34, v40, v38
	v_addc_co_u32_e32 v37, vcc, 0, v37, vcc
	global_store_dwordx4 v[36:37], v[32:35], off offset:2048
	ds_read_b128 v[32:35], v59 offset:4608
	ds_read_b128 v[36:39], v60 offset:144
	ds_read_b128 v[40:43], v60 offset:288
	s_waitcnt lgkmcnt(2)
	v_lshlrev_b32_e32 v66, 16, v32
	s_waitcnt lgkmcnt(1)
	v_lshlrev_b32_e32 v68, 16, v36
	v_and_b32_e32 v69, 0xffff0000, v36
	v_and_b32_e32 v67, 0xffff0000, v32
	v_pk_mul_f32 v[68:69], v[20:21], v[68:69]
	s_waitcnt lgkmcnt(0)
	v_lshlrev_b32_e32 v70, 16, v40
	v_and_b32_e32 v71, 0xffff0000, v40
	v_pk_fma_f32 v[66:67], v[16:17], v[66:67], v[68:69]
	s_nop 0
	v_pk_fma_f32 v[66:67], v[24:25], v[70:71], v[66:67]
	s_nop 0
	v_pk_add_f32 v[66:67], v[28:29], v[66:67]
	s_nop 0
	v_mul_f32_e32 v32, 0xbfb8aa3b, v66
	v_exp_f32_e32 v68, v32
	v_mul_f32_e32 v32, 0xbfb8aa3b, v67
	v_exp_f32_e32 v69, v32
	s_nop 0
	v_pk_add_f32 v[68:69], v[68:69], 1.0 op_sel_hi:[1,0]
	s_nop 0
	s_nop 0
	v_rcp_f32_e32 v32, v69
	s_nop 0
	v_mul_f32_e32 v51, v67, v32
	s_nop 0
	v_lshlrev_b32_e32 v36, 16, v37
	v_and_b32_e32 v37, 0xffff0000, v37
	v_rcp_f32_e32 v32, v68
	s_nop 0
	v_mul_f32_e32 v65, v66, v32
	v_lshlrev_b32_e32 v32, 16, v33
	v_and_b32_e32 v33, 0xffff0000, v33
	v_pk_mul_f32 v[36:37], v[22:23], v[36:37]
	v_lshlrev_b32_e32 v40, 16, v41
	v_and_b32_e32 v41, 0xffff0000, v41
	v_pk_fma_f32 v[32:33], v[18:19], v[32:33], v[36:37]
	s_nop 0
	v_pk_fma_f32 v[32:33], v[26:27], v[40:41], v[32:33]
	s_nop 0
	v_pk_add_f32 v[32:33], v[30:31], v[32:33]
	s_nop 0
	v_mul_f32_e32 v36, 0xbfb8aa3b, v32
	v_mul_f32_e32 v37, 0xbfb8aa3b, v33
	v_exp_f32_e32 v36, v36
	v_exp_f32_e32 v37, v37
	s_nop 0
	v_pk_add_f32 v[36:37], v[36:37], 1.0 op_sel_hi:[1,0]
	s_nop 0
	s_nop 0
	v_rcp_f32_e32 v40, v37
	s_nop 0
	v_mul_f32_e32 v66, v33, v40
	s_nop 0
	v_rcp_f32_e32 v33, v36
	s_nop 0
	v_mul_f32_e32 v67, v32, v33
	v_lshlrev_b32_e32 v36, 16, v38
	v_and_b32_e32 v37, 0xffff0000, v38
	v_lshlrev_b32_e32 v32, 16, v34
	v_and_b32_e32 v33, 0xffff0000, v34
	v_pk_mul_f32 v[36:37], v[4:5], v[36:37]
	v_lshlrev_b32_e32 v40, 16, v42
	v_and_b32_e32 v41, 0xffff0000, v42
	v_pk_fma_f32 v[32:33], v[0:1], v[32:33], v[36:37]
	s_nop 0
	v_pk_fma_f32 v[32:33], v[8:9], v[40:41], v[32:33]
	s_nop 0
	v_pk_add_f32 v[32:33], v[12:13], v[32:33]
	s_nop 0
	v_mul_f32_e32 v34, 0xbfb8aa3b, v32
	v_exp_f32_e32 v36, v34
	v_mul_f32_e32 v34, 0xbfb8aa3b, v33
	v_exp_f32_e32 v37, v34
	s_nop 0
	v_pk_add_f32 v[36:37], v[36:37], 1.0 op_sel_hi:[1,0]
	s_nop 0
	s_nop 0
	v_rcp_f32_e32 v34, v37
	s_nop 0
	v_mul_f32_e32 v38, v33, v34
	s_nop 0
	v_rcp_f32_e32 v33, v36
	s_nop 0
	v_mul_f32_e32 v40, v32, v33
	v_lshlrev_b32_e32 v32, 16, v35
	v_and_b32_e32 v33, 0xffff0000, v35
	v_lshlrev_b32_e32 v34, 16, v39
	v_and_b32_e32 v35, 0xffff0000, v39
	v_pk_mul_f32 v[34:35], v[6:7], v[34:35]
	v_lshlrev_b32_e32 v36, 16, v43
	v_and_b32_e32 v37, 0xffff0000, v43
	v_pk_fma_f32 v[32:33], v[2:3], v[32:33], v[34:35]
	s_nop 0
	v_pk_fma_f32 v[32:33], v[10:11], v[36:37], v[32:33]
	s_nop 0
	v_pk_add_f32 v[32:33], v[14:15], v[32:33]
	s_nop 0
	v_mul_f32_e32 v34, 0xbfb8aa3b, v32
	v_mul_f32_e32 v35, 0xbfb8aa3b, v33
	v_exp_f32_e32 v34, v34
	v_exp_f32_e32 v35, v35
	s_nop 0
	v_pk_add_f32 v[34:35], v[34:35], 1.0 op_sel_hi:[1,0]
	s_nop 0
	s_nop 0
	v_rcp_f32_e32 v36, v35
	s_nop 0
	v_mul_f32_e32 v35, v33, v36
	s_nop 0
	v_rcp_f32_e32 v33, v34
	s_nop 0
	v_mul_f32_e32 v36, v32, v33
	v_cvt_pk_bf16_f32 v35, v36, v35
	v_add_u32_e32 v36, 32, v50
	v_ashrrev_i32_e32 v37, 31, v36
	v_lshlrev_b64 v[36:37], 10, v[36:37]
	v_lshl_add_u64 v[36:37], s[20:21], 0, v[36:37]
	v_lshl_add_u64 v[36:37], v[36:37], 0, v[128:129]
	v_add_co_u32_e32 v36, vcc, s17, v36
	v_cvt_pk_bf16_f32 v32, v65, v51
	v_cvt_pk_bf16_f32 v33, v67, v66
	v_cvt_pk_bf16_f32 v34, v40, v38
	v_addc_co_u32_e32 v37, vcc, 0, v37, vcc
	global_store_dwordx4 v[36:37], v[32:35], off offset:2048
	ds_read_b128 v[32:35], v60 offset:4608
	ds_read_b128 v[36:39], v61 offset:144
	ds_read_b128 v[40:43], v61 offset:288
	s_waitcnt lgkmcnt(2)
	v_lshlrev_b32_e32 v66, 16, v32
	s_waitcnt lgkmcnt(1)
	v_lshlrev_b32_e32 v68, 16, v36
	v_and_b32_e32 v69, 0xffff0000, v36
	v_and_b32_e32 v67, 0xffff0000, v32
	v_pk_mul_f32 v[68:69], v[20:21], v[68:69]
	s_waitcnt lgkmcnt(0)
	v_lshlrev_b32_e32 v70, 16, v40
	v_and_b32_e32 v71, 0xffff0000, v40
	v_pk_fma_f32 v[66:67], v[16:17], v[66:67], v[68:69]
	s_nop 0
	v_pk_fma_f32 v[66:67], v[24:25], v[70:71], v[66:67]
	s_nop 0
	v_pk_add_f32 v[66:67], v[28:29], v[66:67]
	s_nop 0
	v_mul_f32_e32 v32, 0xbfb8aa3b, v66
	v_exp_f32_e32 v68, v32
	v_mul_f32_e32 v32, 0xbfb8aa3b, v67
	v_exp_f32_e32 v69, v32
	s_nop 0
	v_pk_add_f32 v[68:69], v[68:69], 1.0 op_sel_hi:[1,0]
	s_nop 0
	s_nop 0
	v_rcp_f32_e32 v32, v69
	s_nop 0
	v_mul_f32_e32 v51, v67, v32
	s_nop 0
	v_lshlrev_b32_e32 v36, 16, v37
	v_and_b32_e32 v37, 0xffff0000, v37
	v_rcp_f32_e32 v32, v68
	s_nop 0
	v_mul_f32_e32 v65, v66, v32
	v_lshlrev_b32_e32 v32, 16, v33
	v_and_b32_e32 v33, 0xffff0000, v33
	v_pk_mul_f32 v[36:37], v[22:23], v[36:37]
	v_lshlrev_b32_e32 v40, 16, v41
	v_and_b32_e32 v41, 0xffff0000, v41
	v_pk_fma_f32 v[32:33], v[18:19], v[32:33], v[36:37]
	s_nop 0
	v_pk_fma_f32 v[32:33], v[26:27], v[40:41], v[32:33]
	s_nop 0
	v_pk_add_f32 v[32:33], v[30:31], v[32:33]
	s_nop 0
	v_mul_f32_e32 v36, 0xbfb8aa3b, v32
	v_mul_f32_e32 v37, 0xbfb8aa3b, v33
	v_exp_f32_e32 v36, v36
	v_exp_f32_e32 v37, v37
	s_nop 0
	v_pk_add_f32 v[36:37], v[36:37], 1.0 op_sel_hi:[1,0]
	s_nop 0
	s_nop 0
	v_rcp_f32_e32 v40, v37
	s_nop 0
	v_mul_f32_e32 v66, v33, v40
	s_nop 0
	v_rcp_f32_e32 v33, v36
	s_nop 0
	v_mul_f32_e32 v67, v32, v33
	v_lshlrev_b32_e32 v36, 16, v38
	v_and_b32_e32 v37, 0xffff0000, v38
	v_lshlrev_b32_e32 v32, 16, v34
	v_and_b32_e32 v33, 0xffff0000, v34
	v_pk_mul_f32 v[36:37], v[4:5], v[36:37]
	v_lshlrev_b32_e32 v40, 16, v42
	v_and_b32_e32 v41, 0xffff0000, v42
	v_pk_fma_f32 v[32:33], v[0:1], v[32:33], v[36:37]
	s_nop 0
	v_pk_fma_f32 v[32:33], v[8:9], v[40:41], v[32:33]
	s_nop 0
	v_pk_add_f32 v[32:33], v[12:13], v[32:33]
	s_nop 0
	v_mul_f32_e32 v34, 0xbfb8aa3b, v32
	v_exp_f32_e32 v36, v34
	v_mul_f32_e32 v34, 0xbfb8aa3b, v33
	v_exp_f32_e32 v37, v34
	s_nop 0
	v_pk_add_f32 v[36:37], v[36:37], 1.0 op_sel_hi:[1,0]
	s_nop 0
	s_nop 0
	v_rcp_f32_e32 v34, v37
	s_nop 0
	v_mul_f32_e32 v38, v33, v34
	s_nop 0
	v_rcp_f32_e32 v33, v36
	s_nop 0
	v_mul_f32_e32 v40, v32, v33
	v_lshlrev_b32_e32 v32, 16, v35
	v_and_b32_e32 v33, 0xffff0000, v35
	v_lshlrev_b32_e32 v34, 16, v39
	v_and_b32_e32 v35, 0xffff0000, v39
	v_pk_mul_f32 v[34:35], v[6:7], v[34:35]
	v_lshlrev_b32_e32 v36, 16, v43
	v_and_b32_e32 v37, 0xffff0000, v43
	v_pk_fma_f32 v[32:33], v[2:3], v[32:33], v[34:35]
	s_nop 0
	v_pk_fma_f32 v[32:33], v[10:11], v[36:37], v[32:33]
	s_nop 0
	v_pk_add_f32 v[32:33], v[14:15], v[32:33]
	s_nop 0
	v_mul_f32_e32 v34, 0xbfb8aa3b, v32
	v_mul_f32_e32 v35, 0xbfb8aa3b, v33
	v_exp_f32_e32 v34, v34
	v_exp_f32_e32 v35, v35
	s_nop 0
	v_pk_add_f32 v[34:35], v[34:35], 1.0 op_sel_hi:[1,0]
	s_nop 0
	s_nop 0
	v_rcp_f32_e32 v36, v35
	s_nop 0
	v_mul_f32_e32 v35, v33, v36
	s_nop 0
	v_rcp_f32_e32 v33, v34
	s_nop 0
	v_mul_f32_e32 v36, v32, v33
	v_cvt_pk_bf16_f32 v35, v36, v35
	v_add_u32_e32 v36, 64, v50
	v_ashrrev_i32_e32 v37, 31, v36
	v_lshlrev_b64 v[36:37], 10, v[36:37]
	v_lshl_add_u64 v[36:37], s[20:21], 0, v[36:37]
	v_lshl_add_u64 v[36:37], v[36:37], 0, v[128:129]
	v_add_co_u32_e32 v36, vcc, s17, v36
	v_cvt_pk_bf16_f32 v32, v65, v51
	v_cvt_pk_bf16_f32 v33, v67, v66
	v_cvt_pk_bf16_f32 v34, v40, v38
	v_addc_co_u32_e32 v37, vcc, 0, v37, vcc
	global_store_dwordx4 v[36:37], v[32:35], off offset:2048
	ds_read_b128 v[32:35], v61 offset:4608
	ds_read_b128 v[36:39], v62 offset:144
	ds_read_b128 v[40:43], v62 offset:288
	s_waitcnt lgkmcnt(2)
	v_lshlrev_b32_e32 v66, 16, v32
	s_waitcnt lgkmcnt(1)
	v_lshlrev_b32_e32 v68, 16, v36
	v_and_b32_e32 v69, 0xffff0000, v36
	v_and_b32_e32 v67, 0xffff0000, v32
	v_pk_mul_f32 v[20:21], v[20:21], v[68:69]
	s_waitcnt lgkmcnt(0)
	v_lshlrev_b32_e32 v70, 16, v40
	v_and_b32_e32 v71, 0xffff0000, v40
	v_pk_fma_f32 v[16:17], v[16:17], v[66:67], v[20:21]
	s_nop 0
	v_pk_fma_f32 v[16:17], v[24:25], v[70:71], v[16:17]
	s_nop 0
	v_pk_add_f32 v[16:17], v[28:29], v[16:17]
	s_nop 0
	v_mul_f32_e32 v20, 0xbfb8aa3b, v16
	v_mul_f32_e32 v21, 0xbfb8aa3b, v17
	v_exp_f32_e32 v20, v20
	v_exp_f32_e32 v21, v21
	s_nop 0
	v_pk_add_f32 v[20:21], v[20:21], 1.0 op_sel_hi:[1,0]
	s_nop 0
	s_nop 0
	v_rcp_f32_e32 v24, v21
	s_nop 0
	v_mul_f32_e32 v28, v17, v24
	s_nop 0
	v_rcp_f32_e32 v17, v20
	s_nop 0
	v_mul_f32_e32 v29, v16, v17
	v_lshlrev_b32_e32 v20, 16, v37
	v_and_b32_e32 v21, 0xffff0000, v37
	v_lshlrev_b32_e32 v16, 16, v33
	v_and_b32_e32 v17, 0xffff0000, v33
	v_pk_mul_f32 v[20:21], v[22:23], v[20:21]
	v_lshlrev_b32_e32 v24, 16, v41
	v_and_b32_e32 v25, 0xffff0000, v41
	v_pk_fma_f32 v[16:17], v[18:19], v[16:17], v[20:21]
	s_nop 0
	v_pk_fma_f32 v[16:17], v[26:27], v[24:25], v[16:17]
	s_nop 0
	v_pk_add_f32 v[16:17], v[30:31], v[16:17]
	s_nop 0
	v_mul_f32_e32 v18, 0xbfb8aa3b, v16
	v_mul_f32_e32 v19, 0xbfb8aa3b, v17
	v_exp_f32_e32 v18, v18
	v_exp_f32_e32 v19, v19
	s_nop 0
	v_pk_add_f32 v[18:19], v[18:19], 1.0 op_sel_hi:[1,0]
	s_nop 0
	s_nop 0
	v_rcp_f32_e32 v20, v19
	s_nop 0
	v_mul_f32_e32 v22, v17, v20
	s_nop 0
	v_rcp_f32_e32 v17, v18
	s_nop 0
	v_mul_f32_e32 v23, v16, v17
	v_lshlrev_b32_e32 v18, 16, v38
	v_and_b32_e32 v19, 0xffff0000, v38
	v_lshlrev_b32_e32 v16, 16, v34
	v_and_b32_e32 v17, 0xffff0000, v34
	v_pk_mul_f32 v[4:5], v[4:5], v[18:19]
	v_lshlrev_b32_e32 v20, 16, v42
	v_and_b32_e32 v21, 0xffff0000, v42
	v_pk_fma_f32 v[0:1], v[0:1], v[16:17], v[4:5]
	s_nop 0
	v_pk_fma_f32 v[0:1], v[8:9], v[20:21], v[0:1]
	s_nop 0
	v_pk_add_f32 v[0:1], v[12:13], v[0:1]
	s_nop 0
	v_mul_f32_e32 v4, 0xbfb8aa3b, v0
	v_mul_f32_e32 v5, 0xbfb8aa3b, v1
	v_exp_f32_e32 v4, v4
	v_exp_f32_e32 v5, v5
	s_nop 0
	v_pk_add_f32 v[4:5], v[4:5], 1.0 op_sel_hi:[1,0]
	s_nop 0
	s_nop 0
	v_rcp_f32_e32 v8, v5
	s_nop 0
	v_mul_f32_e32 v12, v1, v8
	s_nop 0
	v_rcp_f32_e32 v1, v4
	s_nop 0
	v_mul_f32_e32 v13, v0, v1
	v_lshlrev_b32_e32 v4, 16, v39
	v_and_b32_e32 v5, 0xffff0000, v39
	v_lshlrev_b32_e32 v0, 16, v35
	v_and_b32_e32 v1, 0xffff0000, v35
	v_pk_mul_f32 v[4:5], v[6:7], v[4:5]
	v_lshlrev_b32_e32 v8, 16, v43
	v_and_b32_e32 v9, 0xffff0000, v43
	v_pk_fma_f32 v[0:1], v[2:3], v[0:1], v[4:5]
	s_nop 0
	v_pk_fma_f32 v[0:1], v[10:11], v[8:9], v[0:1]
	s_nop 0
	v_pk_add_f32 v[0:1], v[14:15], v[0:1]
	s_nop 0
	v_mul_f32_e32 v2, 0xbfb8aa3b, v0
	v_mul_f32_e32 v3, 0xbfb8aa3b, v1
	v_exp_f32_e32 v2, v2
	v_exp_f32_e32 v3, v3
	s_nop 0
	v_pk_add_f32 v[2:3], v[2:3], 1.0 op_sel_hi:[1,0]
	s_nop 0
	s_nop 0
	v_rcp_f32_e32 v4, v3
	s_nop 0
	v_mul_f32_e32 v3, v1, v4
	s_nop 0
	v_rcp_f32_e32 v1, v2
	s_nop 0
	v_mul_f32_e32 v4, v0, v1
	v_cvt_pk_bf16_f32 v3, v4, v3
	v_add_u32_e32 v4, 0x60, v50
	v_ashrrev_i32_e32 v5, 31, v4
	v_lshlrev_b64 v[4:5], 10, v[4:5]
	v_lshl_add_u64 v[4:5], s[20:21], 0, v[4:5]
	v_lshl_add_u64 v[4:5], v[4:5], 0, v[128:129]
	v_add_co_u32_e32 v4, vcc, 0x12d1f000, v4
	v_cvt_pk_bf16_f32 v0, v29, v28
	v_cvt_pk_bf16_f32 v1, v23, v22
	v_cvt_pk_bf16_f32 v2, v13, v12
	v_addc_co_u32_e32 v5, vcc, 0, v5, vcc
	global_store_dwordx4 v[4:5], v[0:3], off offset:2048
	s_cmp_gt_i32 s2, 19
	s_cbranch_scc1 .LBB0_736
	s_branch .LBB0_745

.LBB0_745:
	v_or_b32_e32 v0, s18, v46
	v_ashrrev_i32_e32 v1, 31, v0
	v_lshlrev_b64 v[6:7], 2, v[0:1]
	v_add_u32_e32 v128, s18, v56
	v_lshl_add_u64 v[0:1], s[10:11], 0, v[6:7]
	v_lshl_add_u64 v[2:3], v[128:129], 2, s[10:11]
	global_load_dword v0, v[0:1], off
	v_add_u32_e32 v128, s18, v57
	global_load_dword v2, v[2:3], off
	v_lshl_add_u64 v[4:5], v[128:129], 2, s[10:11]
	global_load_dword v4, v[4:5], off
	v_lshl_add_u64 v[6:7], s[14:15], 0, v[6:7]
	global_load_dword v6, v[6:7], off
	v_add_u32_e32 v1, v58, v63
	ds_read_u16 v3, v1 offset:864
	ds_read_u16 v5, v1 offset:1008
	s_ashr_i32 s17, s16, 31
	s_add_i32 s19, s18, 0xfffffc00
	s_cmp_lt_i32 s2, 16
	s_waitcnt lgkmcnt(1)
	v_lshlrev_b32_e32 v10, 16, v3
	ds_read_u16 v3, v1 offset:1152
	ds_read_u16 v7, v1 offset:1296
	s_waitcnt lgkmcnt(2)
	v_lshlrev_b32_e32 v11, 16, v5
	s_cselect_b32 s2, s18, s19
	s_cselect_b32 s20, 10, 8
	s_waitcnt lgkmcnt(1)
	v_lshlrev_b32_e32 v15, 16, v3
	ds_read_u16 v3, v1 offset:576
	ds_read_u16 v5, v1 offset:720
	s_cselect_b32 s18, s31, s35
	s_cselect_b32 s19, s34, s38
	s_lshl_b64 s[16:17], s[16:17], s20
	s_waitcnt lgkmcnt(1)
	v_lshlrev_b32_e32 v16, 16, v3
	s_waitcnt lgkmcnt(0)
	v_lshlrev_b32_e32 v17, 16, v5
	ds_read_u16 v3, v1 offset:288
	ds_read_u16 v5, v1 offset:432
	s_ashr_i32 s20, s2, 31
	s_add_u32 s2, s16, s2
	s_addc_u32 s16, s17, s20
	s_waitcnt lgkmcnt(1)
	v_lshlrev_b32_e32 v18, 16, v3
	s_waitcnt lgkmcnt(0)
	v_lshlrev_b32_e32 v19, 16, v5
	ds_read_u16 v3, v1
	ds_read_u16 v5, v1 offset:144
	v_mov_b32_e32 v9, s16
	v_lshlrev_b32_e32 v13, 16, v7
	v_mov_b32_e32 v14, v11
	s_waitcnt lgkmcnt(1)
	v_lshlrev_b32_e32 v20, 16, v3
	s_waitcnt lgkmcnt(0)
	v_lshlrev_b32_e32 v21, 16, v5
	v_pk_mov_b32 v[22:23], v[20:21], v[18:19] op_sel:[1,0]
	v_mov_b32_e32 v12, v15
	v_or_b32_e32 v8, s2, v46
	v_lshlrev_b64 v[8:9], 8, v[8:9]
	v_lshl_add_u64 v[8:9], s[18:19], 0, v[8:9]
	v_lshl_add_u64 v[8:9], v[48:49], 1, v[8:9]
	s_waitcnt vmcnt(2)
	v_pk_mul_f32 v[22:23], v[2:3], v[22:23] op_sel_hi:[0,1]
	v_pk_fma_f32 v[20:21], v[0:1], v[20:21], v[22:23] op_sel_hi:[0,1,1]
	s_waitcnt vmcnt(1)
	v_pk_fma_f32 v[20:21], v[4:5], v[18:19], v[20:21] op_sel_hi:[0,1,1]
	s_waitcnt vmcnt(0)
	v_pk_add_f32 v[20:21], v[6:7], v[20:21] op_sel_hi:[0,1]
	v_mul_f32_e32 v3, 0xbfb8aa3b, v20
	v_exp_f32_e32 v22, v3
	v_mul_f32_e32 v3, 0xbfb8aa3b, v21
	v_exp_f32_e32 v23, v3
	s_nop 0
	v_pk_add_f32 v[22:23], v[22:23], 1.0 op_sel_hi:[1,0]
	s_nop 0
	s_nop 0
	v_rcp_f32_e32 v3, v23
	s_nop 0
	v_mul_f32_e32 v3, v21, v3
	v_pk_mul_f32 v[14:15], v[2:3], v[14:15] op_sel_hi:[0,1]
	v_rcp_f32_e32 v5, v22
	s_nop 0
	v_mul_f32_e32 v5, v20, v5
	v_pk_mov_b32 v[20:21], v[18:19], v[16:17] op_sel:[1,0]
	s_nop 0
	v_pk_mul_f32 v[20:21], v[2:3], v[20:21] op_sel_hi:[0,1]
	v_pk_fma_f32 v[18:19], v[0:1], v[18:19], v[20:21] op_sel_hi:[0,1,1]
	v_pk_fma_f32 v[18:19], v[4:5], v[16:17], v[18:19] op_sel_hi:[0,1,1]
	v_pk_add_f32 v[18:19], v[6:7], v[18:19] op_sel_hi:[0,1]
	v_mul_f32_e32 v7, 0xbfb8aa3b, v18
	v_exp_f32_e32 v20, v7
	v_mul_f32_e32 v7, 0xbfb8aa3b, v19
	v_exp_f32_e32 v21, v7
	s_nop 0
	v_pk_add_f32 v[20:21], v[20:21], 1.0 op_sel_hi:[1,0]
	s_nop 0
	s_nop 0
	v_rcp_f32_e32 v7, v21
	s_nop 0
	v_mul_f32_e32 v7, v19, v7
	s_nop 0
	v_rcp_f32_e32 v19, v20
	s_nop 0
	v_mul_f32_e32 v20, v18, v19
	v_pk_mov_b32 v[18:19], v[16:17], v[10:11] op_sel:[1,0]
	s_nop 0
	v_pk_mul_f32 v[18:19], v[2:3], v[18:19] op_sel_hi:[0,1]
	v_pk_fma_f32 v[16:17], v[0:1], v[16:17], v[18:19] op_sel_hi:[0,1,1]
	v_pk_fma_f32 v[16:17], v[4:5], v[10:11], v[16:17] op_sel_hi:[0,1,1]
	v_pk_add_f32 v[16:17], v[6:7], v[16:17] op_sel_hi:[0,1]
	v_mul_f32_e32 v18, 0xbfb8aa3b, v16
	v_mul_f32_e32 v19, 0xbfb8aa3b, v17
	v_exp_f32_e32 v18, v18
	v_exp_f32_e32 v19, v19
	v_pk_fma_f32 v[10:11], v[0:1], v[10:11], v[14:15] op_sel_hi:[0,1,1]
	v_pk_fma_f32 v[10:11], v[4:5], v[12:13], v[10:11] op_sel_hi:[0,1,1]
	v_pk_add_f32 v[10:11], v[6:7], v[10:11] op_sel_hi:[0,1]
	v_pk_add_f32 v[18:19], v[18:19], 1.0 op_sel_hi:[1,0]
	v_mul_f32_e32 v12, 0xbfb8aa3b, v10
	v_mul_f32_e32 v13, 0xbfb8aa3b, v11
	v_exp_f32_e32 v12, v12
	v_exp_f32_e32 v13, v13
	v_rcp_f32_e32 v21, v19
	s_nop 0
	v_mul_f32_e32 v17, v17, v21
	v_pk_add_f32 v[12:13], v[12:13], 1.0 op_sel_hi:[1,0]
	v_rcp_f32_e32 v19, v18
	s_nop 0
	v_mul_f32_e32 v16, v16, v19
	v_rcp_f32_e32 v14, v13
	s_nop 0
	v_mul_f32_e32 v13, v11, v14
	s_nop 0
	v_rcp_f32_e32 v11, v12
	s_nop 0
	v_mul_f32_e32 v14, v10, v11
	v_cvt_pk_bf16_f32 v10, v5, v3
	v_cvt_pk_bf16_f32 v11, v20, v7
	v_cvt_pk_bf16_f32 v12, v16, v17
	v_cvt_pk_bf16_f32 v13, v14, v13
	global_store_dwordx4 v[8:9], v[10:13], off
	ds_read_u16 v3, v1 offset:5472
	ds_read_u16 v5, v1 offset:5616
	s_waitcnt lgkmcnt(1)
	v_lshlrev_b32_e32 v10, 16, v3
	ds_read_u16 v3, v1 offset:5760
	ds_read_u16 v7, v1 offset:5904
	s_waitcnt lgkmcnt(2)
	v_lshlrev_b32_e32 v11, 16, v5
	v_mov_b32_e32 v14, v11
	s_waitcnt lgkmcnt(1)
	v_lshlrev_b32_e32 v15, 16, v3
	ds_read_u16 v3, v1 offset:5184
	ds_read_u16 v5, v1 offset:5328
	s_waitcnt lgkmcnt(2)
	v_lshlrev_b32_e32 v13, 16, v7
	v_mov_b32_e32 v12, v15
	s_waitcnt lgkmcnt(1)
	v_lshlrev_b32_e32 v16, 16, v3
	s_waitcnt lgkmcnt(0)
	v_lshlrev_b32_e32 v17, 16, v5
	ds_read_u16 v3, v1 offset:4896
	ds_read_u16 v5, v1 offset:5040
	s_waitcnt lgkmcnt(1)
	v_lshlrev_b32_e32 v18, 16, v3
	s_waitcnt lgkmcnt(0)
	v_lshlrev_b32_e32 v19, 16, v5
	ds_read_u16 v3, v64
	ds_read_u16 v5, v1 offset:4752
	s_waitcnt lgkmcnt(1)
	v_lshlrev_b32_e32 v20, 16, v3
	s_waitcnt lgkmcnt(0)
	v_lshlrev_b32_e32 v21, 16, v5
	v_pk_mov_b32 v[22:23], v[20:21], v[18:19] op_sel:[1,0]
	s_nop 0
	v_pk_mul_f32 v[22:23], v[2:3], v[22:23] op_sel_hi:[0,1]
	v_pk_fma_f32 v[20:21], v[0:1], v[20:21], v[22:23] op_sel_hi:[0,1,1]
	v_pk_fma_f32 v[20:21], v[4:5], v[18:19], v[20:21] op_sel_hi:[0,1,1]
	v_pk_add_f32 v[20:21], v[6:7], v[20:21] op_sel_hi:[0,1]
	v_mul_f32_e32 v3, 0xbfb8aa3b, v20
	v_exp_f32_e32 v22, v3
	v_mul_f32_e32 v3, 0xbfb8aa3b, v21
	v_exp_f32_e32 v23, v3
	s_nop 0
	v_pk_add_f32 v[22:23], v[22:23], 1.0 op_sel_hi:[1,0]
	s_nop 0
	s_nop 0
	v_rcp_f32_e32 v3, v23
	s_nop 0
	v_mul_f32_e32 v3, v21, v3
	v_pk_mul_f32 v[14:15], v[2:3], v[14:15] op_sel_hi:[0,1]
	v_rcp_f32_e32 v5, v22
	s_nop 0
	v_mul_f32_e32 v5, v20, v5
	v_pk_mov_b32 v[20:21], v[18:19], v[16:17] op_sel:[1,0]
	s_nop 0
	v_pk_mul_f32 v[20:21], v[2:3], v[20:21] op_sel_hi:[0,1]
	v_pk_fma_f32 v[18:19], v[0:1], v[18:19], v[20:21] op_sel_hi:[0,1,1]
	v_pk_fma_f32 v[18:19], v[4:5], v[16:17], v[18:19] op_sel_hi:[0,1,1]
	v_pk_add_f32 v[18:19], v[6:7], v[18:19] op_sel_hi:[0,1]
	v_mul_f32_e32 v7, 0xbfb8aa3b, v18
	v_exp_f32_e32 v20, v7
	v_mul_f32_e32 v7, 0xbfb8aa3b, v19
	v_exp_f32_e32 v21, v7
	s_nop 0
	v_pk_add_f32 v[20:21], v[20:21], 1.0 op_sel_hi:[1,0]
	s_nop 0
	s_nop 0
	v_rcp_f32_e32 v7, v21
	s_nop 0
	v_mul_f32_e32 v7, v19, v7
	s_nop 0
	v_rcp_f32_e32 v19, v20
	s_nop 0
	v_mul_f32_e32 v20, v18, v19
	v_pk_mov_b32 v[18:19], v[16:17], v[10:11] op_sel:[1,0]
	s_nop 0
	v_pk_mul_f32 v[18:19], v[2:3], v[18:19] op_sel_hi:[0,1]
	v_pk_fma_f32 v[16:17], v[0:1], v[16:17], v[18:19] op_sel_hi:[0,1,1]
	v_pk_fma_f32 v[16:17], v[4:5], v[10:11], v[16:17] op_sel_hi:[0,1,1]
	v_pk_add_f32 v[16:17], v[6:7], v[16:17] op_sel_hi:[0,1]
	v_mul_f32_e32 v18, 0xbfb8aa3b, v16
	v_mul_f32_e32 v19, 0xbfb8aa3b, v17
	v_exp_f32_e32 v18, v18
	v_exp_f32_e32 v19, v19
	v_pk_fma_f32 v[10:11], v[0:1], v[10:11], v[14:15] op_sel_hi:[0,1,1]
	v_pk_fma_f32 v[10:11], v[4:5], v[12:13], v[10:11] op_sel_hi:[0,1,1]
	v_pk_add_f32 v[10:11], v[6:7], v[10:11] op_sel_hi:[0,1]
	v_pk_add_f32 v[18:19], v[18:19], 1.0 op_sel_hi:[1,0]
	v_mul_f32_e32 v12, 0xbfb8aa3b, v10
	v_mul_f32_e32 v13, 0xbfb8aa3b, v11
	v_exp_f32_e32 v12, v12
	v_exp_f32_e32 v13, v13
	v_rcp_f32_e32 v21, v19
	s_nop 0
	v_mul_f32_e32 v17, v17, v21
	v_pk_add_f32 v[12:13], v[12:13], 1.0 op_sel_hi:[1,0]
	v_rcp_f32_e32 v19, v18
	s_nop 0
	v_mul_f32_e32 v16, v16, v19
	v_rcp_f32_e32 v14, v13
	s_nop 0
	v_mul_f32_e32 v13, v11, v14
	s_nop 0
	v_rcp_f32_e32 v11, v12
	s_nop 0
	v_mul_f32_e32 v14, v10, v11
	v_cvt_pk_bf16_f32 v10, v5, v3
	v_cvt_pk_bf16_f32 v11, v20, v7
	v_cvt_pk_bf16_f32 v12, v16, v17
	v_cvt_pk_bf16_f32 v13, v14, v13
	global_store_dwordx4 v[8:9], v[10:13], off offset:64
	ds_read_u16 v3, v1 offset:10080
	ds_read_u16 v5, v1 offset:10224
	s_waitcnt lgkmcnt(1)
	v_lshlrev_b32_e32 v10, 16, v3
	ds_read_u16 v3, v1 offset:10368
	ds_read_u16 v7, v1 offset:10512
	s_waitcnt lgkmcnt(2)
	v_lshlrev_b32_e32 v11, 16, v5
	v_mov_b32_e32 v14, v11
	s_waitcnt lgkmcnt(1)
	v_lshlrev_b32_e32 v15, 16, v3
	ds_read_u16 v3, v1 offset:9792
	ds_read_u16 v5, v1 offset:9936
	s_waitcnt lgkmcnt(2)
	v_lshlrev_b32_e32 v13, 16, v7
	v_mov_b32_e32 v12, v15
	s_waitcnt lgkmcnt(1)
	v_lshlrev_b32_e32 v16, 16, v3
	s_waitcnt lgkmcnt(0)
	v_lshlrev_b32_e32 v17, 16, v5
	ds_read_u16 v3, v1 offset:9504
	ds_read_u16 v5, v1 offset:9648
	s_waitcnt lgkmcnt(1)
	v_lshlrev_b32_e32 v18, 16, v3
	s_waitcnt lgkmcnt(0)
	v_lshlrev_b32_e32 v19, 16, v5
	ds_read_u16 v3, v64 offset:4608
	ds_read_u16 v5, v1 offset:9360
	s_waitcnt lgkmcnt(1)
	v_lshlrev_b32_e32 v20, 16, v3
	s_waitcnt lgkmcnt(0)
	v_lshlrev_b32_e32 v21, 16, v5
	v_pk_mov_b32 v[22:23], v[20:21], v[18:19] op_sel:[1,0]
	s_nop 0
	v_pk_mul_f32 v[22:23], v[2:3], v[22:23] op_sel_hi:[0,1]
	v_pk_fma_f32 v[20:21], v[0:1], v[20:21], v[22:23] op_sel_hi:[0,1,1]
	v_pk_fma_f32 v[20:21], v[4:5], v[18:19], v[20:21] op_sel_hi:[0,1,1]
	v_pk_add_f32 v[20:21], v[6:7], v[20:21] op_sel_hi:[0,1]
	v_mul_f32_e32 v3, 0xbfb8aa3b, v20
	v_exp_f32_e32 v22, v3
	v_mul_f32_e32 v3, 0xbfb8aa3b, v21
	v_exp_f32_e32 v23, v3
	s_nop 0
	v_pk_add_f32 v[22:23], v[22:23], 1.0 op_sel_hi:[1,0]
	s_nop 0
	s_nop 0
	v_rcp_f32_e32 v3, v23
	s_nop 0
	v_mul_f32_e32 v3, v21, v3
	v_pk_mul_f32 v[14:15], v[2:3], v[14:15] op_sel_hi:[0,1]
	v_rcp_f32_e32 v5, v22
	s_nop 0
	v_mul_f32_e32 v5, v20, v5
	v_pk_mov_b32 v[20:21], v[18:19], v[16:17] op_sel:[1,0]
	s_nop 0
	v_pk_mul_f32 v[20:21], v[2:3], v[20:21] op_sel_hi:[0,1]
	v_pk_fma_f32 v[18:19], v[0:1], v[18:19], v[20:21] op_sel_hi:[0,1,1]
	v_pk_fma_f32 v[18:19], v[4:5], v[16:17], v[18:19] op_sel_hi:[0,1,1]
	v_pk_add_f32 v[18:19], v[6:7], v[18:19] op_sel_hi:[0,1]
	v_mul_f32_e32 v7, 0xbfb8aa3b, v18
	v_exp_f32_e32 v20, v7
	v_mul_f32_e32 v7, 0xbfb8aa3b, v19
	v_exp_f32_e32 v21, v7
	s_nop 0
	v_pk_add_f32 v[20:21], v[20:21], 1.0 op_sel_hi:[1,0]
	s_nop 0
	s_nop 0
	v_rcp_f32_e32 v7, v21
	s_nop 0
	v_mul_f32_e32 v7, v19, v7
	s_nop 0
	v_rcp_f32_e32 v19, v20
	s_nop 0
	v_mul_f32_e32 v20, v18, v19
	v_pk_mov_b32 v[18:19], v[16:17], v[10:11] op_sel:[1,0]
	s_nop 0
	v_pk_mul_f32 v[18:19], v[2:3], v[18:19] op_sel_hi:[0,1]
	v_pk_fma_f32 v[16:17], v[0:1], v[16:17], v[18:19] op_sel_hi:[0,1,1]
	v_pk_fma_f32 v[16:17], v[4:5], v[10:11], v[16:17] op_sel_hi:[0,1,1]
	v_pk_add_f32 v[16:17], v[6:7], v[16:17] op_sel_hi:[0,1]
	v_mul_f32_e32 v18, 0xbfb8aa3b, v16
	v_mul_f32_e32 v19, 0xbfb8aa3b, v17
	v_exp_f32_e32 v18, v18
	v_exp_f32_e32 v19, v19
	v_pk_fma_f32 v[10:11], v[0:1], v[10:11], v[14:15] op_sel_hi:[0,1,1]
	v_pk_fma_f32 v[10:11], v[4:5], v[12:13], v[10:11] op_sel_hi:[0,1,1]
	v_pk_add_f32 v[10:11], v[6:7], v[10:11] op_sel_hi:[0,1]
	v_pk_add_f32 v[18:19], v[18:19], 1.0 op_sel_hi:[1,0]
	v_mul_f32_e32 v12, 0xbfb8aa3b, v10
	v_mul_f32_e32 v13, 0xbfb8aa3b, v11
	v_exp_f32_e32 v12, v12
	v_exp_f32_e32 v13, v13
	v_rcp_f32_e32 v21, v19
	s_nop 0
	v_mul_f32_e32 v17, v17, v21
	v_pk_add_f32 v[12:13], v[12:13], 1.0 op_sel_hi:[1,0]
	v_rcp_f32_e32 v19, v18
	s_nop 0
	v_mul_f32_e32 v16, v16, v19
	v_rcp_f32_e32 v14, v13
	s_nop 0
	v_mul_f32_e32 v13, v11, v14
	s_nop 0
	v_rcp_f32_e32 v11, v12
	s_nop 0
	v_mul_f32_e32 v14, v10, v11
	v_cvt_pk_bf16_f32 v10, v5, v3
	v_cvt_pk_bf16_f32 v11, v20, v7
	v_cvt_pk_bf16_f32 v12, v16, v17
	v_cvt_pk_bf16_f32 v13, v14, v13
	global_store_dwordx4 v[8:9], v[10:13], off offset:128
	ds_read_u16 v3, v1 offset:14688
	ds_read_u16 v5, v1 offset:14832
	s_waitcnt lgkmcnt(1)
	v_lshlrev_b32_e32 v10, 16, v3
	ds_read_u16 v3, v1 offset:14976
	ds_read_u16 v7, v1 offset:15120
	s_waitcnt lgkmcnt(2)
	v_lshlrev_b32_e32 v11, 16, v5
	v_mov_b32_e32 v14, v11
	s_waitcnt lgkmcnt(1)
	v_lshlrev_b32_e32 v15, 16, v3
	ds_read_u16 v3, v1 offset:14400
	ds_read_u16 v5, v1 offset:14544
	s_waitcnt lgkmcnt(2)
	v_lshlrev_b32_e32 v13, 16, v7
	v_mov_b32_e32 v12, v15
	s_waitcnt lgkmcnt(1)
	v_lshlrev_b32_e32 v16, 16, v3
	s_waitcnt lgkmcnt(0)
	v_lshlrev_b32_e32 v17, 16, v5
	ds_read_u16 v3, v1 offset:14112
	ds_read_u16 v5, v1 offset:14256
	s_waitcnt lgkmcnt(1)
	v_lshlrev_b32_e32 v18, 16, v3
	ds_read_u16 v3, v64 offset:9216
	ds_read_u16 v1, v1 offset:13968
	s_waitcnt lgkmcnt(2)
	v_lshlrev_b32_e32 v19, 16, v5
	s_waitcnt lgkmcnt(1)
	v_lshlrev_b32_e32 v20, 16, v3
	s_waitcnt lgkmcnt(0)
	v_lshlrev_b32_e32 v21, 16, v1
	v_pk_mov_b32 v[22:23], v[20:21], v[18:19] op_sel:[1,0]
	s_nop 0
	v_pk_mul_f32 v[22:23], v[2:3], v[22:23] op_sel_hi:[0,1]
	v_pk_fma_f32 v[20:21], v[0:1], v[20:21], v[22:23] op_sel_hi:[0,1,1]
	v_pk_fma_f32 v[20:21], v[4:5], v[18:19], v[20:21] op_sel_hi:[0,1,1]
	v_pk_add_f32 v[20:21], v[6:7], v[20:21] op_sel_hi:[0,1]
	v_mul_f32_e32 v1, 0xbfb8aa3b, v20
	v_exp_f32_e32 v22, v1
	v_mul_f32_e32 v1, 0xbfb8aa3b, v21
	v_exp_f32_e32 v23, v1
	s_nop 0
	v_pk_add_f32 v[22:23], v[22:23], 1.0 op_sel_hi:[1,0]
	s_nop 0
	s_nop 0
	v_rcp_f32_e32 v1, v23
	s_nop 0
	v_mul_f32_e32 v5, v21, v1
	s_nop 0
	v_rcp_f32_e32 v1, v22
	s_nop 0
	v_mul_f32_e32 v7, v20, v1
	v_pk_mov_b32 v[20:21], v[18:19], v[16:17] op_sel:[1,0]
	s_nop 0
	v_pk_mul_f32 v[20:21], v[2:3], v[20:21] op_sel_hi:[0,1]
	v_pk_fma_f32 v[18:19], v[0:1], v[18:19], v[20:21] op_sel_hi:[0,1,1]
	v_pk_fma_f32 v[18:19], v[4:5], v[16:17], v[18:19] op_sel_hi:[0,1,1]
	v_pk_add_f32 v[18:19], v[6:7], v[18:19] op_sel_hi:[0,1]
	v_mul_f32_e32 v1, 0xbfb8aa3b, v18
	v_exp_f32_e32 v20, v1
	v_mul_f32_e32 v1, 0xbfb8aa3b, v19
	v_exp_f32_e32 v21, v1
	s_nop 0
	v_pk_add_f32 v[20:21], v[20:21], 1.0 op_sel_hi:[1,0]
	s_nop 0
	s_nop 0
	v_rcp_f32_e32 v1, v21
	s_nop 0
	v_mul_f32_e32 v21, v19, v1
	s_nop 0
	v_rcp_f32_e32 v1, v20
	s_nop 0
	v_mul_f32_e32 v20, v18, v1
	v_pk_mov_b32 v[18:19], v[16:17], v[10:11] op_sel:[1,0]
	s_nop 0
	v_pk_mul_f32 v[18:19], v[2:3], v[18:19] op_sel_hi:[0,1]
	v_pk_fma_f32 v[16:17], v[0:1], v[16:17], v[18:19] op_sel_hi:[0,1,1]
	v_pk_fma_f32 v[16:17], v[4:5], v[10:11], v[16:17] op_sel_hi:[0,1,1]
	v_pk_add_f32 v[16:17], v[6:7], v[16:17] op_sel_hi:[0,1]
	v_mul_f32_e32 v1, 0xbfb8aa3b, v16
	v_exp_f32_e32 v18, v1
	v_mul_f32_e32 v1, 0xbfb8aa3b, v17
	v_exp_f32_e32 v19, v1
	s_nop 0
	v_pk_add_f32 v[18:19], v[18:19], 1.0 op_sel_hi:[1,0]
	s_nop 0
	s_nop 0
	v_rcp_f32_e32 v1, v19
	s_nop 0
	v_mul_f32_e32 v17, v17, v1
	s_nop 0
	v_pk_mul_f32 v[2:3], v[2:3], v[14:15] op_sel_hi:[0,1]
	v_rcp_f32_e32 v1, v18
	s_nop 0
	v_mul_f32_e32 v16, v16, v1
	v_pk_fma_f32 v[0:1], v[0:1], v[10:11], v[2:3] op_sel_hi:[0,1,1]
	v_pk_fma_f32 v[0:1], v[4:5], v[12:13], v[0:1] op_sel_hi:[0,1,1]
	v_pk_add_f32 v[0:1], v[6:7], v[0:1] op_sel_hi:[0,1]
	v_mul_f32_e32 v2, 0xbfb8aa3b, v0
	v_mul_f32_e32 v3, 0xbfb8aa3b, v1
	v_exp_f32_e32 v2, v2
	v_exp_f32_e32 v3, v3
	s_nop 0
	v_pk_add_f32 v[2:3], v[2:3], 1.0 op_sel_hi:[1,0]
	s_nop 0
	s_nop 0
	v_rcp_f32_e32 v4, v3
	s_nop 0
	v_mul_f32_e32 v3, v1, v4
	s_nop 0
	v_rcp_f32_e32 v1, v2
	s_nop 0
	v_mul_f32_e32 v4, v0, v1
	v_cvt_pk_bf16_f32 v0, v7, v5
	v_cvt_pk_bf16_f32 v1, v20, v21
	v_cvt_pk_bf16_f32 v2, v16, v17
	v_cvt_pk_bf16_f32 v3, v4, v3
	global_store_dwordx4 v[8:9], v[0:3], off offset:192
	s_branch .LBB0_736

.LBB0_748:
	s_or_b64 exec, exec, s[12:13]
	v_mul_f32_e32 v27, v5, v5
	v_fmamk_f32 v28, v27, 0xb94c1982, v213
	v_fmaak_f32 v28, v27, v28, 0xbe2aaa9d
	v_mul_f32_e32 v28, v27, v28
	v_fmac_f32_e32 v5, v5, v28
	v_fmamk_f32 v28, v27, 0x37d75334, v214
	v_fmaak_f32 v28, v27, v28, 0x3d2aabf7
	v_fmaak_f32 v28, v27, v28, 0xbf000004
	v_fma_f32 v27, v27, v28, 1.0
	v_and_b32_e32 v28, 1, v3
	v_cmp_eq_u32_e32 vcc, 0, v28
	v_lshlrev_b32_e32 v3, 30, v3
	s_brev_b32 s2, 1
	v_cndmask_b32_e64 v5, -v5, v27, vcc
	s_mov_b32 s12, 0x7f800000
	v_bitop3_b32 v3, v3, v5, s2 bitop3:0x6c
	v_cmp_lg_f32_e32 vcc, s12, v2
	s_nop 1
	s_nop 0
	v_cndmask_b32_e32 v2, v223, v3, vcc
	v_mul_f32_e32 v3, v26, v26
	v_fmamk_f32 v5, v3, 0xb94c1982, v213
	v_fmaak_f32 v5, v3, v5, 0xbe2aaa9d
	v_mul_f32_e32 v5, v3, v5
	v_fmac_f32_e32 v26, v26, v5
	v_fmamk_f32 v5, v3, 0x37d75334, v214
	v_fmaak_f32 v5, v3, v5, 0x3d2aabf7
	v_fmaak_f32 v5, v3, v5, 0xbf000004
	v_fma_f32 v3, v3, v5, 1.0
	v_and_b32_e32 v5, 1, v23
	v_cmp_eq_u32_e64 s[12:13], 0, v5
	v_lshlrev_b32_e32 v5, 30, v23
	s_nop 0
	v_cndmask_b32_e64 v3, v3, v26, s[12:13]
	v_bitop3_b32 v3, v5, v3, s2 bitop3:0x6c
	v_cndmask_b32_e32 v26, v223, v3, vcc
	v_pk_mul_f32 v[26:27], v[26:27], v[0:1] op_sel:[0,1] op_sel_hi:[0,0]
	v_pk_mul_f32 v[28:29], v[2:3], v[0:1] op_sel_hi:[0,1]
	v_pk_fma_f32 v[0:1], v[2:3], v[0:1], v[26:27] op_sel_hi:[0,1,1] neg_lo:[0,0,1] neg_hi:[0,0,1]
	v_add_f32_e32 v0, v28, v26

.LBB0_756:
	s_andn2_saveexec_b64 s[24:25], s[12:13]
	s_cbranch_execz .LBB0_751
	v_lshl_add_u64 v[0:1], v[20:21], 0, v[8:9]
	v_add_co_u32_e32 v0, vcc, 0x26a2000, v0
	s_nop 1
	s_nop 0
	v_addc_co_u32_e32 v1, vcc, 0, v1, vcc
	global_load_dwordx2 v[2:3], v[0:1], off offset:544
	s_nop 0
	global_load_dwordx2 v[0:1], v[0:1], off offset:32
	s_waitcnt vmcnt(1)
	v_lshlrev_b32_e32 v28, 16, v2
	v_and_b32_e32 v29, 0xffff0000, v2
	v_lshlrev_b32_e32 v26, 16, v3
	v_and_b32_e32 v27, 0xffff0000, v3
	s_waitcnt vmcnt(0)
	v_lshlrev_b32_e32 v24, 16, v0
	v_and_b32_e32 v25, 0xffff0000, v0
	v_lshlrev_b32_e32 v30, 16, v1
	v_and_b32_e32 v31, 0xffff0000, v1
	v_pk_mul_f32 v[0:1], v[28:29], v[28:29]
	v_pk_mul_f32 v[2:3], v[26:27], v[26:27]
	v_add_f32_e32 v0, v0, v1
	v_and_b32_e32 v1, 64, v216
	v_add_f32_e32 v0, v2, v0
	v_add_u32_e32 v1, 64, v1
	v_xor_b32_e32 v2, 1, v216
	v_cmp_lt_i32_e32 vcc, v2, v1
	v_add_f32_e32 v0, v3, v0
	s_nop 0
	v_cndmask_b32_e32 v2, v216, v2, vcc
	v_lshlrev_b32_e32 v2, 2, v2
	ds_bpermute_b32 v3, v2, v0
	s_waitcnt lgkmcnt(0)
	v_add_f32_e32 v0, v0, v3
	v_xor_b32_e32 v3, 2, v216
	v_cmp_lt_i32_e32 vcc, v3, v1
	s_nop 1
	s_nop 0
	v_cndmask_b32_e32 v3, v216, v3, vcc
	v_lshlrev_b32_e32 v3, 2, v3
	ds_bpermute_b32 v5, v3, v0
	s_waitcnt lgkmcnt(0)
	v_add_f32_e32 v0, v0, v5
	v_xor_b32_e32 v5, 4, v216
	v_cmp_lt_i32_e32 vcc, v5, v1
	s_nop 1
	s_nop 0
	v_cndmask_b32_e32 v5, v216, v5, vcc
	v_lshlrev_b32_e32 v32, 2, v5
	ds_bpermute_b32 v5, v32, v0
	s_waitcnt lgkmcnt(0)
	v_add_f32_e32 v0, v0, v5
	v_xor_b32_e32 v5, 8, v216
	v_cmp_lt_i32_e32 vcc, v5, v1
	s_nop 1
	s_nop 0
	v_cndmask_b32_e32 v5, v216, v5, vcc
	v_lshlrev_b32_e32 v33, 2, v5
	ds_bpermute_b32 v5, v33, v0
	s_waitcnt lgkmcnt(0)
	v_add_f32_e32 v0, v0, v5
	v_xor_b32_e32 v5, 16, v216
	v_cmp_lt_i32_e32 vcc, v5, v1
	s_nop 1
	s_nop 0
	v_cndmask_b32_e32 v5, v216, v5, vcc
	v_lshlrev_b32_e32 v34, 2, v5
	ds_bpermute_b32 v5, v34, v0
	s_waitcnt lgkmcnt(0)
	v_add_f32_e32 v5, v0, v5
	v_xor_b32_e32 v0, 32, v216
	v_cmp_lt_i32_e32 vcc, v0, v1
	s_nop 1
	s_nop 0
	v_cndmask_b32_e32 v0, v216, v0, vcc
	v_lshlrev_b32_e32 v1, 2, v0
	v_mul_f32_e32 v0, v25, v25
	v_fmac_f32_e32 v0, v24, v24
	v_fmac_f32_e32 v0, v30, v30
	v_fmac_f32_e32 v0, v31, v31
	ds_bpermute_b32 v2, v2, v0
	ds_bpermute_b32 v23, v1, v5
	s_waitcnt lgkmcnt(1)
	v_add_f32_e32 v0, v0, v2
	ds_bpermute_b32 v2, v3, v0
	s_waitcnt lgkmcnt(0)
	v_add_f32_e32 v0, v0, v2
	ds_bpermute_b32 v2, v32, v0
	s_waitcnt lgkmcnt(0)
	v_add_f32_e32 v0, v0, v2
	ds_bpermute_b32 v2, v33, v0
	s_waitcnt lgkmcnt(0)
	v_add_f32_e32 v0, v0, v2
	ds_bpermute_b32 v2, v34, v0
	s_waitcnt lgkmcnt(0)
	v_add_f32_e32 v0, v0, v2
	ds_bpermute_b32 v1, v1, v0
	s_and_saveexec_b64 s[12:13], s[4:5]
	s_cbranch_execz .LBB0_759
	s_waitcnt lgkmcnt(0)
	v_add_f32_e32 v0, v0, v1
	v_fmamk_f32 v0, v0, 0x3b800000, v206
	v_mul_f32_e32 v1, 0x4b800000, v0
	v_cmp_gt_f32_e32 vcc, s83, v0
	s_nop 1
	s_nop 0
	v_cndmask_b32_e32 v0, v0, v1, vcc
	v_rsq_f32_e32 v0, v0
	s_nop 0
	v_mul_f32_e32 v1, 0x45800000, v0
	v_cndmask_b32_e32 v0, v0, v1, vcc
	global_store_dword v[18:19], v0, off

.LBB0_763:
	s_or_b64 exec, exec, s[12:13]
	v_ashrrev_i32_e32 v25, 31, v24
	v_cvt_pk_bf16_f32 v0, v0, v1
	v_cvt_pk_bf16_f32 v1, v2, v3
	v_lshlrev_b64 v[2:3], 9, v[24:25]
	v_lshl_add_u64 v[2:3], v[10:11], 0, v[2:3]
	global_store_dwordx2 v[2:3], v[0:1], off
	s_and_saveexec_b64 s[26:27], s[6:7]
	s_cbranch_execz .LBB0_750
	v_lshl_add_u64 v[0:1], v[20:21], 0, v[12:13]
	v_add_co_u32_e32 v0, vcc, 0x26a2000, v0
	s_nop 1
	s_nop 0
	v_addc_co_u32_e32 v1, vcc, 0, v1, vcc
	global_load_ushort v2, v[0:1], off offset:1056
	s_nop 0
	global_load_ushort v0, v[0:1], off offset:1088
	v_cmp_lt_i32_e32 vcc, s82, v4
	s_waitcnt vmcnt(1)
	v_lshlrev_b32_e32 v1, 16, v2
	s_waitcnt vmcnt(0)
	v_lshlrev_b32_e32 v0, 16, v0
	s_and_saveexec_b64 s[28:29], vcc
	s_cbranch_execz .LBB0_749
	v_lshrrev_b32_e32 v2, 6, v5
	v_and_b32_e32 v3, 63, v5
	v_cndmask_b32_e64 v2, v3, v2, s[8:9]
	v_cvt_f32_u32_e32 v2, v2
	s_brev_b32 s2, 18
	v_mul_f32_e32 v2, v7, v2
	v_cmp_ngt_f32_e32 vcc, s2, v2
	s_and_saveexec_b64 s[12:13], vcc
	s_xor_b64 s[30:31], exec, s[12:13]
	s_cbranch_execz .LBB0_767
	v_lshrrev_b32_e32 v3, 23, v2
	v_add_u32_e32 v3, 0xffffff88, v3
	v_cmp_lt_u32_e64 s[12:13], 63, v3
	s_mov_b32 s2, 0xfe5163ab
	s_nop 0
	v_cndmask_b32_e64 v5, 0, v221, s[12:13]
	v_add_u32_e32 v3, v5, v3
	v_cmp_lt_u32_e64 s[14:15], 31, v3
	s_nop 1
	s_nop 0
	v_cndmask_b32_e64 v5, 0, v222, s[14:15]
	v_add_u32_e32 v3, v5, v3
	v_cmp_lt_u32_e64 s[16:17], 31, v3
	s_nop 1
	s_nop 0
	v_cndmask_b32_e64 v5, 0, v222, s[16:17]
	v_add_u32_e32 v3, v5, v3
	v_and_b32_e32 v5, 0x7fffff, v2
	v_or_b32_e32 v5, 0x800000, v5
	v_mad_u64_u32 v[26:27], s[18:19], v5, s2, 0
	v_mov_b32_e32 v128, v27
	s_mov_b32 s2, 0x3c439041
	v_mad_u64_u32 v[28:29], s[18:19], v5, s2, v[128:129]
	v_mov_b32_e32 v128, v29
	s_mov_b32 s2, 0xdb629599
	v_mad_u64_u32 v[30:31], s[18:19], v5, s2, v[128:129]
	v_mov_b32_e32 v128, v31
	s_mov_b32 s2, 0xf534ddc0
	v_mad_u64_u32 v[32:33], s[18:19], v5, s2, v[128:129]
	v_mov_b32_e32 v128, v33
	s_mov_b32 s2, 0xfc2757d1
	v_mad_u64_u32 v[34:35], s[18:19], v5, s2, v[128:129]
	v_mov_b32_e32 v128, v35
	s_mov_b32 s2, 0x4e441529
	v_mad_u64_u32 v[36:37], s[18:19], v5, s2, v[128:129]
	v_mov_b32_e32 v128, v37
	s_mov_b32 s2, 0xa2f9836e
	v_mad_u64_u32 v[38:39], s[18:19], v5, s2, v[128:129]
	v_cndmask_b32_e64 v23, v36, v32, s[12:13]
	v_cndmask_b32_e64 v5, v38, v34, s[12:13]
	v_cndmask_b32_e64 v29, v39, v36, s[12:13]
	v_cndmask_b32_e64 v27, v5, v23, s[14:15]
	v_cndmask_b32_e64 v5, v29, v5, s[14:15]
	v_cndmask_b32_e64 v29, v34, v30, s[12:13]
	v_cndmask_b32_e64 v23, v23, v29, s[14:15]
	v_cndmask_b32_e64 v5, v5, v27, s[16:17]
	v_cndmask_b32_e64 v27, v27, v23, s[16:17]
	v_sub_u32_e32 v31, 32, v3
	v_alignbit_b32 v33, v5, v27, v31
	v_cmp_eq_u32_e64 s[18:19], 0, v3
	v_cndmask_b32_e64 v26, v30, v26, s[12:13]
	s_mov_b32 s2, 0x3fc90fda
	v_cndmask_b32_e64 v3, v33, v5, s[18:19]
	v_cndmask_b32_e64 v5, v32, v28, s[12:13]
	v_cndmask_b32_e64 v28, v29, v5, s[14:15]
	v_cndmask_b32_e64 v23, v23, v28, s[16:17]
	v_alignbit_b32 v29, v27, v23, v31
	v_cndmask_b32_e64 v5, v5, v26, s[14:15]
	v_cndmask_b32_e64 v27, v29, v27, s[18:19]
	v_bfe_u32 v33, v3, 29, 1
	v_cndmask_b32_e64 v5, v28, v5, s[16:17]
	v_alignbit_b32 v29, v3, v27, 30
	v_sub_u32_e32 v34, 0, v33
	v_alignbit_b32 v26, v23, v5, v31
	v_xor_b32_e32 v29, v29, v34
	v_cndmask_b32_e64 v23, v26, v23, s[18:19]
	v_alignbit_b32 v26, v27, v23, 30
	v_ffbh_u32_e32 v27, v29
	v_min_u32_e32 v27, 32, v27
	v_alignbit_b32 v5, v23, v5, 30
	v_xor_b32_e32 v26, v26, v34
	v_sub_u32_e32 v28, 31, v27
	v_xor_b32_e32 v5, v5, v34
	v_alignbit_b32 v29, v29, v26, v28
	v_alignbit_b32 v5, v26, v5, v28
	v_alignbit_b32 v23, v29, v5, 9
	v_ffbh_u32_e32 v26, v23
	v_min_u32_e32 v26, 32, v26
	v_lshrrev_b32_e32 v32, 29, v3
	v_not_b32_e32 v28, v26
	v_alignbit_b32 v5, v23, v5, v28
	v_lshlrev_b32_e32 v23, 31, v32
	v_or_b32_e32 v28, 0x33000000, v23
	v_add_lshl_u32 v26, v26, v27, 23
	v_lshrrev_b32_e32 v5, 9, v5
	v_sub_u32_e32 v26, v28, v26
	v_or_b32_e32 v23, 0.5, v23
	v_lshlrev_b32_e32 v27, 23, v27
	v_or_b32_e32 v5, v26, v5
	v_lshrrev_b32_e32 v26, 9, v29
	v_sub_u32_e32 v23, v23, v27
	v_or_b32_e32 v23, v26, v23
	v_mul_f32_e32 v26, 0x3fc90fda, v23
	v_fma_f32 v27, v23, s2, -v26
	v_fmac_f32_e32 v27, 0x33a22168, v23
	v_fmac_f32_e32 v27, 0x3fc90fda, v5
	v_lshrrev_b32_e32 v3, 30, v3
	v_add_f32_e32 v5, v26, v27
	v_add_u32_e32 v3, v33, v3
	s_andn2_saveexec_b64 s[12:13], s[30:31]
	s_branch .LBB0_768

.LBB0_768:
	v_mul_f32_e32 v3, 0x3f22f983, v2
	v_rndne_f32_e32 v23, v3
	v_cvt_i32_f32_e32 v3, v23
	v_fmamk_f32 v5, v23, 0xbfc90fda, v2
	v_fmac_f32_e32 v5, 0xb3a22168, v23
	v_fmac_f32_e32 v5, 0xa7c234c4, v23
	s_or_b64 exec, exec, s[12:13]
	s_and_saveexec_b64 s[12:13], vcc
	s_xor_b64 s[18:19], exec, s[12:13]
	s_cbranch_execz .LBB0_771
	v_lshrrev_b32_e32 v23, 23, v2
	v_add_u32_e32 v23, 0xffffff88, v23
	v_cmp_lt_u32_e32 vcc, 63, v23
	s_mov_b32 s2, 0xfe5163ab
	s_nop 0
	v_cndmask_b32_e32 v26, 0, v221, vcc
	v_add_u32_e32 v23, v26, v23
	v_cmp_lt_u32_e64 s[12:13], 31, v23
	s_nop 1
	s_nop 0
	v_cndmask_b32_e64 v26, 0, v222, s[12:13]
	v_add_u32_e32 v23, v26, v23
	v_cmp_lt_u32_e64 s[14:15], 31, v23
	s_nop 1
	s_nop 0
	v_cndmask_b32_e64 v26, 0, v222, s[14:15]
	v_add_u32_e32 v23, v26, v23
	v_and_b32_e32 v26, 0x7fffff, v2
	v_or_b32_e32 v38, 0x800000, v26
	v_mad_u64_u32 v[26:27], s[16:17], v38, s2, 0
	v_mov_b32_e32 v128, v27
	s_mov_b32 s2, 0x3c439041
	v_mad_u64_u32 v[28:29], s[16:17], v38, s2, v[128:129]
	v_mov_b32_e32 v128, v29
	s_mov_b32 s2, 0xdb629599
	v_mad_u64_u32 v[30:31], s[16:17], v38, s2, v[128:129]
	v_mov_b32_e32 v128, v31
	s_mov_b32 s2, 0xf534ddc0
	v_mad_u64_u32 v[32:33], s[16:17], v38, s2, v[128:129]
	v_mov_b32_e32 v128, v33
	s_mov_b32 s2, 0xfc2757d1
	v_mad_u64_u32 v[34:35], s[16:17], v38, s2, v[128:129]
	v_mov_b32_e32 v128, v35
	s_mov_b32 s2, 0x4e441529
	v_mad_u64_u32 v[36:37], s[16:17], v38, s2, v[128:129]
	v_mov_b32_e32 v128, v37
	s_mov_b32 s2, 0xa2f9836e
	v_mad_u64_u32 v[38:39], s[16:17], v38, s2, v[128:129]
	v_cndmask_b32_e32 v27, v36, v32, vcc
	v_cndmask_b32_e32 v29, v38, v34, vcc
	v_cndmask_b32_e32 v33, v39, v36, vcc
	v_cndmask_b32_e64 v31, v29, v27, s[12:13]
	v_cndmask_b32_e64 v29, v33, v29, s[12:13]
	v_cndmask_b32_e32 v33, v34, v30, vcc
	v_cndmask_b32_e64 v27, v27, v33, s[12:13]
	v_cndmask_b32_e64 v29, v29, v31, s[14:15]
	v_cndmask_b32_e64 v31, v31, v27, s[14:15]
	v_sub_u32_e32 v34, 32, v23
	v_alignbit_b32 v35, v29, v31, v34
	v_cmp_eq_u32_e64 s[16:17], 0, v23
	v_cndmask_b32_e32 v28, v32, v28, vcc
	v_cndmask_b32_e32 v26, v30, v26, vcc
	v_cndmask_b32_e64 v23, v35, v29, s[16:17]
	v_cndmask_b32_e64 v29, v33, v28, s[12:13]
	v_cndmask_b32_e64 v27, v27, v29, s[14:15]
	v_alignbit_b32 v32, v31, v27, v34
	v_cndmask_b32_e64 v31, v32, v31, s[16:17]
	v_bfe_u32 v35, v23, 29, 1
	v_cndmask_b32_e64 v26, v28, v26, s[12:13]
	v_alignbit_b32 v32, v23, v31, 30
	v_sub_u32_e32 v36, 0, v35
	v_cndmask_b32_e64 v26, v29, v26, s[14:15]
	v_xor_b32_e32 v32, v32, v36
	v_alignbit_b32 v28, v27, v26, v34
	v_cndmask_b32_e64 v27, v28, v27, s[16:17]
	v_ffbh_u32_e32 v29, v32
	v_alignbit_b32 v28, v31, v27, 30
	v_min_u32_e32 v29, 32, v29
	v_alignbit_b32 v26, v27, v26, 30
	v_xor_b32_e32 v28, v28, v36
	v_sub_u32_e32 v30, 31, v29
	v_xor_b32_e32 v26, v26, v36
	v_alignbit_b32 v31, v32, v28, v30
	v_alignbit_b32 v26, v28, v26, v30
	v_alignbit_b32 v27, v31, v26, 9
	v_ffbh_u32_e32 v28, v27
	v_min_u32_e32 v28, 32, v28
	v_lshrrev_b32_e32 v33, 29, v23
	v_not_b32_e32 v30, v28
	v_alignbit_b32 v26, v27, v26, v30
	v_lshlrev_b32_e32 v27, 31, v33
	v_or_b32_e32 v30, 0x33000000, v27
	v_add_lshl_u32 v28, v28, v29, 23
	v_lshrrev_b32_e32 v26, 9, v26
	v_sub_u32_e32 v28, v30, v28
	v_or_b32_e32 v27, 0.5, v27
	v_lshlrev_b32_e32 v29, 23, v29
	v_or_b32_e32 v26, v28, v26
	v_lshrrev_b32_e32 v28, 9, v31
	v_sub_u32_e32 v27, v27, v29
	v_or_b32_e32 v27, v28, v27
	v_mul_f32_e32 v28, 0x3fc90fda, v27
	s_mov_b32 s2, 0x3fc90fda
	v_fma_f32 v29, v27, s2, -v28
	v_fmac_f32_e32 v29, 0x33a22168, v27
	v_fmac_f32_e32 v29, 0x3fc90fda, v26
	v_lshrrev_b32_e32 v23, 30, v23
	v_add_f32_e32 v26, v28, v29
	v_add_u32_e32 v23, v35, v23
	s_andn2_saveexec_b64 s[12:13], s[18:19]
	s_cbranch_execz .LBB0_748
	s_branch .LBB0_772

.LBB0_923:
	s_setprio 0
	s_waitcnt lgkmcnt(0)
	s_barrier
	s_load_dword s64, s[0:1], 0x118
	v_readlane_b32 s66, v252, 31
	v_readlane_b32 s67, v252, 32
	v_readlane_b32 s70, v252, 34
	v_readlane_b32 s76, v252, 36
	v_readlane_b32 s38, v252, 38
	v_readlane_b32 s61, v252, 30
	v_readlane_b32 s65, v252, 33
	v_readlane_b32 s71, v252, 35
	s_movk_i32 s72, 0xc00
	s_movk_i32 s73, 0x300
	s_movk_i32 s74, 0xaff
	v_readlane_b32 s77, v252, 37
	s_movk_i32 s75, 0xb00
	s_movk_i32 s78, 0xff80
	s_movk_i32 s79, 0x3ff
	s_movk_i32 s80, 0x400
	s_movk_i32 s81, 0x1800
	s_movk_i32 s82, 0xfff
	s_mov_b32 s83, 0x800000
	s_movk_i32 s84, 0x4fff
	s_movk_i32 s85, 0x48
	s_mov_b32 s86, 0x10000
	s_mov_b32 s87, 0x20000
	s_mov_b32 s88, 0x30000
	s_mov_b32 s89, 0xfff90000
	s_mov_b32 s90, 0xfffa0000
	s_mov_b32 s91, 0xfffb0000
	s_mov_b32 s92, 0xfffc0000
	s_mov_b32 s93, 0xfffd0000
	s_mov_b32 s94, 0xfffe0000
	s_mov_b32 s95, 0xffff0000
	s_movk_i32 s67, 0x1000
	s_movk_i32 s47, 0x110
	s_movk_i32 s53, 0x90
	s_mov_b32 s55, 0xfffffc0
	s_movk_i32 s42, 0x6800
	s_movk_i32 s43, 0x210
	s_mov_b32 s44, 0xfffb7000
	v_readlane_b32 s39, v252, 39
	s_mov_b64 s[36:37], 0x1000

.LBB0_1267:
	s_setprio 3
	v_mov_b32_e32 v180, v205
	s_mov_b64 s[4:5], s[0:1]
	s_bfe_u32 s92, s27, 0x10004
	s_load_dwordx2 s[4:5], s[4:5], 0x78
	s_lshl_b32 s2, s92, 4
	v_readlane_b32 s6, v252, 50
	s_and_b32 s93, s27, 15
	s_or_b32 s2, s2, s6
	v_readfirstlane_b32 s19, v180
	s_and_b32 s91, s27, 0xffffffe0
	s_or_b32 s2, s2, s93
	s_ashr_i32 s14, s19, 6
	s_add_i32 s91, s91, 32
	s_bfe_i32 s16, s27, 0x10004
	s_bfe_u32 s94, s27, 0x10003
	s_lshl_b64 s[6:7], s[2:3], 2
	s_waitcnt lgkmcnt(0)
	s_add_u32 s4, s4, s6
	s_addc_u32 s5, s5, s7
	global_load_dword v179, v129, s[4:5]
	s_mov_b64 s[4:5], s[0:1]
	s_load_dwordx2 s[8:9], s[4:5], 0x108
	s_mov_b64 s[4:5], s[0:1]
	s_load_dwordx2 s[70:71], s[4:5], 0x108
	s_mov_b64 s[4:5], s[0:1]
	s_mov_b64 s[6:7], s[0:1]
	s_load_dwordx2 s[4:5], s[4:5], 0x108
	s_load_dwordx2 s[10:11], s[6:7], 0x108
	s_mov_b64 s[6:7], s[0:1]
	s_load_dwordx2 s[6:7], s[6:7], 0x108
	v_and_b32_e32 v40, 31, v180
	v_bfe_u32 v37, v180, 5, 1
	v_lshlrev_b32_e32 v128, 2, v40
	v_lshlrev_b32_e32 v0, 11, v37
	s_waitcnt lgkmcnt(0)
	s_add_u32 s95, s6, 0x1d561000
	s_addc_u32 s96, s7, 0
	s_mov_b64 s[6:7], s[0:1]
	s_lshl_b32 s2, s14, 1
	s_load_dwordx2 s[12:13], s[6:7], 0x108
	s_add_i32 s15, s2, 2
	s_cmp_eq_u32 s92, 0
	s_cselect_b64 s[6:7], -1, 0
	s_and_b64 s[20:21], s[6:7], exec
	s_cselect_b32 s17, 0x1400, 0
	s_mov_b64 s[20:21], s[0:1]
	s_cselect_b32 s15, s15, 8
	s_waitcnt lgkmcnt(0)
	s_add_u32 s17, s12, s17
	s_addc_u32 s18, s13, 0
	s_lshl_b32 s12, s92, 3
	s_load_dwordx2 s[12:13], s[20:21], s12 offset:0x28
	s_lshl_b32 s20, s27, 1
	s_andn2_b32 s20, s20, 63
	v_readlane_b32 s21, v252, 51
	s_or_b32 s20, s21, s20
	s_or_b32 s20, s20, s93
	s_ashr_i32 s21, s20, 31
	s_lshl_b64 s[20:21], s[20:21], 15
	s_waitcnt lgkmcnt(0)
	s_add_u32 s22, s12, s20
	s_addc_u32 s23, s13, s21
	s_lshl_b32 s12, s14, 5
	s_ashr_i32 s13, s12, 31
	s_lshl_b64 s[20:21], s[12:13], 2
	s_add_u32 s20, s22, s20
	s_addc_u32 s21, s23, s21
	v_lshl_add_u64 v[2:3], s[20:21], 0, v[128:129]
	v_mov_b32_e32 v1, v129
	v_lshl_add_u64 v[28:29], v[2:3], 0, v[0:1]
	global_load_dword v0, v[28:29], off
	global_load_dword v1, v[28:29], off offset:512
	global_load_dword v2, v[28:29], off offset:1024
	global_load_dword v3, v[28:29], off offset:1536
	v_add_co_u32_e32 v8, vcc, s67, v28
	s_movk_i32 s20, 0x2000
	s_nop 0
	v_addc_co_u32_e32 v9, vcc, 0, v29, vcc
	v_add_co_u32_e32 v12, vcc, s20, v28
	s_movk_i32 s20, 0x3000
	s_nop 0
	v_addc_co_u32_e32 v13, vcc, 0, v29, vcc
	global_load_dword v4, v[12:13], off offset:-4096
	global_load_dword v5, v[8:9], off offset:512
	global_load_dword v6, v[8:9], off offset:1024
	global_load_dword v7, v[8:9], off offset:1536
	s_nop 0
	global_load_dword v8, v[12:13], off
	global_load_dword v9, v[12:13], off offset:512
	global_load_dword v10, v[12:13], off offset:1024
	global_load_dword v11, v[12:13], off offset:1536
	v_add_co_u32_e32 v16, vcc, s20, v28
	s_movk_i32 s20, 0x4000
	s_nop 0
	v_addc_co_u32_e32 v17, vcc, 0, v29, vcc
	v_add_co_u32_e32 v20, vcc, s20, v28
	s_movk_i32 s20, 0x5000
	s_nop 0
	v_addc_co_u32_e32 v21, vcc, 0, v29, vcc
	global_load_dword v12, v[20:21], off offset:-4096
	global_load_dword v13, v[16:17], off offset:512
	global_load_dword v14, v[16:17], off offset:1024
	global_load_dword v15, v[16:17], off offset:1536
	s_nop 0
	global_load_dword v16, v[20:21], off
	global_load_dword v17, v[20:21], off offset:512
	global_load_dword v18, v[20:21], off offset:1024
	global_load_dword v19, v[20:21], off offset:1536
	v_add_co_u32_e32 v24, vcc, s20, v28
	s_movk_i32 s20, 0x6000
	s_nop 0
	v_addc_co_u32_e32 v25, vcc, 0, v29, vcc
	v_add_co_u32_e32 v30, vcc, s20, v28
	s_movk_i32 s20, 0x7000
	s_nop 0
	v_addc_co_u32_e32 v31, vcc, 0, v29, vcc
	global_load_dword v20, v[30:31], off offset:-4096
	global_load_dword v21, v[24:25], off offset:512
	global_load_dword v22, v[24:25], off offset:1024
	global_load_dword v23, v[24:25], off offset:1536
	s_nop 0
	global_load_dword v24, v[30:31], off
	global_load_dword v25, v[30:31], off offset:512
	global_load_dword v26, v[30:31], off offset:1024
	global_load_dword v27, v[30:31], off offset:1536
	v_add_co_u32_e32 v32, vcc, s20, v28
	s_andn2_b32 s19, s19, 63
	s_nop 0
	v_addc_co_u32_e32 v33, vcc, 0, v29, vcc
	global_load_dword v28, v[32:33], off
	global_load_dword v29, v[32:33], off offset:512
	global_load_dword v30, v[32:33], off offset:1024
	global_load_dword v31, v[32:33], off offset:1536
	v_lshlrev_b32_e32 v36, 1, v40
	v_or_b32_e32 v32, s19, v36
	s_movk_i32 s20, 0x440
	v_mad_u32_u24 v32, v37, s20, v32
	s_waitcnt vmcnt(63) expcnt(7) lgkmcnt(15)
	s_barrier
	s_and_b32 s16, s16, s2
	s_lshl_b32 s2, s93, 14
	s_add_u32 s8, s8, s2
	v_or_b32_e32 v182, s12, v40
	s_addc_u32 s9, s9, 0
	v_ashrrev_i32_e32 v183, 31, v182
	s_movk_i32 s2, 0x80
	s_lshl_b32 s52, s14, 7
	v_ashrrev_i32_e32 v42, 4, v180
	v_ashrrev_i32_e32 v43, 31, v42
	v_lshlrev_b64 v[188:189], 8, v[42:43]
	v_lshlrev_b32_e32 v34, 3, v37
	v_cmp_ge_i32_e32 vcc, v34, v182
	v_mul_u32_u24_e32 v35, 0x440, v37
	v_lshl_or_b32 v203, v37, 2, s12
	v_lshl_add_u64 v[190:191], v[188:189], 0, s[36:37]
	v_mul_u32_u24_e32 v39, 0x110, v40
	s_mov_b32 s90, 31
	s_mov_b32 s97, 0
	v_ashrrev_i32_e32 v181, 31, v180
	v_lshlrev_b32_e32 v204, 2, v180
	v_or_b32_e32 v228, 1, v203
	v_or_b32_e32 v229, 2, v203
	v_or_b32_e32 v230, 3, v203
	v_or_b32_e32 v231, 8, v203
	v_or_b32_e32 v232, 9, v203
	v_or_b32_e32 v233, 10, v203
	v_or_b32_e32 v234, 11, v203
	v_or_b32_e32 v235, 16, v203
	v_or_b32_e32 v236, 17, v203
	s_waitcnt vmcnt(31)
	v_cvt_pk_bf16_f32 v33, v0, s0
	ds_write_b16 v32, v33 offset:34816
	s_waitcnt vmcnt(30)
	v_cvt_pk_bf16_f32 v33, v1, s0
	ds_write_b16 v32, v33 offset:35088
	s_waitcnt vmcnt(29)
	v_cvt_pk_bf16_f32 v33, v2, s0
	ds_write_b16 v32, v33 offset:35360
	s_waitcnt vmcnt(28)
	v_cvt_pk_bf16_f32 v33, v3, s0
	ds_write_b16 v32, v33 offset:35632
	s_waitcnt vmcnt(27)
	v_cvt_pk_bf16_f32 v33, v4, s0
	ds_write_b16 v32, v33 offset:36992
	s_waitcnt vmcnt(26)
	v_cvt_pk_bf16_f32 v33, v5, s0
	ds_write_b16 v32, v33 offset:37264
	s_waitcnt vmcnt(25)
	v_cvt_pk_bf16_f32 v33, v6, s0
	ds_write_b16 v32, v33 offset:37536
	s_waitcnt vmcnt(24)
	v_cvt_pk_bf16_f32 v33, v7, s0
	ds_write_b16 v32, v33 offset:37808
	s_waitcnt vmcnt(23)
	v_cvt_pk_bf16_f32 v33, v8, s0
	ds_write_b16 v32, v33 offset:39168
	s_waitcnt vmcnt(22)
	v_cvt_pk_bf16_f32 v33, v9, s0
	ds_write_b16 v32, v33 offset:39440
	s_waitcnt vmcnt(21)
	v_cvt_pk_bf16_f32 v33, v10, s0
	ds_write_b16 v32, v33 offset:39712
	s_waitcnt vmcnt(20)
	v_cvt_pk_bf16_f32 v33, v11, s0
	ds_write_b16 v32, v33 offset:39984
	s_waitcnt vmcnt(19)
	v_cvt_pk_bf16_f32 v33, v12, s0
	ds_write_b16 v32, v33 offset:41344
	s_waitcnt vmcnt(18)
	v_cvt_pk_bf16_f32 v33, v13, s0
	ds_write_b16 v32, v33 offset:41616
	s_waitcnt vmcnt(17)
	v_cvt_pk_bf16_f32 v33, v14, s0
	ds_write_b16 v32, v33 offset:41888
	s_waitcnt vmcnt(16)
	v_cvt_pk_bf16_f32 v33, v15, s0
	ds_write_b16 v32, v33 offset:42160
	s_waitcnt vmcnt(15)
	v_cvt_pk_bf16_f32 v33, v16, s0
	ds_write_b16 v32, v33 offset:43520
	s_waitcnt vmcnt(14)
	v_cvt_pk_bf16_f32 v33, v17, s0
	ds_write_b16 v32, v33 offset:43792
	s_waitcnt vmcnt(13)
	v_cvt_pk_bf16_f32 v33, v18, s0
	ds_write_b16 v32, v33 offset:44064
	s_waitcnt vmcnt(12)
	v_cvt_pk_bf16_f32 v33, v19, s0
	ds_write_b16 v32, v33 offset:44336
	s_waitcnt vmcnt(11)
	v_cvt_pk_bf16_f32 v33, v20, s0
	ds_write_b16 v32, v33 offset:45696
	s_waitcnt vmcnt(10)
	v_cvt_pk_bf16_f32 v33, v21, s0
	ds_write_b16 v32, v33 offset:45968
	s_waitcnt vmcnt(9)
	v_cvt_pk_bf16_f32 v33, v22, s0
	ds_write_b16 v32, v33 offset:46240
	s_waitcnt vmcnt(8)
	v_cvt_pk_bf16_f32 v33, v23, s0
	ds_write_b16 v32, v33 offset:46512
	s_waitcnt vmcnt(7)
	v_cvt_pk_bf16_f32 v33, v24, s0
	ds_write_b16 v32, v33 offset:47872
	s_waitcnt vmcnt(6)
	v_cvt_pk_bf16_f32 v33, v25, s0
	ds_write_b16 v32, v33 offset:48144
	s_waitcnt vmcnt(5)
	v_cvt_pk_bf16_f32 v33, v26, s0
	ds_write_b16 v32, v33 offset:48416
	s_waitcnt vmcnt(4)
	v_cvt_pk_bf16_f32 v33, v27, s0
	ds_write_b16 v32, v33 offset:48688
	s_waitcnt vmcnt(3)
	v_cvt_pk_bf16_f32 v33, v28, s0
	ds_write_b16 v32, v33 offset:50048
	s_waitcnt vmcnt(2)
	v_cvt_pk_bf16_f32 v33, v29, s0
	ds_write_b16 v32, v33 offset:50320
	s_waitcnt vmcnt(1)
	v_cvt_pk_bf16_f32 v33, v30, s0
	ds_write_b16 v32, v33 offset:50592
	s_waitcnt vmcnt(0)
	v_cvt_pk_bf16_f32 v33, v31, s0
	ds_write_b16 v32, v33 offset:50864
	v_lshlrev_b32_e32 v32, 3, v180
	v_and_b32_e32 v38, 0x78, v32
	v_lshlrev_b32_e32 v128, 1, v38
	v_lshl_add_u64 v[32:33], s[8:9], 0, v[128:129]
	s_mov_b64 s[8:9], 0x10520000
	v_lshl_add_u64 v[184:185], v[32:33], 0, s[8:9]
	v_lshlrev_b64 v[32:33], 8, v[182:183]
	v_lshl_add_u64 v[44:45], s[10:11], 0, v[32:33]
	v_lshlrev_b32_e32 v32, 4, v37
	v_mov_b32_e32 v33, v129
	v_cmp_gt_i32_e64 s[8:9], s2, v180
	s_lshl_b32 s2, s94, 7
	v_lshl_add_u64 v[46:47], s[4:5], 0, v[32:33]
	s_lshl_b32 s4, s93, 7
	s_add_u32 s50, s17, s4
	s_addc_u32 s51, s18, 0
	s_sub_i32 s4, s52, s19
	v_lshl_add_u64 v[44:45], v[44:45], 0, v[32:33]
	v_or_b32_e32 v33, s4, v36
	s_mov_b64 s[4:5], 0x2000
	v_lshl_add_u64 v[192:193], v[188:189], 0, s[4:5]
	s_mov_b64 s[4:5], 0x3000
	s_cmp_lt_i32 s16, 1
	s_mov_b64 s[10:11], 0x1c980000
	v_lshl_add_u64 v[194:195], v[188:189], 0, s[4:5]
	s_cselect_b64 s[4:5], -1, 0
	s_cmp_gt_i32 s15, 0
	v_lshl_add_u64 v[186:187], v[44:45], 0, s[10:11]
	s_cselect_b64 s[10:11], -1, 0
	s_and_b64 s[72:73], s[4:5], s[10:11]
	s_cmp_lt_i32 s16, 2
	s_cselect_b64 s[4:5], -1, 0
	s_cmp_gt_i32 s15, 1
	s_cselect_b64 s[10:11], -1, 0
	s_and_b64 s[74:75], s[4:5], s[10:11]
	s_cmp_lt_i32 s16, 3
	s_cselect_b64 s[4:5], -1, 0
	s_cmp_gt_i32 s15, 2
	s_cselect_b64 s[10:11], -1, 0
	s_and_b64 s[76:77], s[4:5], s[10:11]
	s_cmp_lt_i32 s16, 4
	s_cselect_b64 s[4:5], -1, 0
	s_cmp_gt_i32 s15, 3
	s_cselect_b64 s[10:11], -1, 0
	s_and_b64 s[78:79], s[4:5], s[10:11]
	s_cmp_lt_i32 s16, 5
	s_cselect_b64 s[4:5], -1, 0
	s_cmp_gt_i32 s15, 4
	s_cselect_b64 s[10:11], -1, 0
	s_and_b64 s[80:81], s[4:5], s[10:11]
	s_cmp_lt_i32 s16, 6
	s_cselect_b64 s[4:5], -1, 0
	s_cmp_gt_i32 s15, 5
	s_cselect_b64 s[10:11], -1, 0
	s_and_b64 s[82:83], s[4:5], s[10:11]
	s_cmp_lt_i32 s16, 7
	s_cselect_b64 s[4:5], -1, 0
	s_cmp_gt_i32 s15, 6
	s_cselect_b64 s[10:11], -1, 0
	s_and_b64 s[84:85], s[4:5], s[10:11]
	v_or_b32_e32 v44, s2, v40
	v_mov_b32_e32 v45, v129
	s_cmp_lt_i32 s16, 8
	v_lshl_add_u64 v[44:45], s[12:13], 0, v[44:45]
	s_cselect_b64 s[4:5], -1, 0
	s_cmp_gt_i32 s15, 7
	v_lshlrev_b64 v[44:45], 8, v[44:45]
	s_cselect_b64 s[10:11], -1, 0
	s_and_b64 s[86:87], s[4:5], s[10:11]
	v_lshl_add_u64 v[44:45], v[46:47], 0, v[44:45]
	s_mov_b64 s[4:5], 0x14120000
	v_lshl_add_u64 v[196:197], v[44:45], 0, s[4:5]
	v_mad_u64_u32 v[198:199], s[4:5], v42, s47, v[128:129]
	v_cmp_le_i32_e64 s[4:5], v34, v182
	v_cndmask_b32_e64 v42, 0, 1, vcc
	v_lshlrev_b32_e32 v199, 5, v37
	v_cndmask_b32_e64 v41, 0, 1, s[4:5]
	v_cndmask_b32_e64 v41, v42, v41, s[6:7]
	v_and_b32_e32 v41, 1, v41
	v_cmp_eq_u32_e64 s[4:5], 1, v41
	v_or_b32_e32 v37, 1, v34
	v_cmp_ge_i32_e32 vcc, v37, v182
	v_writelane_b32 v252, s4, 52
	v_lshlrev_b32_e32 v183, 2, v182
	v_cndmask_b32_e64 v41, 0, 1, vcc
	v_writelane_b32 v252, s5, 53
	v_cmp_lt_i32_e64 s[4:5], v34, v182
	v_or_b32_e32 v237, 18, v203
	v_or_b32_e32 v238, 19, v203
	v_cndmask_b32_e64 v37, 0, 1, s[4:5]
	v_cndmask_b32_e64 v37, v41, v37, s[6:7]
	v_and_b32_e32 v37, 1, v37
	v_cmp_eq_u32_e64 s[4:5], 1, v37
	v_or_b32_e32 v37, 2, v34
	v_cmp_ge_i32_e32 vcc, v37, v182
	v_writelane_b32 v252, s4, 54
	v_or_b32_e32 v239, 24, v203
	v_cndmask_b32_e64 v41, 0, 1, vcc
	v_writelane_b32 v252, s5, 55
	v_cmp_le_i32_e64 s[4:5], v37, v182
	v_or_b32_e32 v240, 25, v203
	v_or_b32_e32 v241, 26, v203
	v_cndmask_b32_e64 v37, 0, 1, s[4:5]
	v_cndmask_b32_e64 v37, v41, v37, s[6:7]
	v_and_b32_e32 v37, 1, v37
	v_cmp_eq_u32_e64 s[4:5], 1, v37
	v_or_b32_e32 v37, 3, v34
	v_cmp_ge_i32_e32 vcc, v37, v182
	v_writelane_b32 v252, s4, 56
	v_or_b32_e32 v242, 27, v203
	v_cndmask_b32_e64 v41, 0, 1, vcc
	v_writelane_b32 v252, s5, 57
	v_cmp_le_i32_e64 s[4:5], v37, v182
	v_lshlrev_b32_e32 v244, 2, v38
	s_lshl_b32 s2, s2, 1
	v_cndmask_b32_e64 v37, 0, 1, s[4:5]
	v_cndmask_b32_e64 v37, v41, v37, s[6:7]
	v_and_b32_e32 v37, 1, v37
	v_cmp_eq_u32_e64 s[4:5], 1, v37
	v_or_b32_e32 v37, 4, v34
	v_cmp_ge_i32_e32 vcc, v37, v182
	v_writelane_b32 v252, s4, 58
	v_lshlrev_b32_e32 v128, 1, v34
	v_cndmask_b32_e64 v41, 0, 1, vcc
	v_writelane_b32 v252, s5, 59
	v_cmp_le_i32_e64 s[4:5], v37, v182
	v_add_u32_e32 v245, s52, v32
	v_add_u32_e32 v246, v33, v35
	v_cndmask_b32_e64 v37, 0, 1, s[4:5]
	v_cndmask_b32_e64 v37, v41, v37, s[6:7]
	v_and_b32_e32 v37, 1, v37
	v_cmp_eq_u32_e64 s[4:5], 1, v37
	v_or_b32_e32 v37, 5, v34
	v_cmp_ge_i32_e32 vcc, v37, v182
	v_writelane_b32 v252, s4, 60
	v_add_u32_e32 v247, v32, v39
	v_cndmask_b32_e64 v41, 0, 1, vcc
	v_writelane_b32 v252, s5, 61
	v_cmp_le_i32_e64 s[4:5], v37, v182
	s_nop 1
	v_cndmask_b32_e64 v37, 0, 1, s[4:5]
	v_cndmask_b32_e64 v37, v41, v37, s[6:7]
	v_and_b32_e32 v37, 1, v37
	v_cmp_eq_u32_e64 s[4:5], 1, v37
	v_or_b32_e32 v37, 6, v34
	v_cmp_ge_i32_e32 vcc, v37, v182
	v_writelane_b32 v252, s4, 62
	s_nop 0
	v_cndmask_b32_e64 v41, 0, 1, vcc
	v_writelane_b32 v252, s5, 63
	v_cmp_le_i32_e64 s[4:5], v37, v182
	s_nop 1
	v_cndmask_b32_e64 v37, 0, 1, s[4:5]
	v_cndmask_b32_e64 v37, v41, v37, s[6:7]
	v_and_b32_e32 v37, 1, v37
	v_cmp_eq_u32_e64 s[4:5], 1, v37
	v_or_b32_e32 v37, 7, v34
	v_cmp_ge_i32_e32 vcc, v37, v182
	v_writelane_b32 v251, s4, 0
	s_nop 0
	v_cndmask_b32_e64 v41, 0, 1, vcc
	v_writelane_b32 v251, s5, 1
	v_cmp_le_i32_e64 s[4:5], v37, v182
	s_nop 1
	v_cndmask_b32_e64 v37, 0, 1, s[4:5]
	v_cndmask_b32_e64 v37, v41, v37, s[6:7]
	v_and_b32_e32 v37, 1, v37
	v_cmp_eq_u32_e64 s[4:5], 1, v37
	v_or_b32_e32 v37, 16, v34
	v_cmp_ge_i32_e32 vcc, v37, v182
	v_writelane_b32 v251, s4, 2
	s_nop 0
	v_cndmask_b32_e64 v41, 0, 1, vcc
	v_writelane_b32 v251, s5, 3
	v_cmp_le_i32_e64 s[4:5], v37, v182
	s_nop 1
	v_cndmask_b32_e64 v37, 0, 1, s[4:5]
	v_cndmask_b32_e64 v37, v41, v37, s[6:7]
	v_and_b32_e32 v37, 1, v37
	v_cmp_eq_u32_e64 s[4:5], 1, v37
	v_or_b32_e32 v37, 17, v34
	v_cmp_ge_i32_e32 vcc, v37, v182
	v_writelane_b32 v251, s4, 4
	s_nop 0
	v_cndmask_b32_e64 v41, 0, 1, vcc
	v_writelane_b32 v251, s5, 5
	v_cmp_le_i32_e64 s[4:5], v37, v182
	s_nop 1
	v_cndmask_b32_e64 v37, 0, 1, s[4:5]
	v_cndmask_b32_e64 v37, v41, v37, s[6:7]
	v_and_b32_e32 v37, 1, v37
	v_cmp_eq_u32_e64 s[4:5], 1, v37
	v_or_b32_e32 v37, 18, v34
	v_cmp_ge_i32_e32 vcc, v37, v182
	v_writelane_b32 v251, s4, 6
	s_nop 0
	v_cndmask_b32_e64 v41, 0, 1, vcc
	v_writelane_b32 v251, s5, 7
	v_cmp_le_i32_e64 s[4:5], v37, v182
	s_nop 1
	v_cndmask_b32_e64 v37, 0, 1, s[4:5]
	v_cndmask_b32_e64 v37, v41, v37, s[6:7]
	v_and_b32_e32 v37, 1, v37
	v_cmp_eq_u32_e64 s[4:5], 1, v37
	v_or_b32_e32 v37, 19, v34
	v_cmp_ge_i32_e32 vcc, v37, v182
	v_writelane_b32 v251, s4, 8
	s_nop 0
	v_cndmask_b32_e64 v41, 0, 1, vcc
	v_writelane_b32 v251, s5, 9
	v_cmp_le_i32_e64 s[4:5], v37, v182
	s_nop 1
	v_cndmask_b32_e64 v37, 0, 1, s[4:5]
	v_cndmask_b32_e64 v37, v41, v37, s[6:7]
	v_and_b32_e32 v37, 1, v37
	v_cmp_eq_u32_e64 s[4:5], 1, v37
	v_or_b32_e32 v37, 20, v34
	v_cmp_ge_i32_e32 vcc, v37, v182
	v_writelane_b32 v251, s4, 10
	s_nop 0
	v_cndmask_b32_e64 v41, 0, 1, vcc
	v_writelane_b32 v251, s5, 11
	v_cmp_le_i32_e64 s[4:5], v37, v182
	s_nop 1
	v_cndmask_b32_e64 v37, 0, 1, s[4:5]
	v_cndmask_b32_e64 v37, v41, v37, s[6:7]
	v_and_b32_e32 v37, 1, v37
	v_cmp_eq_u32_e64 s[4:5], 1, v37
	v_or_b32_e32 v37, 21, v34
	v_cmp_ge_i32_e32 vcc, v37, v182
	v_writelane_b32 v251, s4, 12
	s_nop 0
	v_cndmask_b32_e64 v41, 0, 1, vcc
	v_writelane_b32 v251, s5, 13
	v_cmp_le_i32_e64 s[4:5], v37, v182
	s_nop 1
	v_cndmask_b32_e64 v37, 0, 1, s[4:5]
	v_cndmask_b32_e64 v37, v41, v37, s[6:7]
	v_and_b32_e32 v37, 1, v37
	v_cmp_eq_u32_e64 s[4:5], 1, v37
	v_or_b32_e32 v37, 22, v34
	v_cmp_ge_i32_e32 vcc, v37, v182
	v_writelane_b32 v251, s4, 14
	s_nop 0
	v_cndmask_b32_e64 v41, 0, 1, vcc
	v_writelane_b32 v251, s5, 15
	v_cmp_le_i32_e64 s[4:5], v37, v182
	s_nop 1
	v_cndmask_b32_e64 v37, 0, 1, s[4:5]
	v_cndmask_b32_e64 v37, v41, v37, s[6:7]
	v_and_b32_e32 v37, 1, v37
	v_cmp_eq_u32_e64 s[4:5], 1, v37
	v_or_b32_e32 v37, 23, v34
	v_cmp_ge_i32_e32 vcc, v37, v182
	v_writelane_b32 v251, s4, 16
	s_nop 0
	v_cndmask_b32_e64 v41, 0, 1, vcc
	v_writelane_b32 v251, s5, 17
	v_cmp_le_i32_e64 s[4:5], v37, v182
	s_nop 1
	v_cndmask_b32_e64 v37, 0, 1, s[4:5]
	v_cndmask_b32_e64 v37, v41, v37, s[6:7]
	v_and_b32_e32 v37, 1, v37
	v_cmp_eq_u32_e64 s[4:5], 1, v37
	v_or_b32_e32 v37, 32, v34
	v_cmp_ge_i32_e32 vcc, v37, v182
	v_writelane_b32 v251, s4, 18
	s_nop 0
	v_cndmask_b32_e64 v41, 0, 1, vcc
	v_writelane_b32 v251, s5, 19
	v_cmp_le_i32_e64 s[4:5], v37, v182
	s_nop 1
	v_cndmask_b32_e64 v37, 0, 1, s[4:5]
	v_cndmask_b32_e64 v37, v41, v37, s[6:7]
	v_and_b32_e32 v37, 1, v37
	v_cmp_eq_u32_e64 s[4:5], 1, v37
	v_or_b32_e32 v37, 33, v34
	v_cmp_ge_i32_e32 vcc, v37, v182
	v_writelane_b32 v251, s4, 20
	s_nop 0
	v_cndmask_b32_e64 v41, 0, 1, vcc
	v_writelane_b32 v251, s5, 21
	v_cmp_le_i32_e64 s[4:5], v37, v182
	s_nop 1
	v_cndmask_b32_e64 v37, 0, 1, s[4:5]
	v_cndmask_b32_e64 v37, v41, v37, s[6:7]
	v_and_b32_e32 v37, 1, v37
	v_cmp_eq_u32_e64 s[4:5], 1, v37
	v_or_b32_e32 v37, 34, v34
	v_cmp_ge_i32_e32 vcc, v37, v182
	v_writelane_b32 v251, s4, 22
	s_nop 0
	v_cndmask_b32_e64 v41, 0, 1, vcc
	v_writelane_b32 v251, s5, 23
	v_cmp_le_i32_e64 s[4:5], v37, v182
	s_nop 1
	v_cndmask_b32_e64 v37, 0, 1, s[4:5]
	v_cndmask_b32_e64 v37, v41, v37, s[6:7]
	v_and_b32_e32 v37, 1, v37
	v_cmp_eq_u32_e64 s[4:5], 1, v37
	v_or_b32_e32 v37, 35, v34
	v_cmp_ge_i32_e32 vcc, v37, v182
	v_writelane_b32 v251, s4, 24
	s_nop 0
	v_cndmask_b32_e64 v41, 0, 1, vcc
	v_writelane_b32 v251, s5, 25
	v_cmp_le_i32_e64 s[4:5], v37, v182
	s_nop 1
	v_cndmask_b32_e64 v37, 0, 1, s[4:5]
	v_cndmask_b32_e64 v37, v41, v37, s[6:7]
	v_and_b32_e32 v37, 1, v37
	v_cmp_eq_u32_e64 s[4:5], 1, v37
	v_or_b32_e32 v37, 36, v34
	v_cmp_ge_i32_e32 vcc, v37, v182
	v_writelane_b32 v251, s4, 26
	s_nop 0
	v_cndmask_b32_e64 v41, 0, 1, vcc
	v_writelane_b32 v251, s5, 27
	v_cmp_le_i32_e64 s[4:5], v37, v182
	s_nop 1
	v_cndmask_b32_e64 v37, 0, 1, s[4:5]
	v_cndmask_b32_e64 v37, v41, v37, s[6:7]
	v_and_b32_e32 v37, 1, v37
	v_cmp_eq_u32_e64 s[4:5], 1, v37
	v_or_b32_e32 v37, 37, v34
	v_cmp_ge_i32_e32 vcc, v37, v182
	v_writelane_b32 v251, s4, 28
	s_nop 0
	v_cndmask_b32_e64 v41, 0, 1, vcc
	v_writelane_b32 v251, s5, 29
	v_cmp_le_i32_e64 s[4:5], v37, v182
	s_nop 1
	v_cndmask_b32_e64 v37, 0, 1, s[4:5]
	v_cndmask_b32_e64 v37, v41, v37, s[6:7]
	v_and_b32_e32 v37, 1, v37
	v_cmp_eq_u32_e64 s[4:5], 1, v37
	v_or_b32_e32 v37, 38, v34
	v_cmp_ge_i32_e32 vcc, v37, v182
	v_writelane_b32 v251, s4, 30
	s_nop 0
	v_cndmask_b32_e64 v41, 0, 1, vcc
	v_writelane_b32 v251, s5, 31
	v_cmp_le_i32_e64 s[4:5], v37, v182
	s_nop 1
	v_cndmask_b32_e64 v37, 0, 1, s[4:5]
	v_cndmask_b32_e64 v37, v41, v37, s[6:7]
	v_and_b32_e32 v37, 1, v37
	v_cmp_eq_u32_e64 s[4:5], 1, v37
	v_or_b32_e32 v37, 39, v34
	v_cmp_ge_i32_e32 vcc, v37, v182
	v_writelane_b32 v251, s4, 32
	s_nop 0
	v_cndmask_b32_e64 v41, 0, 1, vcc
	v_writelane_b32 v251, s5, 33
	v_cmp_le_i32_e64 s[4:5], v37, v182
	s_nop 1
	v_cndmask_b32_e64 v37, 0, 1, s[4:5]
	v_cndmask_b32_e64 v37, v41, v37, s[6:7]
	v_and_b32_e32 v37, 1, v37
	v_cmp_eq_u32_e64 s[4:5], 1, v37
	v_or_b32_e32 v37, 48, v34
	v_cmp_ge_i32_e32 vcc, v37, v182
	v_writelane_b32 v251, s4, 34
	s_nop 0
	v_cndmask_b32_e64 v41, 0, 1, vcc
	v_writelane_b32 v251, s5, 35
	v_cmp_le_i32_e64 s[4:5], v37, v182
	s_nop 1
	v_cndmask_b32_e64 v37, 0, 1, s[4:5]
	v_cndmask_b32_e64 v37, v41, v37, s[6:7]
	v_and_b32_e32 v37, 1, v37
	v_cmp_eq_u32_e64 s[4:5], 1, v37
	v_or_b32_e32 v37, 49, v34
	v_cmp_ge_i32_e32 vcc, v37, v182
	v_writelane_b32 v251, s4, 36
	s_nop 0
	v_cndmask_b32_e64 v41, 0, 1, vcc
	v_writelane_b32 v251, s5, 37
	v_cmp_le_i32_e64 s[4:5], v37, v182
	s_nop 1
	v_cndmask_b32_e64 v37, 0, 1, s[4:5]
	v_cndmask_b32_e64 v37, v41, v37, s[6:7]
	v_and_b32_e32 v37, 1, v37
	v_cmp_eq_u32_e64 s[4:5], 1, v37
	v_or_b32_e32 v37, 50, v34
	v_cmp_ge_i32_e32 vcc, v37, v182
	v_writelane_b32 v251, s4, 38
	s_nop 0
	v_cndmask_b32_e64 v41, 0, 1, vcc
	v_writelane_b32 v251, s5, 39
	v_cmp_le_i32_e64 s[4:5], v37, v182
	s_nop 1
	v_cndmask_b32_e64 v37, 0, 1, s[4:5]
	v_cndmask_b32_e64 v37, v41, v37, s[6:7]
	v_and_b32_e32 v37, 1, v37
	v_cmp_eq_u32_e64 s[4:5], 1, v37
	v_or_b32_e32 v37, 51, v34
	v_cmp_ge_i32_e32 vcc, v37, v182
	v_writelane_b32 v251, s4, 40
	s_nop 0
	v_cndmask_b32_e64 v41, 0, 1, vcc
	v_writelane_b32 v251, s5, 41
	v_cmp_le_i32_e64 s[4:5], v37, v182
	s_nop 1
	v_cndmask_b32_e64 v37, 0, 1, s[4:5]
	v_cndmask_b32_e64 v37, v41, v37, s[6:7]
	v_and_b32_e32 v37, 1, v37
	v_cmp_eq_u32_e64 s[4:5], 1, v37
	v_or_b32_e32 v37, 52, v34
	v_cmp_ge_i32_e32 vcc, v37, v182
	v_writelane_b32 v251, s4, 42
	s_nop 0
	v_cndmask_b32_e64 v41, 0, 1, vcc
	v_writelane_b32 v251, s5, 43
	v_cmp_le_i32_e64 s[4:5], v37, v182
	s_nop 1
	v_cndmask_b32_e64 v37, 0, 1, s[4:5]
	v_cndmask_b32_e64 v37, v41, v37, s[6:7]
	v_and_b32_e32 v37, 1, v37
	v_cmp_eq_u32_e64 s[4:5], 1, v37
	v_or_b32_e32 v37, 53, v34
	v_cmp_ge_i32_e32 vcc, v37, v182
	v_writelane_b32 v251, s4, 44
	s_nop 0
	v_cndmask_b32_e64 v41, 0, 1, vcc
	v_writelane_b32 v251, s5, 45
	v_cmp_le_i32_e64 s[4:5], v37, v182
	s_nop 1
	v_cndmask_b32_e64 v37, 0, 1, s[4:5]
	v_cndmask_b32_e64 v37, v41, v37, s[6:7]
	v_and_b32_e32 v37, 1, v37
	v_cmp_eq_u32_e64 s[4:5], 1, v37
	v_or_b32_e32 v37, 54, v34
	v_cmp_ge_i32_e32 vcc, v37, v182
	v_writelane_b32 v251, s4, 46
	s_nop 0
	v_cndmask_b32_e64 v41, 0, 1, vcc
	v_writelane_b32 v251, s5, 47
	v_cmp_le_i32_e64 s[4:5], v37, v182
	s_nop 1
	v_cndmask_b32_e64 v37, 0, 1, s[4:5]
	v_cndmask_b32_e64 v37, v41, v37, s[6:7]
	v_and_b32_e32 v37, 1, v37
	v_cmp_eq_u32_e64 s[4:5], 1, v37
	v_or_b32_e32 v37, 55, v34
	v_cmp_ge_i32_e32 vcc, v37, v182
	v_writelane_b32 v251, s4, 48
	s_nop 0
	v_cndmask_b32_e64 v41, 0, 1, vcc
	v_writelane_b32 v251, s5, 49
	v_cmp_le_i32_e64 s[4:5], v37, v182
	s_nop 1
	v_cndmask_b32_e64 v37, 0, 1, s[4:5]
	v_cndmask_b32_e64 v37, v41, v37, s[6:7]
	v_and_b32_e32 v37, 1, v37
	v_cmp_eq_u32_e64 s[4:5], 1, v37
	v_or_b32_e32 v37, 64, v34
	v_cmp_ge_i32_e32 vcc, v37, v182
	v_writelane_b32 v251, s4, 50
	s_nop 0
	v_cndmask_b32_e64 v41, 0, 1, vcc
	v_writelane_b32 v251, s5, 51
	v_cmp_le_i32_e64 s[4:5], v37, v182
	s_nop 1
	v_cndmask_b32_e64 v37, 0, 1, s[4:5]
	v_cndmask_b32_e64 v37, v41, v37, s[6:7]
	v_and_b32_e32 v37, 1, v37
	v_cmp_eq_u32_e64 s[4:5], 1, v37
	v_or_b32_e32 v37, 0x41, v34
	v_cmp_ge_i32_e32 vcc, v37, v182
	v_writelane_b32 v251, s4, 52
	s_nop 0
	v_cndmask_b32_e64 v41, 0, 1, vcc
	v_writelane_b32 v251, s5, 53
	v_cmp_le_i32_e64 s[4:5], v37, v182
	s_nop 1
	v_cndmask_b32_e64 v37, 0, 1, s[4:5]
	v_cndmask_b32_e64 v37, v41, v37, s[6:7]
	v_and_b32_e32 v37, 1, v37
	v_cmp_eq_u32_e64 s[4:5], 1, v37
	v_or_b32_e32 v37, 0x42, v34
	v_cmp_ge_i32_e32 vcc, v37, v182
	v_writelane_b32 v251, s4, 54
	s_nop 0
	v_cndmask_b32_e64 v41, 0, 1, vcc
	v_writelane_b32 v251, s5, 55
	v_cmp_le_i32_e64 s[4:5], v37, v182
	s_nop 1
	v_cndmask_b32_e64 v37, 0, 1, s[4:5]
	v_cndmask_b32_e64 v37, v41, v37, s[6:7]
	v_and_b32_e32 v37, 1, v37
	v_cmp_eq_u32_e64 s[4:5], 1, v37
	v_or_b32_e32 v37, 0x43, v34
	v_cmp_ge_i32_e32 vcc, v37, v182
	v_writelane_b32 v251, s4, 56
	s_nop 0
	v_cndmask_b32_e64 v41, 0, 1, vcc
	v_writelane_b32 v251, s5, 57
	v_cmp_le_i32_e64 s[4:5], v37, v182
	s_nop 1
	v_cndmask_b32_e64 v37, 0, 1, s[4:5]
	v_cndmask_b32_e64 v37, v41, v37, s[6:7]
	v_and_b32_e32 v37, 1, v37
	v_cmp_eq_u32_e64 s[4:5], 1, v37
	v_or_b32_e32 v37, 0x44, v34
	v_cmp_ge_i32_e32 vcc, v37, v182
	v_writelane_b32 v251, s4, 58
	s_nop 0
	v_cndmask_b32_e64 v41, 0, 1, vcc
	v_writelane_b32 v251, s5, 59
	v_cmp_le_i32_e64 s[4:5], v37, v182
	s_nop 1
	v_cndmask_b32_e64 v37, 0, 1, s[4:5]
	v_cndmask_b32_e64 v37, v41, v37, s[6:7]
	v_and_b32_e32 v37, 1, v37
	v_cmp_eq_u32_e64 s[4:5], 1, v37
	v_or_b32_e32 v37, 0x45, v34
	v_cmp_ge_i32_e32 vcc, v37, v182
	v_writelane_b32 v251, s4, 60
	s_nop 0
	v_cndmask_b32_e64 v41, 0, 1, vcc
	v_writelane_b32 v251, s5, 61
	v_cmp_le_i32_e64 s[4:5], v37, v182
	s_nop 1
	v_cndmask_b32_e64 v37, 0, 1, s[4:5]
	v_cndmask_b32_e64 v37, v41, v37, s[6:7]
	v_and_b32_e32 v37, 1, v37
	v_cmp_eq_u32_e64 s[4:5], 1, v37
	v_or_b32_e32 v37, 0x46, v34
	v_cmp_ge_i32_e32 vcc, v37, v182
	v_writelane_b32 v251, s4, 62
	s_nop 0
	v_cndmask_b32_e64 v41, 0, 1, vcc
	v_writelane_b32 v251, s5, 63
	v_cmp_le_i32_e64 s[4:5], v37, v182
	s_nop 1
	v_cndmask_b32_e64 v37, 0, 1, s[4:5]
	v_cndmask_b32_e64 v37, v41, v37, s[6:7]
	v_and_b32_e32 v37, 1, v37
	v_cmp_eq_u32_e64 s[4:5], 1, v37
	v_or_b32_e32 v37, 0x47, v34
	v_cmp_ge_i32_e32 vcc, v37, v182
	v_writelane_b32 v250, s4, 0
	s_nop 0
	v_cndmask_b32_e64 v41, 0, 1, vcc
	v_writelane_b32 v250, s5, 1
	v_cmp_le_i32_e64 s[4:5], v37, v182
	s_nop 1
	v_cndmask_b32_e64 v37, 0, 1, s[4:5]
	v_cndmask_b32_e64 v37, v41, v37, s[6:7]
	v_and_b32_e32 v37, 1, v37
	v_cmp_eq_u32_e64 s[4:5], 1, v37
	v_or_b32_e32 v37, 0x50, v34
	v_cmp_ge_i32_e32 vcc, v37, v182
	v_writelane_b32 v250, s4, 2
	s_nop 0
	v_cndmask_b32_e64 v41, 0, 1, vcc
	v_writelane_b32 v250, s5, 3
	v_cmp_le_i32_e64 s[4:5], v37, v182
	s_nop 1
	v_cndmask_b32_e64 v37, 0, 1, s[4:5]
	v_cndmask_b32_e64 v37, v41, v37, s[6:7]
	v_and_b32_e32 v37, 1, v37
	v_cmp_eq_u32_e64 s[4:5], 1, v37
	v_or_b32_e32 v37, 0x51, v34
	v_cmp_ge_i32_e32 vcc, v37, v182
	v_writelane_b32 v250, s4, 4
	s_nop 0
	v_cndmask_b32_e64 v41, 0, 1, vcc
	v_writelane_b32 v250, s5, 5
	v_cmp_le_i32_e64 s[4:5], v37, v182
	s_nop 1
	v_cndmask_b32_e64 v37, 0, 1, s[4:5]
	v_cndmask_b32_e64 v37, v41, v37, s[6:7]
	v_and_b32_e32 v37, 1, v37
	v_cmp_eq_u32_e64 s[4:5], 1, v37
	v_or_b32_e32 v37, 0x52, v34
	v_cmp_ge_i32_e32 vcc, v37, v182
	v_writelane_b32 v250, s4, 6
	s_nop 0
	v_cndmask_b32_e64 v41, 0, 1, vcc
	v_writelane_b32 v250, s5, 7
	v_cmp_le_i32_e64 s[4:5], v37, v182
	s_nop 1
	v_cndmask_b32_e64 v37, 0, 1, s[4:5]
	v_cndmask_b32_e64 v37, v41, v37, s[6:7]
	v_and_b32_e32 v37, 1, v37
	v_cmp_eq_u32_e64 s[4:5], 1, v37
	v_or_b32_e32 v37, 0x53, v34
	v_cmp_ge_i32_e32 vcc, v37, v182
	v_writelane_b32 v250, s4, 8
	s_nop 0
	v_cndmask_b32_e64 v41, 0, 1, vcc
	v_writelane_b32 v250, s5, 9
	v_cmp_le_i32_e64 s[4:5], v37, v182
	s_nop 1
	v_cndmask_b32_e64 v37, 0, 1, s[4:5]
	v_cndmask_b32_e64 v37, v41, v37, s[6:7]
	v_and_b32_e32 v37, 1, v37
	v_cmp_eq_u32_e64 s[4:5], 1, v37
	v_or_b32_e32 v37, 0x54, v34
	v_cmp_ge_i32_e32 vcc, v37, v182
	v_cmp_le_i32_e64 s[10:11], v37, v182
	v_writelane_b32 v250, s4, 10
	v_cndmask_b32_e64 v41, 0, 1, vcc
	v_cndmask_b32_e64 v37, 0, 1, s[10:11]
	v_cndmask_b32_e64 v37, v41, v37, s[6:7]
	v_and_b32_e32 v37, 1, v37
	v_cmp_eq_u32_e64 s[66:67], 1, v37
	v_or_b32_e32 v37, 0x55, v34
	v_cmp_ge_i32_e32 vcc, v37, v182
	v_cmp_le_i32_e64 s[10:11], v37, v182
	v_writelane_b32 v250, s5, 11
	v_cndmask_b32_e64 v41, 0, 1, vcc
	v_cndmask_b32_e64 v37, 0, 1, s[10:11]
	v_cndmask_b32_e64 v37, v41, v37, s[6:7]
	v_and_b32_e32 v37, 1, v37
	v_cmp_eq_u32_e64 s[10:11], 1, v37
	v_or_b32_e32 v37, 0x56, v34
	v_cmp_ge_i32_e32 vcc, v37, v182
	v_cmp_le_i32_e64 s[12:13], v37, v182
	s_movk_i32 s4, 0x110
	v_cndmask_b32_e64 v41, 0, 1, vcc
	v_cndmask_b32_e64 v37, 0, 1, s[12:13]
	v_cndmask_b32_e64 v37, v41, v37, s[6:7]
	v_and_b32_e32 v37, 1, v37
	v_cmp_eq_u32_e64 s[12:13], 1, v37
	v_or_b32_e32 v37, 0x57, v34
	v_cmp_ge_i32_e32 vcc, v37, v182
	v_cmp_le_i32_e64 s[14:15], v37, v182
	s_nop 0
	v_cndmask_b32_e64 v41, 0, 1, vcc
	v_cndmask_b32_e64 v37, 0, 1, s[14:15]
	v_cndmask_b32_e64 v37, v41, v37, s[6:7]
	v_and_b32_e32 v37, 1, v37
	v_cmp_eq_u32_e64 s[14:15], 1, v37
	v_or_b32_e32 v37, 0x60, v34
	v_cmp_ge_i32_e32 vcc, v37, v182
	v_cmp_le_i32_e64 s[16:17], v37, v182
	s_nop 0
	v_cndmask_b32_e64 v41, 0, 1, vcc
	v_cndmask_b32_e64 v37, 0, 1, s[16:17]
	v_cndmask_b32_e64 v37, v41, v37, s[6:7]
	v_and_b32_e32 v37, 1, v37
	v_cmp_eq_u32_e64 s[16:17], 1, v37
	v_or_b32_e32 v37, 0x61, v34
	v_cmp_ge_i32_e32 vcc, v37, v182
	v_cmp_le_i32_e64 s[18:19], v37, v182
	s_nop 0
	v_cndmask_b32_e64 v41, 0, 1, vcc
	v_cndmask_b32_e64 v37, 0, 1, s[18:19]
	v_cndmask_b32_e64 v37, v41, v37, s[6:7]
	v_and_b32_e32 v37, 1, v37
	v_cmp_eq_u32_e64 s[18:19], 1, v37
	v_or_b32_e32 v37, 0x62, v34
	v_cmp_ge_i32_e32 vcc, v37, v182
	v_cmp_le_i32_e64 s[20:21], v37, v182
	s_nop 0
	v_cndmask_b32_e64 v41, 0, 1, vcc
	v_cndmask_b32_e64 v37, 0, 1, s[20:21]
	v_cndmask_b32_e64 v37, v41, v37, s[6:7]
	v_and_b32_e32 v37, 1, v37
	v_cmp_eq_u32_e64 s[20:21], 1, v37
	v_or_b32_e32 v37, 0x63, v34
	v_cmp_ge_i32_e32 vcc, v37, v182
	v_cmp_le_i32_e64 s[22:23], v37, v182
	s_nop 0
	v_cndmask_b32_e64 v41, 0, 1, vcc
	v_cndmask_b32_e64 v37, 0, 1, s[22:23]
	v_cndmask_b32_e64 v37, v41, v37, s[6:7]
	v_and_b32_e32 v37, 1, v37
	v_cmp_eq_u32_e64 s[22:23], 1, v37
	v_or_b32_e32 v37, 0x64, v34
	v_cmp_ge_i32_e32 vcc, v37, v182
	v_cmp_le_i32_e64 s[24:25], v37, v182
	s_nop 0
	v_cndmask_b32_e64 v41, 0, 1, vcc
	v_cndmask_b32_e64 v37, 0, 1, s[24:25]
	v_cndmask_b32_e64 v37, v41, v37, s[6:7]
	v_and_b32_e32 v37, 1, v37
	v_cmp_eq_u32_e64 s[24:25], 1, v37
	v_or_b32_e32 v37, 0x65, v34
	v_cmp_ge_i32_e32 vcc, v37, v182
	v_cmp_le_i32_e64 s[26:27], v37, v182
	s_nop 0
	v_cndmask_b32_e64 v41, 0, 1, vcc
	v_cndmask_b32_e64 v37, 0, 1, s[26:27]
	v_cndmask_b32_e64 v37, v41, v37, s[6:7]
	v_and_b32_e32 v37, 1, v37
	v_cmp_eq_u32_e64 s[26:27], 1, v37
	v_or_b32_e32 v37, 0x66, v34
	v_cmp_ge_i32_e32 vcc, v37, v182
	v_cmp_le_i32_e64 s[28:29], v37, v182
	s_nop 0
	v_cndmask_b32_e64 v41, 0, 1, vcc
	v_cndmask_b32_e64 v37, 0, 1, s[28:29]
	v_cndmask_b32_e64 v37, v41, v37, s[6:7]
	v_and_b32_e32 v37, 1, v37
	v_cmp_eq_u32_e64 s[28:29], 1, v37
	v_or_b32_e32 v37, 0x67, v34
	v_cmp_ge_i32_e32 vcc, v37, v182
	v_cmp_le_i32_e64 s[30:31], v37, v182
	s_nop 0
	v_cndmask_b32_e64 v41, 0, 1, vcc
	v_cndmask_b32_e64 v37, 0, 1, s[30:31]
	v_cndmask_b32_e64 v37, v41, v37, s[6:7]
	v_and_b32_e32 v37, 1, v37
	v_cmp_eq_u32_e64 s[30:31], 1, v37
	v_or_b32_e32 v37, 0x70, v34
	v_cmp_ge_i32_e32 vcc, v37, v182
	v_cmp_le_i32_e64 s[34:35], v37, v182
	s_nop 0
	v_cndmask_b32_e64 v41, 0, 1, vcc
	v_cndmask_b32_e64 v37, 0, 1, s[34:35]
	v_cndmask_b32_e64 v37, v41, v37, s[6:7]
	v_and_b32_e32 v37, 1, v37
	v_cmp_eq_u32_e64 s[34:35], 1, v37
	v_or_b32_e32 v37, 0x71, v34
	v_cmp_ge_i32_e32 vcc, v37, v182
	v_cmp_le_i32_e64 s[36:37], v37, v182
	s_nop 0
	v_cndmask_b32_e64 v41, 0, 1, vcc
	v_cndmask_b32_e64 v37, 0, 1, s[36:37]
	v_cndmask_b32_e64 v37, v41, v37, s[6:7]
	v_and_b32_e32 v37, 1, v37
	v_cmp_eq_u32_e64 s[36:37], 1, v37
	v_or_b32_e32 v37, 0x72, v34
	v_cmp_ge_i32_e32 vcc, v37, v182
	v_cmp_le_i32_e64 s[38:39], v37, v182
	s_nop 0
	v_cndmask_b32_e64 v41, 0, 1, vcc
	v_cndmask_b32_e64 v37, 0, 1, s[38:39]
	v_cndmask_b32_e64 v37, v41, v37, s[6:7]
	v_and_b32_e32 v37, 1, v37
	v_cmp_eq_u32_e64 s[38:39], 1, v37
	v_or_b32_e32 v37, 0x73, v34
	v_cmp_ge_i32_e32 vcc, v37, v182
	v_cmp_le_i32_e64 s[40:41], v37, v182
	s_nop 0
	v_cndmask_b32_e64 v41, 0, 1, vcc
	v_cndmask_b32_e64 v37, 0, 1, s[40:41]
	v_cndmask_b32_e64 v37, v41, v37, s[6:7]
	v_and_b32_e32 v37, 1, v37
	v_cmp_eq_u32_e64 s[40:41], 1, v37
	v_or_b32_e32 v37, 0x74, v34
	v_cmp_ge_i32_e32 vcc, v37, v182
	v_cmp_le_i32_e64 s[42:43], v37, v182
	s_nop 0
	v_cndmask_b32_e64 v41, 0, 1, vcc
	v_cndmask_b32_e64 v37, 0, 1, s[42:43]
	v_cndmask_b32_e64 v37, v41, v37, s[6:7]
	v_and_b32_e32 v37, 1, v37
	v_cmp_eq_u32_e64 s[42:43], 1, v37
	v_or_b32_e32 v37, 0x75, v34
	v_cmp_ge_i32_e32 vcc, v37, v182
	v_cmp_le_i32_e64 s[44:45], v37, v182
	s_nop 0
	v_cndmask_b32_e64 v41, 0, 1, vcc
	v_cndmask_b32_e64 v37, 0, 1, s[44:45]
	v_cndmask_b32_e64 v37, v41, v37, s[6:7]
	v_and_b32_e32 v37, 1, v37
	v_cmp_eq_u32_e64 s[44:45], 1, v37
	v_or_b32_e32 v37, 0x76, v34
	v_cmp_ge_i32_e32 vcc, v37, v182
	v_cmp_le_i32_e64 s[46:47], v37, v182
	s_nop 0
	v_cndmask_b32_e64 v41, 0, 1, vcc
	v_cndmask_b32_e64 v37, 0, 1, s[46:47]
	v_cndmask_b32_e64 v37, v41, v37, s[6:7]
	v_and_b32_e32 v37, 1, v37
	v_cmp_eq_u32_e64 s[46:47], 1, v37
	v_or_b32_e32 v37, 0x77, v34
	v_cmp_ge_i32_e32 vcc, v37, v182
	v_cmp_le_i32_e64 s[48:49], v37, v182
	s_nop 0
	v_cndmask_b32_e64 v41, 0, 1, vcc
	v_cndmask_b32_e64 v37, 0, 1, s[48:49]
	v_cndmask_b32_e64 v37, v41, v37, s[6:7]
	v_and_b32_e32 v37, 1, v37
	v_cmp_eq_u32_e64 s[48:49], 1, v37
	v_mov_b32_e32 v37, v129
	v_lshl_add_u64 v[36:37], s[50:51], 0, v[36:37]
	s_mov_b64 s[50:51], 0x26a0000
	v_lshl_add_u64 v[200:201], v[36:37], 0, s[50:51]
	v_lshlrev_b32_e32 v36, 1, v203
	v_mad_u32_u24 v227, v40, s4, v36
	v_add_u32_e32 v243, 0x2200, v227
	s_branch .LBB0_1271

.LBB0_1674:
	v_add_u32_e32 v32, s24, v147
	v_ashrrev_i32_e32 v33, 31, v32
	v_lshlrev_b64 v[34:35], 10, v[32:33]
	v_lshlrev_b64 v[32:33], 6, v[32:33]
	v_lshl_add_u64 v[32:33], v[118:119], 0, v[32:33]
	v_lshl_add_u64 v[34:35], v[120:121], 0, v[34:35]
	v_lshl_add_u64 v[32:33], v[32:33], 0, s[14:15]
	v_cndmask_b32_e32 v33, v33, v35, vcc
	v_cndmask_b32_e32 v32, v32, v34, vcc
	global_load_dwordx4 v[88:91], v[32:33], off
	v_add_u32_e32 v32, s24, v146
	v_ashrrev_i32_e32 v33, 31, v32
	v_lshlrev_b64 v[34:35], 10, v[32:33]
	v_lshlrev_b64 v[32:33], 6, v[32:33]
	v_lshl_add_u64 v[32:33], v[122:123], 0, v[32:33]
	v_lshl_add_u64 v[34:35], v[124:125], 0, v[34:35]
	v_lshl_add_u64 v[32:33], v[32:33], 0, s[14:15]
	v_cndmask_b32_e64 v33, v33, v35, s[6:7]
	v_cndmask_b32_e64 v32, v32, v34, s[6:7]
	global_load_dwordx4 v[92:95], v[32:33], off
	v_add_u32_e32 v32, s24, v145
	v_ashrrev_i32_e32 v33, 31, v32
	v_lshlrev_b64 v[34:35], 10, v[32:33]
	v_lshlrev_b64 v[32:33], 6, v[32:33]
	v_lshl_add_u64 v[32:33], v[126:127], 0, v[32:33]
	s_and_b32 s9, s2, 1
	v_lshl_add_u64 v[34:35], v[130:131], 0, v[34:35]
	v_lshl_add_u64 v[32:33], v[32:33], 0, s[14:15]
	v_cndmask_b32_e64 v33, v33, v35, s[4:5]
	v_cndmask_b32_e64 v32, v32, v34, s[4:5]
	s_mul_i32 s12, s9, 0x3400
	global_load_dwordx4 v[96:99], v[32:33], off
	global_load_dwordx4 v[104:107], v[134:135], off
	global_load_dwordx4 v[100:103], v[132:133], off
	v_or_b32_e32 v32, s12, v143
	v_mov_b32_e32 v153, v115
	v_add_u32_e32 v115, v32, v117
	ds_read_b128 v[164:167], v115
	ds_read_b128 v[168:171], v115 offset:32
	ds_read_b128 v[172:175], v115 offset:64
	ds_read_b128 v[180:183], v115 offset:96
	ds_read_b128 v[184:187], v115 offset:128
	ds_read_b128 v[188:191], v115 offset:160
	ds_read_b128 v[192:195], v115 offset:6656
	ds_read_b128 v[196:199], v115 offset:6688
	ds_read_b128 v[228:231], v115 offset:6720
	ds_read_b128 v[232:235], v115 offset:6752
	ds_read_b128 v[236:239], v115 offset:6784
	ds_read_b128 v[240:243], v115 offset:6816
	v_mov_b32_e32 v152, v148
	s_mul_i32 s12, s9, 0x2200
	s_xor_b32 s9, s9, 1
	s_add_i32 s2, s2, 1
	s_add_i32 s24, s24, 64
	v_add_u32_e32 v200, s12, v144
	v_lshl_add_u64 v[132:133], v[132:133], 0, s[68:69]
	v_lshl_add_u64 v[134:135], v[134:135], 0, s[68:69]
	v_add_u32_e32 v200, 0x6800, v200
	v_add_u32_e32 v201, 0x1000, v200
	s_waitcnt lgkmcnt(11)
	v_mfma_f32_32x32x16_bf16 v[48:63], v[164:167], v[64:67], 0
	s_waitcnt lgkmcnt(10)
	v_mfma_f32_32x32x16_bf16 v[48:63], v[168:171], v[68:71], v[48:63]
	s_waitcnt lgkmcnt(9)
	v_mfma_f32_32x32x16_bf16 v[48:63], v[172:175], v[76:79], v[48:63]
	s_waitcnt lgkmcnt(8)
	v_mfma_f32_32x32x16_bf16 v[48:63], v[180:183], v[72:75], v[48:63]
	s_waitcnt lgkmcnt(7)
	v_mfma_f32_32x32x16_bf16 v[48:63], v[184:187], v[80:83], v[48:63]
	s_waitcnt lgkmcnt(6)
	v_mfma_f32_32x32x16_bf16 v[48:63], v[188:191], v[84:87], v[48:63]
	s_waitcnt lgkmcnt(5)
	v_mfma_f32_32x32x16_bf16 v[32:47], v[192:195], v[64:67], 0
	s_waitcnt lgkmcnt(4)
	v_mfma_f32_32x32x16_bf16 v[32:47], v[196:199], v[68:71], v[32:47]
	s_waitcnt lgkmcnt(3)
	v_mfma_f32_32x32x16_bf16 v[32:47], v[228:231], v[76:79], v[32:47]
	s_waitcnt lgkmcnt(2)
	v_mfma_f32_32x32x16_bf16 v[32:47], v[232:235], v[72:75], v[32:47]
	s_waitcnt lgkmcnt(1)
	v_mfma_f32_32x32x16_bf16 v[32:47], v[236:239], v[80:83], v[32:47]
	s_waitcnt lgkmcnt(0)
	v_mfma_f32_32x32x16_bf16 v[32:47], v[240:243], v[84:87], v[32:47]
	ds_read2_b64 v[164:167], v200 offset1:2
	ds_read2_b64 v[168:171], v201 offset0:32 offset1:34
	ds_read2_b64 v[172:175], v201 offset0:36 offset1:38
	ds_read2_b64 v[180:183], v200 offset0:4 offset1:6
	ds_read2_b64 v[184:187], v200 offset0:8 offset1:10
	ds_read2_b64 v[188:191], v201 offset0:40 offset1:42
	ds_read2_b64 v[192:195], v200 offset0:12 offset1:14
	ds_read2_b64 v[196:199], v201 offset0:44 offset1:46
	v_max_f32_e32 v115, v49, v49
	v_max_f32_e32 v148, v48, v48
	v_max_f32_e32 v115, v148, v115
	v_max3_f32 v115, v115, v50, v51
	v_max3_f32 v115, v115, v52, v53
	v_max3_f32 v115, v115, v54, v55
	v_max3_f32 v115, v115, v56, v57
	v_max3_f32 v115, v115, v58, v59
	v_max3_f32 v115, v115, v60, v61
	v_max3_f32 v115, v115, v62, v63
	s_nop 2
	v_max3_f32 v115, v115, v32, v33
	v_max3_f32 v115, v115, v34, v35
	v_max3_f32 v115, v115, v36, v37
	v_max3_f32 v115, v115, v38, v39
	v_max3_f32 v115, v115, v40, v41
	v_max3_f32 v115, v115, v42, v43
	v_max3_f32 v115, v115, v44, v45
	v_max3_f32 v115, v115, v46, v47
	ds_bpermute_b32 v148, v111, v115
	s_waitcnt lgkmcnt(0)
	v_max3_f32 v148, v152, v115, v148
	v_sub_f32_e32 v48, v48, v148
	v_exp_f32_e32 v48, v48
	v_sub_f32_e32 v49, v49, v148
	v_exp_f32_e32 v49, v49
	v_sub_f32_e32 v50, v50, v148
	v_exp_f32_e32 v50, v50
	v_sub_f32_e32 v51, v51, v148
	v_sub_f32_e32 v115, v152, v148
	v_exp_f32_e32 v51, v51
	v_sub_f32_e32 v52, v52, v148
	v_exp_f32_e32 v150, v115
	v_add_f32_e32 v115, 0, v48
	v_exp_f32_e32 v52, v52
	v_sub_f32_e32 v53, v53, v148
	v_sub_f32_e32 v32, v32, v148
	v_add_f32_e32 v115, v49, v115
	v_exp_f32_e32 v53, v53
	v_sub_f32_e32 v54, v54, v148
	v_exp_f32_e32 v149, v32
	v_sub_f32_e32 v32, v33, v148
	v_add_f32_e32 v115, v50, v115
	v_exp_f32_e32 v54, v54
	v_sub_f32_e32 v55, v55, v148
	v_exp_f32_e32 v151, v32
	v_sub_f32_e32 v32, v34, v148
	v_add_f32_e32 v115, v51, v115
	v_exp_f32_e32 v55, v55
	v_sub_f32_e32 v56, v56, v148
	v_exp_f32_e32 v152, v32
	v_sub_f32_e32 v32, v35, v148
	v_add_f32_e32 v115, v52, v115
	v_exp_f32_e32 v56, v56
	v_sub_f32_e32 v57, v57, v148
	v_exp_f32_e32 v154, v32
	v_sub_f32_e32 v32, v36, v148
	v_add_f32_e32 v115, v53, v115
	v_exp_f32_e32 v57, v57
	v_sub_f32_e32 v58, v58, v148
	v_exp_f32_e32 v155, v32
	v_sub_f32_e32 v32, v37, v148
	v_add_f32_e32 v115, v54, v115
	v_exp_f32_e32 v58, v58
	v_sub_f32_e32 v59, v59, v148
	v_exp_f32_e32 v156, v32
	v_sub_f32_e32 v32, v38, v148
	v_add_f32_e32 v115, v55, v115
	v_exp_f32_e32 v59, v59
	v_sub_f32_e32 v60, v60, v148
	v_exp_f32_e32 v157, v32
	v_sub_f32_e32 v32, v39, v148
	v_add_f32_e32 v115, v56, v115
	v_exp_f32_e32 v60, v60
	v_sub_f32_e32 v61, v61, v148
	v_exp_f32_e32 v158, v32
	v_sub_f32_e32 v32, v40, v148
	v_add_f32_e32 v115, v57, v115
	v_exp_f32_e32 v61, v61
	v_sub_f32_e32 v62, v62, v148
	v_exp_f32_e32 v159, v32
	v_sub_f32_e32 v32, v41, v148
	v_add_f32_e32 v115, v58, v115
	v_exp_f32_e32 v62, v62
	v_sub_f32_e32 v63, v63, v148
	v_exp_f32_e32 v160, v32
	v_sub_f32_e32 v32, v42, v148
	v_add_f32_e32 v115, v59, v115
	v_exp_f32_e32 v63, v63
	v_exp_f32_e32 v161, v32
	v_sub_f32_e32 v32, v43, v148
	v_add_f32_e32 v115, v60, v115
	v_exp_f32_e32 v162, v32
	v_sub_f32_e32 v32, v44, v148
	v_add_f32_e32 v115, v61, v115
	v_exp_f32_e32 v44, v32
	v_sub_f32_e32 v32, v45, v148
	v_add_f32_e32 v115, v62, v115
	v_exp_f32_e32 v45, v32
	v_sub_f32_e32 v32, v46, v148
	v_add_f32_e32 v115, v63, v115
	v_exp_f32_e32 v46, v32
	v_sub_f32_e32 v32, v47, v148
	v_exp_f32_e32 v47, v32
	v_add_f32_e32 v32, v149, v115
	v_add_f32_e32 v32, v151, v32
	v_add_f32_e32 v32, v152, v32
	v_add_f32_e32 v32, v154, v32
	v_add_f32_e32 v32, v155, v32
	v_add_f32_e32 v32, v156, v32
	v_add_f32_e32 v32, v157, v32
	v_add_f32_e32 v32, v158, v32
	v_add_f32_e32 v32, v159, v32
	v_add_f32_e32 v32, v160, v32
	v_add_f32_e32 v32, v161, v32
	v_add_f32_e32 v32, v162, v32
	v_add_f32_e32 v32, v44, v32
	v_add_f32_e32 v32, v45, v32
	v_add_f32_e32 v32, v46, v32
	v_add_f32_e32 v115, v47, v32
	v_cvt_pk_bf16_f32 v32, v48, v49
	v_pk_mul_f32 v[30:31], v[30:31], v[150:151] op_sel_hi:[1,0]
	v_pk_mul_f32 v[28:29], v[28:29], v[150:151] op_sel_hi:[1,0]
	v_pk_mul_f32 v[26:27], v[26:27], v[150:151] op_sel_hi:[1,0]
	v_pk_mul_f32 v[24:25], v[24:25], v[150:151] op_sel_hi:[1,0]
	v_pk_mul_f32 v[22:23], v[22:23], v[150:151] op_sel_hi:[1,0]
	v_pk_mul_f32 v[20:21], v[20:21], v[150:151] op_sel_hi:[1,0]
	v_pk_mul_f32 v[18:19], v[18:19], v[150:151] op_sel_hi:[1,0]
	v_pk_mul_f32 v[16:17], v[16:17], v[150:151] op_sel_hi:[1,0]
	v_cvt_pk_bf16_f32 v33, v50, v51
	v_cvt_pk_bf16_f32 v34, v52, v53
	v_cvt_pk_bf16_f32 v35, v54, v55
	v_pk_mul_f32 v[14:15], v[14:15], v[150:151] op_sel_hi:[1,0]
	v_mul_f32_e64 v12, v12, v150
	v_mul_f32_e64 v13, v13, v150
	v_mul_f32_e64 v10, v10, v150
	v_mul_f32_e64 v11, v11, v150
	v_pk_mul_f32 v[8:9], v[8:9], v[150:151] op_sel_hi:[1,0]
	v_pk_mul_f32 v[6:7], v[6:7], v[150:151] op_sel_hi:[1,0]
	v_pk_mul_f32 v[4:5], v[4:5], v[150:151] op_sel_hi:[1,0]
	v_pk_mul_f32 v[2:3], v[2:3], v[150:151] op_sel_hi:[1,0]
	v_pk_mul_f32 v[0:1], v[0:1], v[150:151] op_sel_hi:[1,0]
	s_mul_i32 s12, s9, 0x3400
	s_mulk_i32 s9, 0xee00
	s_waitcnt lgkmcnt(0)
	v_mfma_f32_32x32x16_bf16 v[16:31], v[164:167], v[32:35], v[16:31]
	v_mfma_f32_32x32x16_bf16 v[0:15], v[168:171], v[32:35], v[0:15]
	v_cvt_pk_bf16_f32 v32, v56, v57
	v_cvt_pk_bf16_f32 v33, v58, v59
	v_cvt_pk_bf16_f32 v34, v60, v61
	v_cvt_pk_bf16_f32 v35, v62, v63
	v_fmac_f32_e32 v115, v153, v150
	s_nop 0
	v_mfma_f32_32x32x16_bf16 v[0:15], v[172:175], v[32:35], v[0:15]
	v_mfma_f32_32x32x16_bf16 v[16:31], v[180:183], v[32:35], v[16:31]
	v_cvt_pk_bf16_f32 v32, v149, v151
	v_cvt_pk_bf16_f32 v33, v152, v154
	v_cvt_pk_bf16_f32 v34, v155, v156
	v_cvt_pk_bf16_f32 v35, v157, v158
	s_nop 1
	v_mfma_f32_32x32x16_bf16 v[16:31], v[184:187], v[32:35], v[16:31]
	v_mfma_f32_32x32x16_bf16 v[0:15], v[188:191], v[32:35], v[0:15]
	v_cvt_pk_bf16_f32 v32, v159, v160
	v_cvt_pk_bf16_f32 v33, v161, v162
	v_cvt_pk_bf16_f32 v34, v44, v45
	v_cvt_pk_bf16_f32 v35, v46, v47
	s_nop 1
	v_mfma_f32_32x32x16_bf16 v[16:31], v[192:195], v[32:35], v[16:31]
	v_mfma_f32_32x32x16_bf16 v[0:15], v[196:199], v[32:35], v[0:15]
	v_lshlrev_b32_e32 v32, 1, v137
	v_lshlrev_b32_e32 v33, 1, v114
	v_add3_u32 v32, s12, v32, v33
	s_waitcnt vmcnt(4)
	ds_write_b128 v32, v[88:91]
	v_lshlrev_b32_e32 v32, 1, v138
	v_lshlrev_b32_e32 v33, 1, v116
	v_add3_u32 v32, s12, v32, v33
	s_waitcnt vmcnt(3)
	ds_write_b128 v32, v[92:95]
	v_lshlrev_b32_e32 v32, 1, v139
	v_add3_u32 v32, s12, v32, v140
	s_add_i32 s12, s12, s9
	s_waitcnt vmcnt(2)
	ds_write_b128 v32, v[96:99]
	v_lshl_add_u32 v32, v141, 1, s12
	v_add3_u32 v32, v32, v128, s42
	s_waitcnt vmcnt(1)
	ds_write2_b64 v32, v[104:105], v[106:107] offset1:1
	v_lshl_add_u32 v32, v142, 1, s12
	v_add3_u32 v32, v32, v128, s42
	s_cmp_lg_u32 s8, s2
	s_waitcnt vmcnt(0)
	ds_write2_b64 v32, v[100:101], v[102:103] offset1:1
	s_waitcnt lgkmcnt(0)
	s_barrier
	s_cbranch_scc1 .LBB0_1674
	s_and_b32 s2, s8, 1
	s_mul_i32 s4, s2, 0x3400
	v_or_b32_e32 v32, s4, v143
	v_add_u32_e32 v88, v32, v117
	ds_read_b128 v[32:35], v88
	ds_read_b128 v[36:39], v88 offset:32
	s_mulk_i32 s2, 0x2200
	s_waitcnt lgkmcnt(1)
	v_mfma_f32_32x32x16_bf16 v[48:63], v[32:35], v[64:67], 0
	ds_read_b128 v[32:35], v88 offset:64
	s_waitcnt lgkmcnt(1)
	v_mfma_f32_32x32x16_bf16 v[48:63], v[36:39], v[68:71], v[48:63]
	s_waitcnt lgkmcnt(0)
	v_mfma_f32_32x32x16_bf16 v[48:63], v[32:35], v[76:79], v[48:63]
	ds_read_b128 v[32:35], v88 offset:96
	s_waitcnt lgkmcnt(0)
	v_mfma_f32_32x32x16_bf16 v[48:63], v[32:35], v[72:75], v[48:63]
	ds_read_b128 v[32:35], v88 offset:128
	s_waitcnt lgkmcnt(0)
	v_mfma_f32_32x32x16_bf16 v[48:63], v[32:35], v[80:83], v[48:63]
	ds_read_b128 v[32:35], v88 offset:160
	s_waitcnt lgkmcnt(0)
	v_mfma_f32_32x32x16_bf16 v[48:63], v[32:35], v[84:87], v[48:63]
	ds_read_b128 v[32:35], v88 offset:6656
	s_waitcnt lgkmcnt(0)
	v_mfma_f32_32x32x16_bf16 v[32:47], v[32:35], v[64:67], 0
	ds_read_b128 v[64:67], v88 offset:6688
	s_waitcnt lgkmcnt(0)
	v_mfma_f32_32x32x16_bf16 v[32:47], v[64:67], v[68:71], v[32:47]
	ds_read_b128 v[64:67], v88 offset:6720
	s_waitcnt lgkmcnt(0)
	v_mfma_f32_32x32x16_bf16 v[32:47], v[64:67], v[76:79], v[32:47]
	ds_read_b128 v[64:67], v88 offset:6752
	s_waitcnt lgkmcnt(0)
	v_mfma_f32_32x32x16_bf16 v[32:47], v[64:67], v[72:75], v[32:47]
	ds_read_b128 v[64:67], v88 offset:6784
	s_waitcnt lgkmcnt(0)
	v_mfma_f32_32x32x16_bf16 v[32:47], v[64:67], v[80:83], v[32:47]
	ds_read_b128 v[64:67], v88 offset:6816
	s_waitcnt lgkmcnt(0)
	v_mfma_f32_32x32x16_bf16 v[32:47], v[64:67], v[84:87], v[32:47]
	v_max_f32_e32 v64, v49, v49
	v_max_f32_e32 v65, v48, v48
	v_max_f32_e32 v64, v65, v64
	v_max3_f32 v64, v64, v50, v51
	v_max3_f32 v64, v64, v52, v53
	v_max3_f32 v64, v64, v54, v55
	v_max3_f32 v64, v64, v56, v57
	v_max3_f32 v64, v64, v58, v59
	v_max3_f32 v64, v64, v60, v61
	v_max3_f32 v64, v64, v62, v63
	s_nop 1
	v_max3_f32 v64, v64, v32, v33
	v_max3_f32 v64, v64, v34, v35
	v_max3_f32 v64, v64, v36, v37
	v_max3_f32 v64, v64, v38, v39
	v_max3_f32 v64, v64, v40, v41
	v_max3_f32 v64, v64, v42, v43
	v_max3_f32 v64, v64, v44, v45
	v_max3_f32 v64, v64, v46, v47
	ds_bpermute_b32 v65, v111, v64
	s_waitcnt lgkmcnt(0)
	v_max3_f32 v65, v148, v64, v65
	v_sub_f32_e32 v48, v48, v65
	v_exp_f32_e32 v48, v48
	v_sub_f32_e32 v49, v49, v65
	v_exp_f32_e32 v49, v49
	v_sub_f32_e32 v50, v50, v65
	v_exp_f32_e32 v50, v50
	v_sub_f32_e32 v51, v51, v65
	v_exp_f32_e32 v51, v51
	v_sub_f32_e32 v52, v52, v65
	v_add_f32_e32 v66, 0, v48
	v_exp_f32_e32 v52, v52
	v_sub_f32_e32 v53, v53, v65
	v_sub_f32_e32 v32, v32, v65
	v_add_f32_e32 v66, v49, v66
	v_exp_f32_e32 v53, v53
	v_sub_f32_e32 v54, v54, v65
	v_exp_f32_e32 v67, v32
	v_sub_f32_e32 v32, v33, v65
	v_add_f32_e32 v66, v50, v66
	v_exp_f32_e32 v54, v54
	v_sub_f32_e32 v55, v55, v65
	v_exp_f32_e32 v68, v32
	v_sub_f32_e32 v32, v34, v65
	v_add_f32_e32 v66, v51, v66
	v_exp_f32_e32 v55, v55
	v_sub_f32_e32 v56, v56, v65
	v_exp_f32_e32 v69, v32
	v_sub_f32_e32 v32, v35, v65
	v_add_f32_e32 v66, v52, v66
	v_exp_f32_e32 v56, v56
	v_sub_f32_e32 v57, v57, v65
	v_exp_f32_e32 v70, v32
	v_sub_f32_e32 v32, v36, v65
	v_add_f32_e32 v66, v53, v66
	v_exp_f32_e32 v57, v57
	v_sub_f32_e32 v58, v58, v65
	v_exp_f32_e32 v71, v32
	v_sub_f32_e32 v32, v37, v65
	v_add_f32_e32 v66, v54, v66
	v_exp_f32_e32 v58, v58
	v_sub_f32_e32 v59, v59, v65
	v_exp_f32_e32 v72, v32
	v_sub_f32_e32 v32, v38, v65
	v_add_f32_e32 v66, v55, v66
	v_exp_f32_e32 v59, v59
	v_sub_f32_e32 v60, v60, v65
	v_exp_f32_e32 v73, v32
	v_sub_f32_e32 v32, v39, v65
	v_add_f32_e32 v66, v56, v66
	v_exp_f32_e32 v60, v60
	v_sub_f32_e32 v61, v61, v65
	v_exp_f32_e32 v74, v32
	v_sub_f32_e32 v32, v40, v65
	v_add_f32_e32 v66, v57, v66
	v_exp_f32_e32 v61, v61
	v_sub_f32_e32 v62, v62, v65
	v_exp_f32_e32 v75, v32
	v_sub_f32_e32 v32, v41, v65
	v_add_f32_e32 v66, v58, v66
	v_exp_f32_e32 v62, v62
	v_sub_f32_e32 v63, v63, v65
	v_exp_f32_e32 v76, v32
	v_sub_f32_e32 v32, v42, v65
	v_add_f32_e32 v66, v59, v66
	v_exp_f32_e32 v63, v63
	v_exp_f32_e32 v77, v32
	v_sub_f32_e32 v32, v43, v65
	v_add_f32_e32 v66, v60, v66
	v_exp_f32_e32 v78, v32
	v_sub_f32_e32 v32, v44, v65
	v_add_f32_e32 v66, v61, v66
	v_exp_f32_e32 v44, v32
	v_sub_f32_e32 v32, v45, v65
	v_add_f32_e32 v66, v62, v66
	v_exp_f32_e32 v45, v32
	v_sub_f32_e32 v32, v46, v65
	v_add_f32_e32 v66, v63, v66
	v_exp_f32_e32 v46, v32
	v_sub_f32_e32 v32, v47, v65
	v_exp_f32_e32 v47, v32
	v_add_f32_e32 v32, v67, v66
	v_add_f32_e32 v32, v68, v32
	v_add_f32_e32 v32, v69, v32
	v_add_f32_e32 v32, v70, v32
	v_add_f32_e32 v32, v71, v32
	v_add_f32_e32 v32, v72, v32
	v_add_f32_e32 v32, v73, v32
	v_add_f32_e32 v32, v74, v32
	v_add_f32_e32 v32, v75, v32
	v_add_f32_e32 v32, v76, v32
	v_sub_f32_e32 v64, v148, v65
	v_add_f32_e32 v32, v77, v32
	v_exp_f32_e32 v64, v64
	v_add_f32_e32 v32, v78, v32
	v_add_f32_e32 v32, v44, v32
	v_add_f32_e32 v32, v45, v32
	v_add_f32_e32 v32, v46, v32
	v_lshlrev_b32_e32 v36, 1, v113
	v_pk_mul_f32 v[30:31], v[30:31], v[64:65] op_sel_hi:[1,0]
	v_pk_mul_f32 v[28:29], v[28:29], v[64:65] op_sel_hi:[1,0]
	v_pk_mul_f32 v[26:27], v[26:27], v[64:65] op_sel_hi:[1,0]
	v_pk_mul_f32 v[24:25], v[24:25], v[64:65] op_sel_hi:[1,0]
	v_pk_mul_f32 v[22:23], v[22:23], v[64:65] op_sel_hi:[1,0]
	v_pk_mul_f32 v[20:21], v[20:21], v[64:65] op_sel_hi:[1,0]
	v_pk_mul_f32 v[18:19], v[18:19], v[64:65] op_sel_hi:[1,0]
	v_pk_mul_f32 v[16:17], v[16:17], v[64:65] op_sel_hi:[1,0]
	v_pk_mul_f32 v[14:15], v[14:15], v[64:65] op_sel_hi:[1,0]
	v_pk_mul_f32 v[12:13], v[12:13], v[64:65] op_sel_hi:[1,0]
	v_pk_mul_f32 v[10:11], v[10:11], v[64:65] op_sel_hi:[1,0]
	v_pk_mul_f32 v[8:9], v[8:9], v[64:65] op_sel_hi:[1,0]
	v_pk_mul_f32 v[6:7], v[6:7], v[64:65] op_sel_hi:[1,0]
	v_pk_mul_f32 v[4:5], v[4:5], v[64:65] op_sel_hi:[1,0]
	v_pk_mul_f32 v[2:3], v[2:3], v[64:65] op_sel_hi:[1,0]
	v_pk_mul_f32 v[0:1], v[0:1], v[64:65] op_sel_hi:[1,0]
	v_add_f32_e32 v65, v47, v32
	v_cvt_pk_bf16_f32 v32, v48, v49
	v_add3_u32 v48, v136, s2, v36
	v_add_u32_e32 v49, 0x6800, v48
	ds_read2_b64 v[36:39], v49 offset1:2
	ds_read2_b64 v[40:43], v49 offset0:4 offset1:6
	v_cvt_pk_bf16_f32 v33, v50, v51
	v_cvt_pk_bf16_f32 v34, v52, v53
	v_cvt_pk_bf16_f32 v35, v54, v55
	v_add_u32_e32 v48, 0x7800, v48
	v_fmac_f32_e32 v65, v115, v64
	s_waitcnt lgkmcnt(1)
	v_mfma_f32_32x32x16_bf16 v[16:31], v[36:39], v[32:35], v[16:31]
	ds_read2_b64 v[36:39], v48 offset0:32 offset1:34
	v_mov_b32_e32 v113, v129
	s_mov_b32 s2, 0x15f20000
	s_waitcnt lgkmcnt(0)
	v_mfma_f32_32x32x16_bf16 v[0:15], v[36:39], v[32:35], v[0:15]
	ds_read2_b64 v[36:39], v48 offset0:36 offset1:38
	v_cvt_pk_bf16_f32 v32, v56, v57
	v_cvt_pk_bf16_f32 v33, v58, v59
	v_cvt_pk_bf16_f32 v34, v60, v61
	v_cvt_pk_bf16_f32 v35, v62, v63
	s_waitcnt lgkmcnt(0)
	s_nop 0
	v_mfma_f32_32x32x16_bf16 v[0:15], v[36:39], v[32:35], v[0:15]
	ds_read2_b64 v[36:39], v49 offset0:8 offset1:10
	v_mfma_f32_32x32x16_bf16 v[16:31], v[40:43], v[32:35], v[16:31]
	v_cvt_pk_bf16_f32 v32, v67, v68
	v_cvt_pk_bf16_f32 v33, v69, v70
	v_cvt_pk_bf16_f32 v34, v71, v72
	v_cvt_pk_bf16_f32 v35, v73, v74
	s_waitcnt lgkmcnt(0)
	s_nop 0
	v_mfma_f32_32x32x16_bf16 v[16:31], v[36:39], v[32:35], v[16:31]
	ds_read2_b64 v[36:39], v48 offset0:40 offset1:42
	s_waitcnt lgkmcnt(0)
	v_mfma_f32_32x32x16_bf16 v[0:15], v[36:39], v[32:35], v[0:15]
	ds_read2_b64 v[36:39], v49 offset0:12 offset1:14
	v_cvt_pk_bf16_f32 v32, v75, v76
	v_cvt_pk_bf16_f32 v33, v77, v78
	v_cvt_pk_bf16_f32 v34, v44, v45
	v_cvt_pk_bf16_f32 v35, v46, v47
	s_waitcnt lgkmcnt(0)
	s_nop 0
	v_mfma_f32_32x32x16_bf16 v[16:31], v[36:39], v[32:35], v[16:31]
	ds_read2_b64 v[36:39], v48 offset0:44 offset1:46
	s_waitcnt lgkmcnt(0)
	s_barrier
	v_mfma_f32_32x32x16_bf16 v[0:15], v[36:39], v[32:35], v[0:15]
	ds_bpermute_b32 v32, v111, v65
	v_mov_b32_e32 v111, v129
	s_waitcnt lgkmcnt(0)
	v_add_f32_e32 v32, v65, v32
	v_div_scale_f32 v33, s[4:5], v32, v32, 1.0
	v_rcp_f32_e32 v34, v33
	s_mov_b64 s[4:5], 0x15f20000
	v_fma_f32 v35, -v33, v34, 1.0
	v_fmac_f32_e32 v34, v35, v34
	v_div_scale_f32 v35, vcc, 1.0, v32, 1.0
	v_mul_f32_e32 v36, v35, v34
	v_fma_f32 v37, -v33, v36, v35
	v_fmac_f32_e32 v36, v37, v34
	v_fma_f32 v33, -v33, v36, v35
	v_div_fmas_f32 v33, v33, v34, v36
	v_lshlrev_b64 v[34:35], 10, v[108:109]
	v_lshl_add_u64 v[34:35], s[10:11], 0, v[34:35]
	v_div_fixup_f32 v32, v33, v32, 1.0
	v_lshl_add_u64 v[34:35], v[34:35], 0, v[112:113]
	v_lshl_add_u64 v[34:35], v[34:35], 0, v[110:111]
	v_pk_mul_f32 v[16:17], v[16:17], v[32:33] op_sel_hi:[1,0]
	v_pk_mul_f32 v[18:19], v[18:19], v[32:33] op_sel_hi:[1,0]
	v_cvt_pk_bf16_f32 v16, v16, v17
	v_cvt_pk_bf16_f32 v17, v18, v19
	v_add_co_u32_e32 v18, vcc, s2, v34
	v_pk_mul_f32 v[0:1], v[0:1], v[32:33] op_sel_hi:[1,0]
	v_pk_mul_f32 v[2:3], v[2:3], v[32:33] op_sel_hi:[1,0]
	v_lshl_add_u64 v[36:37], v[34:35], 0, s[4:5]
	v_addc_co_u32_e32 v19, vcc, 0, v35, vcc
	v_cvt_pk_bf16_f32 v0, v0, v1
	v_cvt_pk_bf16_f32 v1, v2, v3
	global_store_dwordx2 v[18:19], v[16:17], off
	v_pk_mul_f32 v[16:17], v[20:21], v[32:33] op_sel_hi:[1,0]
	v_pk_mul_f32 v[18:19], v[22:23], v[32:33] op_sel_hi:[1,0]
	global_store_dwordx2 v[36:37], v[0:1], off offset:64
	v_pk_mul_f32 v[0:1], v[4:5], v[32:33] op_sel_hi:[1,0]
	v_pk_mul_f32 v[2:3], v[6:7], v[32:33] op_sel_hi:[1,0]
	v_cvt_pk_bf16_f32 v16, v16, v17
	v_cvt_pk_bf16_f32 v17, v18, v19
	v_cvt_pk_bf16_f32 v0, v0, v1
	v_cvt_pk_bf16_f32 v1, v2, v3
	global_store_dwordx2 v[36:37], v[16:17], off offset:16
	v_pk_mul_f32 v[16:17], v[24:25], v[32:33] op_sel_hi:[1,0]
	v_pk_mul_f32 v[18:19], v[26:27], v[32:33] op_sel_hi:[1,0]
	global_store_dwordx2 v[36:37], v[0:1], off offset:80
	v_pk_mul_f32 v[0:1], v[8:9], v[32:33] op_sel_hi:[1,0]
	v_pk_mul_f32 v[2:3], v[10:11], v[32:33] op_sel_hi:[1,0]
	v_cvt_pk_bf16_f32 v16, v16, v17
	v_cvt_pk_bf16_f32 v17, v18, v19
	v_cvt_pk_bf16_f32 v0, v0, v1
	v_cvt_pk_bf16_f32 v1, v2, v3
	global_store_dwordx2 v[36:37], v[16:17], off offset:32
	v_pk_mul_f32 v[16:17], v[28:29], v[32:33] op_sel_hi:[1,0]
	v_pk_mul_f32 v[18:19], v[30:31], v[32:33] op_sel_hi:[1,0]
	global_store_dwordx2 v[36:37], v[0:1], off offset:96
	v_pk_mul_f32 v[0:1], v[12:13], v[32:33] op_sel_hi:[1,0]
	v_pk_mul_f32 v[2:3], v[14:15], v[32:33] op_sel_hi:[1,0]
	v_cvt_pk_bf16_f32 v16, v16, v17
	v_cvt_pk_bf16_f32 v17, v18, v19
	v_cvt_pk_bf16_f32 v0, v0, v1
	v_cvt_pk_bf16_f32 v1, v2, v3
	global_store_dwordx2 v[36:37], v[16:17], off offset:48
	global_store_dwordx2 v[36:37], v[0:1], off offset:112
	s_cbranch_execnz .LBB0_924
	s_branch .LBB0_1267

.LBB0_1731:
	v_add_co_u32_e32 v16, vcc, 0x1000, v14
	s_nop 1
	s_nop 0
	v_addc_co_u32_e32 v17, vcc, 0, v15, vcc
	s_waitcnt lgkmcnt(0)
	global_load_dwordx4 v[0:3], v[16:17], off offset:1024
	global_load_dwordx4 v[4:7], v[14:15], off
	global_load_dwordx4 v[8:11], v[14:15], off offset:3072
	s_waitcnt vmcnt(2)
	v_lshlrev_b32_e32 v18, 16, v0
	v_and_b32_e32 v19, 0xffff0000, v0
	s_waitcnt vmcnt(0)
	v_lshlrev_b32_e32 v0, 16, v8
	v_lshlrev_b32_e32 v20, 16, v4
	v_and_b32_e32 v21, 0xffff0000, v4
	v_and_b32_e32 v4, 0xffff0000, v8
	v_mul_f32_e32 v8, 0xbfb8aa3b, v0
	v_exp_f32_e32 v22, v8
	v_mul_f32_e32 v8, 0xbfb8aa3b, v4
	v_exp_f32_e32 v23, v8
	v_pk_add_f32 v[18:19], v[18:19], v[20:21]
	v_pk_add_f32 v[20:21], v[22:23], 1.0 op_sel_hi:[1,0]
	s_nop 0
	s_nop 0
	v_rcp_f32_e32 v8, v21
	s_nop 0
	v_mul_f32_e32 v21, v4, v8
	s_nop 0
	v_rcp_f32_e32 v4, v20
	s_nop 0
	v_mul_f32_e32 v20, v0, v4
	v_pk_mul_f32 v[26:27], v[18:19], v[20:21]
	v_lshlrev_b32_e32 v0, 16, v1
	v_and_b32_e32 v1, 0xffff0000, v1
	v_lshlrev_b32_e32 v4, 16, v5
	v_and_b32_e32 v5, 0xffff0000, v5
	v_lshlrev_b32_e32 v20, 16, v9
	v_and_b32_e32 v21, 0xffff0000, v9
	v_mul_f32_e32 v8, 0xbfb8aa3b, v20
	v_pk_add_f32 v[0:1], v[0:1], v[4:5]
	v_mul_f32_e32 v4, 0xbfb8aa3b, v21
	v_exp_f32_e32 v8, v8
	v_exp_f32_e32 v9, v4
	v_pk_mul_f32 v[18:19], v[26:27], v[26:27]
	v_pk_add_f32 v[4:5], v[8:9], 1.0 op_sel_hi:[1,0]
	s_nop 0
	s_nop 0
	v_rcp_f32_e32 v8, v5
	s_nop 0
	v_mul_f32_e32 v5, v21, v8
	s_nop 0
	v_rcp_f32_e32 v8, v4
	s_nop 0
	v_mul_f32_e32 v4, v20, v8
	v_pk_mul_f32 v[4:5], v[0:1], v[4:5]
	v_lshlrev_b32_e32 v0, 16, v2
	v_and_b32_e32 v1, 0xffff0000, v2
	v_lshlrev_b32_e32 v8, 16, v6
	v_and_b32_e32 v9, 0xffff0000, v6
	v_lshlrev_b32_e32 v2, 16, v10
	v_and_b32_e32 v6, 0xffff0000, v10
	v_mul_f32_e32 v10, 0xbfb8aa3b, v2
	v_pk_add_f32 v[0:1], v[0:1], v[8:9]
	v_mul_f32_e32 v8, 0xbfb8aa3b, v6
	v_exp_f32_e32 v22, v10
	v_exp_f32_e32 v23, v8
	v_pk_mul_f32 v[20:21], v[4:5], v[4:5]
	v_pk_add_f32 v[8:9], v[22:23], 1.0 op_sel_hi:[1,0]
	s_nop 0
	s_nop 0
	v_rcp_f32_e32 v10, v9
	s_nop 0
	v_mul_f32_e32 v9, v6, v10
	s_nop 0
	v_rcp_f32_e32 v6, v8
	s_nop 0
	v_mul_f32_e32 v8, v2, v6
	v_pk_mul_f32 v[8:9], v[0:1], v[8:9]
	v_lshlrev_b32_e32 v0, 16, v3
	v_and_b32_e32 v1, 0xffff0000, v3
	v_lshlrev_b32_e32 v2, 16, v7
	v_and_b32_e32 v3, 0xffff0000, v7
	v_lshlrev_b32_e32 v10, 16, v11
	v_and_b32_e32 v11, 0xffff0000, v11
	v_mul_f32_e32 v6, 0xbfb8aa3b, v10
	v_pk_add_f32 v[0:1], v[0:1], v[2:3]
	v_mul_f32_e32 v2, 0xbfb8aa3b, v11
	v_exp_f32_e32 v6, v6
	v_exp_f32_e32 v7, v2
	v_pk_mul_f32 v[22:23], v[8:9], v[8:9]
	v_pk_add_f32 v[2:3], v[6:7], 1.0 op_sel_hi:[1,0]
	s_nop 0
	s_nop 0
	v_rcp_f32_e32 v6, v3
	s_nop 0
	v_mul_f32_e32 v3, v11, v6
	s_nop 0
	v_rcp_f32_e32 v6, v2
	s_nop 0
	v_mul_f32_e32 v2, v10, v6
	v_pk_mul_f32 v[6:7], v[0:1], v[2:3]
	v_cvt_pk_bf16_f32 v0, v26, v27
	v_cvt_pk_bf16_f32 v1, v4, v5
	v_cvt_pk_bf16_f32 v2, v8, v9
	v_cvt_pk_bf16_f32 v3, v6, v7
	global_store_dwordx4 v[16:17], v[0:3], off offset:1024
	v_pk_mul_f32 v[24:25], v[6:7], v[6:7]
	global_load_dwordx4 v[0:3], v[16:17], off offset:2048
	global_load_dwordx4 v[4:7], v[14:15], off offset:1024
	global_load_dwordx4 v[8:11], v[16:17], off
	s_waitcnt vmcnt(2)
	v_lshlrev_b32_e32 v26, 16, v0
	v_and_b32_e32 v27, 0xffff0000, v0
	s_waitcnt vmcnt(0)
	v_lshlrev_b32_e32 v0, 16, v8
	v_lshlrev_b32_e32 v28, 16, v4
	v_and_b32_e32 v29, 0xffff0000, v4
	v_and_b32_e32 v4, 0xffff0000, v8
	v_mul_f32_e32 v8, 0xbfb8aa3b, v0
	v_exp_f32_e32 v38, v8
	v_mul_f32_e32 v8, 0xbfb8aa3b, v4
	v_exp_f32_e32 v39, v8
	v_pk_add_f32 v[26:27], v[26:27], v[28:29]
	v_pk_add_f32 v[28:29], v[38:39], 1.0 op_sel_hi:[1,0]
	s_nop 0
	s_nop 0
	v_rcp_f32_e32 v8, v29
	s_nop 0
	v_mul_f32_e32 v29, v4, v8
	s_nop 0
	v_rcp_f32_e32 v4, v28
	s_nop 0
	v_mul_f32_e32 v28, v0, v4
	v_lshlrev_b32_e32 v0, 16, v1
	v_and_b32_e32 v1, 0xffff0000, v1
	v_lshlrev_b32_e32 v4, 16, v5
	v_and_b32_e32 v5, 0xffff0000, v5
	v_lshlrev_b32_e32 v37, 16, v9
	v_and_b32_e32 v38, 0xffff0000, v9
	v_mul_f32_e32 v8, 0xbfb8aa3b, v37
	v_pk_add_f32 v[0:1], v[0:1], v[4:5]
	v_mul_f32_e32 v4, 0xbfb8aa3b, v38
	v_exp_f32_e32 v8, v8
	v_exp_f32_e32 v9, v4
	v_pk_mul_f32 v[26:27], v[26:27], v[28:29]
	v_pk_add_f32 v[4:5], v[8:9], 1.0 op_sel_hi:[1,0]
	s_nop 0
	v_pk_mul_f32 v[28:29], v[26:27], v[26:27]
	v_rcp_f32_e32 v8, v5
	s_nop 0
	v_mul_f32_e32 v5, v38, v8
	s_nop 0
	v_rcp_f32_e32 v8, v4
	s_nop 0
	v_mul_f32_e32 v4, v37, v8
	v_lshlrev_b32_e32 v8, 16, v2
	v_and_b32_e32 v9, 0xffff0000, v2
	v_lshlrev_b32_e32 v2, 16, v10
	v_lshlrev_b32_e32 v38, 16, v6
	v_and_b32_e32 v39, 0xffff0000, v6
	v_and_b32_e32 v6, 0xffff0000, v10
	v_mul_f32_e32 v10, 0xbfb8aa3b, v2
	v_exp_f32_e32 v40, v10
	v_mul_f32_e32 v10, 0xbfb8aa3b, v6
	v_exp_f32_e32 v41, v10
	v_pk_add_f32 v[8:9], v[8:9], v[38:39]
	v_pk_mul_f32 v[4:5], v[0:1], v[4:5]
	v_pk_add_f32 v[38:39], v[40:41], 1.0 op_sel_hi:[1,0]
	s_nop 0
	v_pk_mul_f32 v[0:1], v[4:5], v[4:5]
	v_rcp_f32_e32 v10, v39
	s_nop 0
	v_mul_f32_e32 v39, v6, v10
	s_nop 0
	v_rcp_f32_e32 v6, v38
	s_nop 0
	v_mul_f32_e32 v38, v2, v6
	v_lshlrev_b32_e32 v2, 16, v3
	v_and_b32_e32 v3, 0xffff0000, v3
	v_lshlrev_b32_e32 v6, 16, v7
	v_and_b32_e32 v7, 0xffff0000, v7
	v_lshlrev_b32_e32 v37, 16, v11
	v_and_b32_e32 v40, 0xffff0000, v11
	v_mul_f32_e32 v10, 0xbfb8aa3b, v37
	v_pk_add_f32 v[2:3], v[2:3], v[6:7]
	v_mul_f32_e32 v6, 0xbfb8aa3b, v40
	v_exp_f32_e32 v10, v10
	v_exp_f32_e32 v11, v6
	v_pk_mul_f32 v[8:9], v[8:9], v[38:39]
	v_pk_add_f32 v[6:7], v[10:11], 1.0 op_sel_hi:[1,0]
	s_nop 0
	v_pk_mul_f32 v[38:39], v[8:9], v[8:9]
	v_rcp_f32_e32 v10, v7
	s_nop 0
	v_mul_f32_e32 v7, v40, v10
	s_nop 0
	v_rcp_f32_e32 v10, v6
	s_nop 0
	v_mul_f32_e32 v6, v37, v10
	v_add_f32_e32 v10, v18, v19
	v_add_f32_e32 v10, v20, v10
	v_add_f32_e32 v10, v21, v10
	v_add_f32_e32 v10, v22, v10
	v_add_f32_e32 v10, v23, v10
	v_add_f32_e32 v10, v24, v10
	v_add_f32_e32 v10, v25, v10
	v_add_f32_e32 v10, v28, v10
	v_add_f32_e32 v10, v29, v10
	v_add_f32_e32 v0, v0, v10
	v_add_f32_e32 v0, v1, v0
	v_pk_mul_f32 v[6:7], v[2:3], v[6:7]
	v_add_f32_e32 v0, v38, v0
	v_pk_mul_f32 v[2:3], v[6:7], v[6:7]
	v_add_f32_e32 v0, v39, v0
	v_add_f32_e32 v0, v2, v0
	v_add_f32_e32 v10, v3, v0
	v_cvt_pk_bf16_f32 v0, v26, v27
	v_cvt_pk_bf16_f32 v1, v4, v5
	v_cvt_pk_bf16_f32 v2, v8, v9
	v_cvt_pk_bf16_f32 v3, v6, v7
	global_store_dwordx4 v[16:17], v[0:3], off offset:2048
	ds_bpermute_b32 v0, v31, v10
	s_waitcnt lgkmcnt(0)
	v_add_f32_e32 v0, v10, v0
	ds_bpermute_b32 v1, v32, v0
	s_waitcnt lgkmcnt(0)
	v_add_f32_e32 v0, v0, v1
	ds_bpermute_b32 v1, v33, v0
	s_waitcnt lgkmcnt(0)
	v_add_f32_e32 v0, v0, v1
	ds_bpermute_b32 v1, v34, v0
	s_waitcnt lgkmcnt(0)
	v_add_f32_e32 v0, v0, v1
	ds_bpermute_b32 v1, v35, v0
	s_waitcnt lgkmcnt(0)
	v_add_f32_e32 v0, v0, v1
	ds_bpermute_b32 v1, v36, v0
	s_and_saveexec_b64 s[10:11], s[4:5]
	s_cbranch_execz .LBB0_1730
	s_waitcnt lgkmcnt(0)
	v_add_f32_e32 v0, v0, v1
	v_fmamk_f32 v0, v0, 0x3a800000, v206
	v_mul_f32_e32 v1, 0x4b800000, v0
	v_cmp_gt_f32_e32 vcc, s83, v0
	s_nop 1
	s_nop 0
	v_cndmask_b32_e32 v0, v0, v1, vcc
	v_rsq_f32_e32 v0, v0
	s_nop 0
	v_mul_f32_e32 v1, 0x45800000, v0
	v_cndmask_b32_e32 v0, v0, v1, vcc
	global_store_dword v[12:13], v0, off
	s_branch .LBB0_1730

.LBB0_1789:
	v_mul_f32_e32 v112, 0xbfb8aa3b, v112
	v_mul_f32_e32 v113, 0xbfb8aa3b, v113
	v_exp_f32_e32 v112, v112
	v_exp_f32_e32 v113, v113
	v_mov_b32_e32 v128, v205
	s_lshl_b32 s2, s6, 8
	s_add_i32 s7, s15, 0x600
	s_cmpk_lt_i32 s15, 0x800
	s_waitcnt vmcnt(0)
	v_mov_b32_e32 v130, v205
	v_and_b32_e32 v131, 31, v128
	v_lshrrev_b32_e32 v128, 2, v128
	s_cselect_b32 s8, s15, s7
	v_and_b32_e32 v128, 8, v128
	s_movk_i32 s7, 0xffc0
	v_pk_add_f32 v[112:113], v[112:113], 1.0 op_sel_hi:[1,0]
	v_and_or_b32 v128, v130, s7, v128
	v_mad_u32_u24 v128, v131, s47, v128
	v_mul_f32_e32 v96, 0xbfb8aa3b, v96
	v_mul_f32_e32 v97, 0xbfb8aa3b, v97
	v_exp_f32_e32 v96, v96
	v_rcp_f32_e32 v113, v113
	s_nop 0
	v_exp_f32_e32 v97, v97
	v_mul_f32_e32 v80, 0xbfb8aa3b, v80
	v_mul_f32_e32 v81, 0xbfb8aa3b, v81
	v_rcp_f32_e32 v112, v112
	s_nop 0
	v_cvt_pk_bf16_f32 v112, v112, v113
	v_mul_f32_e32 v113, 0xbfb8aa3b, v114
	v_exp_f32_e32 v114, v113
	v_mul_f32_e32 v113, 0xbfb8aa3b, v115
	v_exp_f32_e32 v115, v113
	v_pk_add_f32 v[96:97], v[96:97], 1.0 op_sel_hi:[1,0]
	v_exp_f32_e32 v80, v80
	v_exp_f32_e32 v81, v81
	v_pk_add_f32 v[114:115], v[114:115], 1.0 op_sel_hi:[1,0]
	v_mul_f32_e32 v64, 0xbfb8aa3b, v64
	v_pk_add_f32 v[80:81], v[80:81], 1.0 op_sel_hi:[1,0]
	v_mul_f32_e32 v65, 0xbfb8aa3b, v65
	v_exp_f32_e32 v64, v64
	v_rcp_f32_e32 v113, v115
	s_nop 0
	v_exp_f32_e32 v65, v65
	v_mul_f32_e32 v48, 0xbfb8aa3b, v48
	v_mul_f32_e32 v49, 0xbfb8aa3b, v49
	v_rcp_f32_e32 v114, v114
	s_nop 0
	v_cvt_pk_bf16_f32 v113, v114, v113
	v_mul_f32_e32 v114, 0xbfb8aa3b, v116
	v_mul_f32_e32 v115, 0xbfb8aa3b, v117
	v_exp_f32_e32 v114, v114
	v_exp_f32_e32 v115, v115
	v_pk_add_f32 v[64:65], v[64:65], 1.0 op_sel_hi:[1,0]
	v_exp_f32_e32 v48, v48
	v_exp_f32_e32 v49, v49
	v_pk_add_f32 v[114:115], v[114:115], 1.0 op_sel_hi:[1,0]
	v_mul_f32_e32 v32, 0xbfb8aa3b, v32
	v_pk_add_f32 v[48:49], v[48:49], 1.0 op_sel_hi:[1,0]
	v_mul_f32_e32 v33, 0xbfb8aa3b, v33
	v_exp_f32_e32 v32, v32
	v_rcp_f32_e32 v115, v115
	s_nop 0
	v_exp_f32_e32 v33, v33
	v_mul_f32_e32 v16, 0xbfb8aa3b, v16
	v_mul_f32_e32 v17, 0xbfb8aa3b, v17
	v_rcp_f32_e32 v114, v114
	s_nop 0
	v_cvt_pk_bf16_f32 v114, v114, v115
	v_mul_f32_e32 v115, 0xbfb8aa3b, v118
	v_exp_f32_e32 v116, v115
	v_mul_f32_e32 v115, 0xbfb8aa3b, v119
	v_exp_f32_e32 v117, v115
	v_pk_add_f32 v[32:33], v[32:33], 1.0 op_sel_hi:[1,0]
	v_exp_f32_e32 v16, v16
	v_exp_f32_e32 v17, v17
	v_pk_add_f32 v[116:117], v[116:117], 1.0 op_sel_hi:[1,0]
	v_mul_f32_e32 v0, 0xbfb8aa3b, v0
	v_pk_add_f32 v[16:17], v[16:17], 1.0 op_sel_hi:[1,0]
	v_mul_f32_e32 v1, 0xbfb8aa3b, v1
	v_exp_f32_e32 v0, v0
	v_rcp_f32_e32 v115, v117
	s_nop 0
	v_exp_f32_e32 v1, v1
	s_mul_i32 s6, s6, 0x248000
	s_mul_hi_i32 s2, s2, 0x2480
	v_rcp_f32_e32 v116, v116
	s_nop 0
	v_cvt_pk_bf16_f32 v115, v116, v115
	ds_write2_b64 v128, v[112:113], v[114:115] offset1:2
	v_mul_f32_e32 v112, 0xbfb8aa3b, v120
	v_mul_f32_e32 v113, 0xbfb8aa3b, v121
	v_exp_f32_e32 v112, v112
	v_exp_f32_e32 v113, v113
	v_pk_add_f32 v[0:1], v[0:1], 1.0 op_sel_hi:[1,0]
	s_add_u32 s6, s4, s6
	s_addc_u32 s2, s5, s2
	v_pk_add_f32 v[112:113], v[112:113], 1.0 op_sel_hi:[1,0]
	s_ashr_i32 s9, s8, 31
	s_lshl_b64 s[4:5], s[8:9], 1
	s_add_u32 s4, s6, s4
	s_addc_u32 s5, s2, s5
	v_rcp_f32_e32 v113, v113
	s_nop 0
	s_nop 0
	v_rcp_f32_e32 v112, v112
	s_nop 0
	v_cvt_pk_bf16_f32 v112, v112, v113
	v_mul_f32_e32 v113, 0xbfb8aa3b, v122
	v_exp_f32_e32 v114, v113
	v_mul_f32_e32 v113, 0xbfb8aa3b, v123
	v_exp_f32_e32 v115, v113
	s_nop 0
	v_pk_add_f32 v[114:115], v[114:115], 1.0 op_sel_hi:[1,0]
	s_nop 0
	s_nop 0
	v_rcp_f32_e32 v113, v115
	s_nop 0
	s_nop 0
	v_rcp_f32_e32 v114, v114
	s_nop 0
	v_cvt_pk_bf16_f32 v113, v114, v113
	v_mul_f32_e32 v114, 0xbfb8aa3b, v124
	v_mul_f32_e32 v115, 0xbfb8aa3b, v125
	v_exp_f32_e32 v114, v114
	v_exp_f32_e32 v115, v115
	s_nop 0
	v_pk_add_f32 v[114:115], v[114:115], 1.0 op_sel_hi:[1,0]
	s_nop 0
	s_nop 0
	v_rcp_f32_e32 v115, v115
	s_nop 0
	s_nop 0
	v_rcp_f32_e32 v114, v114
	s_nop 0
	v_cvt_pk_bf16_f32 v114, v114, v115
	v_mul_f32_e32 v115, 0xbfb8aa3b, v126
	v_exp_f32_e32 v116, v115
	v_mul_f32_e32 v115, 0xbfb8aa3b, v127
	v_exp_f32_e32 v117, v115
	s_nop 0
	v_pk_add_f32 v[116:117], v[116:117], 1.0 op_sel_hi:[1,0]
	s_nop 0
	s_nop 0
	v_rcp_f32_e32 v115, v117
	s_nop 0
	s_nop 0
	v_rcp_f32_e32 v116, v116
	s_nop 0
	v_cvt_pk_bf16_f32 v115, v116, v115
	ds_write2_b64 v128, v[112:113], v[114:115] offset0:4 offset1:6
	s_nop 0
	v_rcp_f32_e32 v97, v97
	s_nop 0
	s_nop 0
	v_rcp_f32_e32 v96, v96
	s_nop 0
	v_cvt_pk_bf16_f32 v96, v96, v97
	v_mul_f32_e32 v97, 0xbfb8aa3b, v98
	v_exp_f32_e32 v98, v97
	v_mul_f32_e32 v97, 0xbfb8aa3b, v99
	v_exp_f32_e32 v99, v97
	s_nop 0
	v_pk_add_f32 v[98:99], v[98:99], 1.0 op_sel_hi:[1,0]
	s_nop 0
	s_nop 0
	v_rcp_f32_e32 v97, v99
	s_nop 0
	s_nop 0
	v_rcp_f32_e32 v98, v98
	s_nop 0
	v_cvt_pk_bf16_f32 v97, v98, v97
	v_mul_f32_e32 v98, 0xbfb8aa3b, v100
	v_mul_f32_e32 v99, 0xbfb8aa3b, v101
	v_exp_f32_e32 v98, v98
	v_exp_f32_e32 v99, v99
	s_nop 0
	v_pk_add_f32 v[98:99], v[98:99], 1.0 op_sel_hi:[1,0]
	s_nop 0
	s_nop 0
	v_rcp_f32_e32 v99, v99
	s_nop 0
	s_nop 0
	v_rcp_f32_e32 v98, v98
	s_nop 0
	v_cvt_pk_bf16_f32 v98, v98, v99
	v_mul_f32_e32 v99, 0xbfb8aa3b, v102
	v_exp_f32_e32 v100, v99
	v_mul_f32_e32 v99, 0xbfb8aa3b, v103
	v_exp_f32_e32 v101, v99
	s_nop 0
	v_pk_add_f32 v[100:101], v[100:101], 1.0 op_sel_hi:[1,0]
	s_nop 0
	s_nop 0
	v_rcp_f32_e32 v99, v101
	s_nop 0
	s_nop 0
	v_rcp_f32_e32 v100, v100
	s_nop 0
	v_cvt_pk_bf16_f32 v99, v100, v99
	v_add_u32_e32 v102, 0x2000, v128
	ds_write2_b64 v102, v[96:97], v[98:99] offset0:64 offset1:66
	v_mul_f32_e32 v96, 0xbfb8aa3b, v104
	v_mul_f32_e32 v97, 0xbfb8aa3b, v105
	v_exp_f32_e32 v96, v96
	v_exp_f32_e32 v97, v97
	s_nop 0
	v_pk_add_f32 v[96:97], v[96:97], 1.0 op_sel_hi:[1,0]
	s_nop 0
	s_nop 0
	v_rcp_f32_e32 v97, v97
	s_nop 0
	s_nop 0
	v_rcp_f32_e32 v96, v96
	s_nop 0
	v_cvt_pk_bf16_f32 v96, v96, v97
	v_mul_f32_e32 v97, 0xbfb8aa3b, v106
	v_exp_f32_e32 v98, v97
	v_mul_f32_e32 v97, 0xbfb8aa3b, v107
	v_exp_f32_e32 v99, v97
	s_nop 0
	v_pk_add_f32 v[98:99], v[98:99], 1.0 op_sel_hi:[1,0]
	s_nop 0
	s_nop 0
	v_rcp_f32_e32 v97, v99
	s_nop 0
	s_nop 0
	v_rcp_f32_e32 v98, v98
	s_nop 0
	v_cvt_pk_bf16_f32 v97, v98, v97
	v_mul_f32_e32 v98, 0xbfb8aa3b, v108
	v_mul_f32_e32 v99, 0xbfb8aa3b, v109
	v_exp_f32_e32 v98, v98
	v_exp_f32_e32 v99, v99
	s_nop 0
	v_pk_add_f32 v[98:99], v[98:99], 1.0 op_sel_hi:[1,0]
	s_nop 0
	s_nop 0
	v_rcp_f32_e32 v99, v99
	s_nop 0
	s_nop 0
	v_rcp_f32_e32 v98, v98
	s_nop 0
	v_cvt_pk_bf16_f32 v98, v98, v99
	v_mul_f32_e32 v99, 0xbfb8aa3b, v110
	v_exp_f32_e32 v100, v99
	v_mul_f32_e32 v99, 0xbfb8aa3b, v111
	v_exp_f32_e32 v101, v99
	s_nop 0
	v_pk_add_f32 v[100:101], v[100:101], 1.0 op_sel_hi:[1,0]
	s_nop 0
	s_nop 0
	v_rcp_f32_e32 v99, v101
	s_nop 0
	s_nop 0
	v_rcp_f32_e32 v100, v100
	s_nop 0
	v_cvt_pk_bf16_f32 v99, v100, v99
	ds_write2_b64 v102, v[96:97], v[98:99] offset0:68 offset1:70
	s_nop 0
	v_rcp_f32_e32 v81, v81
	s_nop 0
	s_nop 0
	v_rcp_f32_e32 v80, v80
	s_nop 0
	v_cvt_pk_bf16_f32 v80, v80, v81
	v_mul_f32_e32 v81, 0xbfb8aa3b, v82
	v_exp_f32_e32 v82, v81
	v_mul_f32_e32 v81, 0xbfb8aa3b, v83
	v_exp_f32_e32 v83, v81
	s_nop 0
	v_pk_add_f32 v[82:83], v[82:83], 1.0 op_sel_hi:[1,0]
	s_nop 0
	s_nop 0
	v_rcp_f32_e32 v81, v83
	s_nop 0
	s_nop 0
	v_rcp_f32_e32 v82, v82
	s_nop 0
	v_cvt_pk_bf16_f32 v81, v82, v81
	v_mul_f32_e32 v82, 0xbfb8aa3b, v84
	v_mul_f32_e32 v83, 0xbfb8aa3b, v85
	v_exp_f32_e32 v82, v82
	v_exp_f32_e32 v83, v83
	s_nop 0
	v_pk_add_f32 v[82:83], v[82:83], 1.0 op_sel_hi:[1,0]
	s_nop 0
	s_nop 0
	v_rcp_f32_e32 v83, v83
	s_nop 0
	s_nop 0
	v_rcp_f32_e32 v82, v82
	s_nop 0
	v_cvt_pk_bf16_f32 v82, v82, v83
	v_mul_f32_e32 v83, 0xbfb8aa3b, v86
	v_exp_f32_e32 v84, v83
	v_mul_f32_e32 v83, 0xbfb8aa3b, v87
	v_exp_f32_e32 v85, v83
	s_nop 0
	v_pk_add_f32 v[84:85], v[84:85], 1.0 op_sel_hi:[1,0]
	s_nop 0
	s_nop 0
	v_rcp_f32_e32 v83, v85
	s_nop 0
	s_nop 0
	v_rcp_f32_e32 v84, v84
	s_nop 0
	v_cvt_pk_bf16_f32 v83, v84, v83
	v_add_u32_e32 v86, 0x4000, v128
	ds_write2_b64 v86, v[80:81], v[82:83] offset0:128 offset1:130
	v_mul_f32_e32 v80, 0xbfb8aa3b, v88
	v_mul_f32_e32 v81, 0xbfb8aa3b, v89
	v_exp_f32_e32 v80, v80
	v_exp_f32_e32 v81, v81
	s_nop 0
	v_pk_add_f32 v[80:81], v[80:81], 1.0 op_sel_hi:[1,0]
	s_nop 0
	s_nop 0
	v_rcp_f32_e32 v81, v81
	s_nop 0
	s_nop 0
	v_rcp_f32_e32 v80, v80
	s_nop 0
	v_cvt_pk_bf16_f32 v80, v80, v81
	v_mul_f32_e32 v81, 0xbfb8aa3b, v90
	v_exp_f32_e32 v82, v81
	v_mul_f32_e32 v81, 0xbfb8aa3b, v91
	v_exp_f32_e32 v83, v81
	s_nop 0
	v_pk_add_f32 v[82:83], v[82:83], 1.0 op_sel_hi:[1,0]
	s_nop 0
	s_nop 0
	v_rcp_f32_e32 v81, v83
	s_nop 0
	s_nop 0
	v_rcp_f32_e32 v82, v82
	s_nop 0
	v_cvt_pk_bf16_f32 v81, v82, v81
	v_mul_f32_e32 v82, 0xbfb8aa3b, v92
	v_mul_f32_e32 v83, 0xbfb8aa3b, v93
	v_exp_f32_e32 v82, v82
	v_exp_f32_e32 v83, v83
	s_nop 0
	v_pk_add_f32 v[82:83], v[82:83], 1.0 op_sel_hi:[1,0]
	s_nop 0
	s_nop 0
	v_rcp_f32_e32 v83, v83
	s_nop 0
	s_nop 0
	v_rcp_f32_e32 v82, v82
	s_nop 0
	v_cvt_pk_bf16_f32 v82, v82, v83
	v_mul_f32_e32 v83, 0xbfb8aa3b, v94
	v_exp_f32_e32 v84, v83
	v_mul_f32_e32 v83, 0xbfb8aa3b, v95
	v_exp_f32_e32 v85, v83
	s_nop 0
	v_pk_add_f32 v[84:85], v[84:85], 1.0 op_sel_hi:[1,0]
	s_nop 0
	s_nop 0
	v_rcp_f32_e32 v83, v85
	s_nop 0
	s_nop 0
	v_rcp_f32_e32 v84, v84
	s_nop 0
	v_cvt_pk_bf16_f32 v83, v84, v83
	ds_write2_b64 v86, v[80:81], v[82:83] offset0:132 offset1:134
	s_nop 0
	v_rcp_f32_e32 v65, v65
	s_nop 0
	s_nop 0
	v_rcp_f32_e32 v64, v64
	s_nop 0
	v_cvt_pk_bf16_f32 v64, v64, v65
	v_mul_f32_e32 v65, 0xbfb8aa3b, v66
	v_exp_f32_e32 v66, v65
	v_mul_f32_e32 v65, 0xbfb8aa3b, v67
	v_exp_f32_e32 v67, v65
	s_nop 0
	v_pk_add_f32 v[66:67], v[66:67], 1.0 op_sel_hi:[1,0]
	s_nop 0
	s_nop 0
	v_rcp_f32_e32 v65, v67
	s_nop 0
	s_nop 0
	v_rcp_f32_e32 v66, v66
	s_nop 0
	v_cvt_pk_bf16_f32 v65, v66, v65
	v_mul_f32_e32 v66, 0xbfb8aa3b, v68
	v_mul_f32_e32 v67, 0xbfb8aa3b, v69
	v_exp_f32_e32 v66, v66
	v_exp_f32_e32 v67, v67
	s_nop 0
	v_pk_add_f32 v[66:67], v[66:67], 1.0 op_sel_hi:[1,0]
	s_nop 0
	s_nop 0
	v_rcp_f32_e32 v67, v67
	s_nop 0
	s_nop 0
	v_rcp_f32_e32 v66, v66
	s_nop 0
	v_cvt_pk_bf16_f32 v66, v66, v67
	v_mul_f32_e32 v67, 0xbfb8aa3b, v70
	v_exp_f32_e32 v68, v67
	v_mul_f32_e32 v67, 0xbfb8aa3b, v71
	v_exp_f32_e32 v69, v67
	s_nop 0
	v_pk_add_f32 v[68:69], v[68:69], 1.0 op_sel_hi:[1,0]
	s_nop 0
	s_nop 0
	v_rcp_f32_e32 v67, v69
	s_nop 0
	s_nop 0
	v_rcp_f32_e32 v68, v68
	s_nop 0
	v_cvt_pk_bf16_f32 v67, v68, v67
	v_add_u32_e32 v70, 0x6000, v128
	ds_write2_b64 v70, v[64:65], v[66:67] offset0:192 offset1:194
	v_mul_f32_e32 v64, 0xbfb8aa3b, v72
	v_mul_f32_e32 v65, 0xbfb8aa3b, v73
	v_exp_f32_e32 v64, v64
	v_exp_f32_e32 v65, v65
	s_nop 0
	v_pk_add_f32 v[64:65], v[64:65], 1.0 op_sel_hi:[1,0]
	s_nop 0
	s_nop 0
	v_rcp_f32_e32 v65, v65
	s_nop 0
	s_nop 0
	v_rcp_f32_e32 v64, v64
	s_nop 0
	v_cvt_pk_bf16_f32 v64, v64, v65
	v_mul_f32_e32 v65, 0xbfb8aa3b, v74
	v_exp_f32_e32 v66, v65
	v_mul_f32_e32 v65, 0xbfb8aa3b, v75
	v_exp_f32_e32 v67, v65
	s_nop 0
	v_pk_add_f32 v[66:67], v[66:67], 1.0 op_sel_hi:[1,0]
	s_nop 0
	s_nop 0
	v_rcp_f32_e32 v65, v67
	s_nop 0
	s_nop 0
	v_rcp_f32_e32 v66, v66
	s_nop 0
	v_cvt_pk_bf16_f32 v65, v66, v65
	v_mul_f32_e32 v66, 0xbfb8aa3b, v76
	v_mul_f32_e32 v67, 0xbfb8aa3b, v77
	v_exp_f32_e32 v66, v66
	v_exp_f32_e32 v67, v67
	s_nop 0
	v_pk_add_f32 v[66:67], v[66:67], 1.0 op_sel_hi:[1,0]
	s_nop 0
	s_nop 0
	v_rcp_f32_e32 v67, v67
	s_nop 0
	s_nop 0
	v_rcp_f32_e32 v66, v66
	s_nop 0
	v_cvt_pk_bf16_f32 v66, v66, v67
	v_mul_f32_e32 v67, 0xbfb8aa3b, v78
	v_exp_f32_e32 v68, v67
	v_mul_f32_e32 v67, 0xbfb8aa3b, v79
	v_exp_f32_e32 v69, v67
	s_nop 0
	v_pk_add_f32 v[68:69], v[68:69], 1.0 op_sel_hi:[1,0]
	s_nop 0
	s_nop 0
	v_rcp_f32_e32 v67, v69
	s_nop 0
	s_nop 0
	v_rcp_f32_e32 v68, v68
	s_nop 0
	v_cvt_pk_bf16_f32 v67, v68, v67
	ds_write2_b64 v70, v[64:65], v[66:67] offset0:196 offset1:198
	s_nop 0
	v_rcp_f32_e32 v49, v49
	s_nop 0
	s_nop 0
	v_rcp_f32_e32 v48, v48
	s_nop 0
	v_cvt_pk_bf16_f32 v48, v48, v49
	v_mul_f32_e32 v49, 0xbfb8aa3b, v50
	v_exp_f32_e32 v50, v49
	v_mul_f32_e32 v49, 0xbfb8aa3b, v51
	v_exp_f32_e32 v51, v49
	s_nop 0
	v_pk_add_f32 v[50:51], v[50:51], 1.0 op_sel_hi:[1,0]
	s_nop 0
	s_nop 0
	v_rcp_f32_e32 v49, v51
	s_nop 0
	s_nop 0
	v_rcp_f32_e32 v50, v50
	s_nop 0
	v_cvt_pk_bf16_f32 v49, v50, v49
	v_mul_f32_e32 v50, 0xbfb8aa3b, v52
	v_mul_f32_e32 v51, 0xbfb8aa3b, v53
	v_exp_f32_e32 v50, v50
	v_exp_f32_e32 v51, v51
	s_nop 0
	v_pk_add_f32 v[50:51], v[50:51], 1.0 op_sel_hi:[1,0]
	s_nop 0
	s_nop 0
	v_rcp_f32_e32 v51, v51
	s_nop 0
	s_nop 0
	v_rcp_f32_e32 v50, v50
	s_nop 0
	v_cvt_pk_bf16_f32 v50, v50, v51
	v_mul_f32_e32 v51, 0xbfb8aa3b, v54
	v_exp_f32_e32 v52, v51
	v_mul_f32_e32 v51, 0xbfb8aa3b, v55
	v_exp_f32_e32 v53, v51
	s_nop 0
	v_pk_add_f32 v[52:53], v[52:53], 1.0 op_sel_hi:[1,0]
	s_nop 0
	s_nop 0
	v_rcp_f32_e32 v51, v53
	s_nop 0
	s_nop 0
	v_rcp_f32_e32 v52, v52
	s_nop 0
	v_cvt_pk_bf16_f32 v51, v52, v51
	v_add_u32_e32 v54, 0x8800, v128
	ds_write2_b64 v54, v[48:49], v[50:51] offset1:2
	v_mul_f32_e32 v48, 0xbfb8aa3b, v56
	v_mul_f32_e32 v49, 0xbfb8aa3b, v57
	v_exp_f32_e32 v48, v48
	v_exp_f32_e32 v49, v49
	s_nop 0
	v_pk_add_f32 v[48:49], v[48:49], 1.0 op_sel_hi:[1,0]
	s_nop 0
	s_nop 0
	v_rcp_f32_e32 v49, v49
	s_nop 0
	s_nop 0
	v_rcp_f32_e32 v48, v48
	s_nop 0
	v_cvt_pk_bf16_f32 v48, v48, v49
	v_mul_f32_e32 v49, 0xbfb8aa3b, v58
	v_exp_f32_e32 v50, v49
	v_mul_f32_e32 v49, 0xbfb8aa3b, v59
	v_exp_f32_e32 v51, v49
	s_nop 0
	v_pk_add_f32 v[50:51], v[50:51], 1.0 op_sel_hi:[1,0]
	s_nop 0
	s_nop 0
	v_rcp_f32_e32 v49, v51
	s_nop 0
	s_nop 0
	v_rcp_f32_e32 v50, v50
	s_nop 0
	v_cvt_pk_bf16_f32 v49, v50, v49
	v_mul_f32_e32 v50, 0xbfb8aa3b, v60
	v_mul_f32_e32 v51, 0xbfb8aa3b, v61
	v_exp_f32_e32 v50, v50
	v_exp_f32_e32 v51, v51
	s_nop 0
	v_pk_add_f32 v[50:51], v[50:51], 1.0 op_sel_hi:[1,0]
	s_nop 0
	s_nop 0
	v_rcp_f32_e32 v51, v51
	s_nop 0
	s_nop 0
	v_rcp_f32_e32 v50, v50
	s_nop 0
	v_cvt_pk_bf16_f32 v50, v50, v51
	v_mul_f32_e32 v51, 0xbfb8aa3b, v62
	v_exp_f32_e32 v52, v51
	v_mul_f32_e32 v51, 0xbfb8aa3b, v63
	v_exp_f32_e32 v53, v51
	s_nop 0
	v_pk_add_f32 v[52:53], v[52:53], 1.0 op_sel_hi:[1,0]
	s_nop 0
	s_nop 0
	v_rcp_f32_e32 v51, v53
	s_nop 0
	s_nop 0
	v_rcp_f32_e32 v52, v52
	s_nop 0
	v_cvt_pk_bf16_f32 v51, v52, v51
	ds_write2_b64 v54, v[48:49], v[50:51] offset0:4 offset1:6
	s_nop 0
	v_rcp_f32_e32 v33, v33
	s_nop 0
	s_nop 0
	v_rcp_f32_e32 v32, v32
	s_nop 0
	v_cvt_pk_bf16_f32 v32, v32, v33
	v_mul_f32_e32 v33, 0xbfb8aa3b, v34
	v_exp_f32_e32 v34, v33
	v_mul_f32_e32 v33, 0xbfb8aa3b, v35
	v_exp_f32_e32 v35, v33
	s_nop 0
	v_pk_add_f32 v[34:35], v[34:35], 1.0 op_sel_hi:[1,0]
	s_nop 0
	s_nop 0
	v_rcp_f32_e32 v33, v35
	s_nop 0
	s_nop 0
	v_rcp_f32_e32 v34, v34
	s_nop 0
	v_cvt_pk_bf16_f32 v33, v34, v33
	v_mul_f32_e32 v34, 0xbfb8aa3b, v36
	v_mul_f32_e32 v35, 0xbfb8aa3b, v37
	v_exp_f32_e32 v34, v34
	v_exp_f32_e32 v35, v35
	s_nop 0
	v_pk_add_f32 v[34:35], v[34:35], 1.0 op_sel_hi:[1,0]
	s_nop 0
	s_nop 0
	v_rcp_f32_e32 v35, v35
	s_nop 0
	s_nop 0
	v_rcp_f32_e32 v34, v34
	s_nop 0
	v_cvt_pk_bf16_f32 v34, v34, v35
	v_mul_f32_e32 v35, 0xbfb8aa3b, v38
	v_exp_f32_e32 v36, v35
	v_mul_f32_e32 v35, 0xbfb8aa3b, v39
	v_exp_f32_e32 v37, v35
	s_nop 0
	v_pk_add_f32 v[36:37], v[36:37], 1.0 op_sel_hi:[1,0]
	s_nop 0
	s_nop 0
	v_rcp_f32_e32 v35, v37
	s_nop 0
	s_nop 0
	v_rcp_f32_e32 v36, v36
	s_nop 0
	v_cvt_pk_bf16_f32 v35, v36, v35
	v_add_u32_e32 v38, 0xa800, v128
	ds_write2_b64 v38, v[32:33], v[34:35] offset0:64 offset1:66
	v_mul_f32_e32 v32, 0xbfb8aa3b, v40
	v_mul_f32_e32 v33, 0xbfb8aa3b, v41
	v_exp_f32_e32 v32, v32
	v_exp_f32_e32 v33, v33
	s_nop 0
	v_pk_add_f32 v[32:33], v[32:33], 1.0 op_sel_hi:[1,0]
	s_nop 0
	s_nop 0
	v_rcp_f32_e32 v33, v33
	s_nop 0
	s_nop 0
	v_rcp_f32_e32 v32, v32
	s_nop 0
	v_cvt_pk_bf16_f32 v32, v32, v33
	v_mul_f32_e32 v33, 0xbfb8aa3b, v42
	v_exp_f32_e32 v34, v33
	v_mul_f32_e32 v33, 0xbfb8aa3b, v43
	v_exp_f32_e32 v35, v33
	s_nop 0
	v_pk_add_f32 v[34:35], v[34:35], 1.0 op_sel_hi:[1,0]
	s_nop 0
	s_nop 0
	v_rcp_f32_e32 v33, v35
	s_nop 0
	s_nop 0
	v_rcp_f32_e32 v34, v34
	s_nop 0
	v_cvt_pk_bf16_f32 v33, v34, v33
	v_mul_f32_e32 v34, 0xbfb8aa3b, v44
	v_mul_f32_e32 v35, 0xbfb8aa3b, v45
	v_exp_f32_e32 v34, v34
	v_exp_f32_e32 v35, v35
	s_nop 0
	v_pk_add_f32 v[34:35], v[34:35], 1.0 op_sel_hi:[1,0]
	s_nop 0
	s_nop 0
	v_rcp_f32_e32 v35, v35
	s_nop 0
	s_nop 0
	v_rcp_f32_e32 v34, v34
	s_nop 0
	v_cvt_pk_bf16_f32 v34, v34, v35
	v_mul_f32_e32 v35, 0xbfb8aa3b, v46
	v_exp_f32_e32 v36, v35
	v_mul_f32_e32 v35, 0xbfb8aa3b, v47
	v_exp_f32_e32 v37, v35
	s_nop 0
	v_pk_add_f32 v[36:37], v[36:37], 1.0 op_sel_hi:[1,0]
	s_nop 0
	s_nop 0
	v_rcp_f32_e32 v35, v37
	s_nop 0
	s_nop 0
	v_rcp_f32_e32 v36, v36
	s_nop 0
	v_cvt_pk_bf16_f32 v35, v36, v35
	ds_write2_b64 v38, v[32:33], v[34:35] offset0:68 offset1:70
	s_nop 0
	v_rcp_f32_e32 v17, v17
	s_nop 0
	s_nop 0
	v_rcp_f32_e32 v16, v16
	s_nop 0
	v_cvt_pk_bf16_f32 v16, v16, v17
	v_mul_f32_e32 v17, 0xbfb8aa3b, v18
	v_exp_f32_e32 v18, v17
	v_mul_f32_e32 v17, 0xbfb8aa3b, v19
	v_exp_f32_e32 v19, v17
	s_nop 0
	v_pk_add_f32 v[18:19], v[18:19], 1.0 op_sel_hi:[1,0]
	s_nop 0
	s_nop 0
	v_rcp_f32_e32 v17, v19
	s_nop 0
	s_nop 0
	v_rcp_f32_e32 v18, v18
	s_nop 0
	v_cvt_pk_bf16_f32 v17, v18, v17
	v_mul_f32_e32 v18, 0xbfb8aa3b, v20
	v_mul_f32_e32 v19, 0xbfb8aa3b, v21
	v_exp_f32_e32 v18, v18
	v_exp_f32_e32 v19, v19
	s_nop 0
	v_pk_add_f32 v[18:19], v[18:19], 1.0 op_sel_hi:[1,0]
	s_nop 0
	s_nop 0
	v_rcp_f32_e32 v19, v19
	s_nop 0
	s_nop 0
	v_rcp_f32_e32 v18, v18
	s_nop 0
	v_cvt_pk_bf16_f32 v18, v18, v19
	v_mul_f32_e32 v19, 0xbfb8aa3b, v22
	v_exp_f32_e32 v20, v19
	v_mul_f32_e32 v19, 0xbfb8aa3b, v23
	v_exp_f32_e32 v21, v19
	s_nop 0
	v_pk_add_f32 v[20:21], v[20:21], 1.0 op_sel_hi:[1,0]
	s_nop 0
	s_nop 0
	v_rcp_f32_e32 v19, v21
	s_nop 0
	s_nop 0
	v_rcp_f32_e32 v20, v20
	s_nop 0
	v_cvt_pk_bf16_f32 v19, v20, v19
	v_add_u32_e32 v22, 0xc800, v128
	ds_write2_b64 v22, v[16:17], v[18:19] offset0:128 offset1:130
	v_mul_f32_e32 v16, 0xbfb8aa3b, v24
	v_mul_f32_e32 v17, 0xbfb8aa3b, v25
	v_exp_f32_e32 v16, v16
	v_exp_f32_e32 v17, v17
	s_nop 0
	v_pk_add_f32 v[16:17], v[16:17], 1.0 op_sel_hi:[1,0]
	s_nop 0
	s_nop 0
	v_rcp_f32_e32 v17, v17
	s_nop 0
	s_nop 0
	v_rcp_f32_e32 v16, v16
	s_nop 0
	v_cvt_pk_bf16_f32 v16, v16, v17
	v_mul_f32_e32 v17, 0xbfb8aa3b, v26
	v_exp_f32_e32 v18, v17
	v_mul_f32_e32 v17, 0xbfb8aa3b, v27
	v_exp_f32_e32 v19, v17
	s_nop 0
	v_pk_add_f32 v[18:19], v[18:19], 1.0 op_sel_hi:[1,0]
	s_nop 0
	s_nop 0
	v_rcp_f32_e32 v17, v19
	s_nop 0
	s_nop 0
	v_rcp_f32_e32 v18, v18
	s_nop 0
	v_cvt_pk_bf16_f32 v17, v18, v17
	v_mul_f32_e32 v18, 0xbfb8aa3b, v28
	v_mul_f32_e32 v19, 0xbfb8aa3b, v29
	v_exp_f32_e32 v18, v18
	v_exp_f32_e32 v19, v19
	s_nop 0
	v_pk_add_f32 v[18:19], v[18:19], 1.0 op_sel_hi:[1,0]
	s_nop 0
	s_nop 0
	v_rcp_f32_e32 v19, v19
	s_nop 0
	s_nop 0
	v_rcp_f32_e32 v18, v18
	s_nop 0
	v_cvt_pk_bf16_f32 v18, v18, v19
	v_mul_f32_e32 v19, 0xbfb8aa3b, v30
	v_exp_f32_e32 v20, v19
	v_mul_f32_e32 v19, 0xbfb8aa3b, v31
	v_exp_f32_e32 v21, v19
	s_nop 0
	v_pk_add_f32 v[20:21], v[20:21], 1.0 op_sel_hi:[1,0]
	s_nop 0
	s_nop 0
	v_rcp_f32_e32 v19, v21
	s_nop 0
	s_nop 0
	v_rcp_f32_e32 v20, v20
	s_nop 0
	v_cvt_pk_bf16_f32 v19, v20, v19
	ds_write2_b64 v22, v[16:17], v[18:19] offset0:132 offset1:134
	s_nop 0
	v_rcp_f32_e32 v1, v1
	s_nop 0
	s_nop 0
	v_rcp_f32_e32 v0, v0
	s_nop 0
	v_cvt_pk_bf16_f32 v0, v0, v1
	v_mul_f32_e32 v1, 0xbfb8aa3b, v2
	v_exp_f32_e32 v2, v1
	v_mul_f32_e32 v1, 0xbfb8aa3b, v3
	v_exp_f32_e32 v3, v1
	s_nop 0
	v_pk_add_f32 v[2:3], v[2:3], 1.0 op_sel_hi:[1,0]
	s_nop 0
	s_nop 0
	v_rcp_f32_e32 v1, v3
	s_nop 0
	s_nop 0
	v_rcp_f32_e32 v2, v2
	s_nop 0
	v_cvt_pk_bf16_f32 v1, v2, v1
	v_mul_f32_e32 v2, 0xbfb8aa3b, v4
	v_mul_f32_e32 v3, 0xbfb8aa3b, v5
	v_exp_f32_e32 v2, v2
	v_exp_f32_e32 v3, v3
	s_nop 0
	v_pk_add_f32 v[2:3], v[2:3], 1.0 op_sel_hi:[1,0]
	s_nop 0
	s_nop 0
	v_rcp_f32_e32 v3, v3
	s_nop 0
	s_nop 0
	v_rcp_f32_e32 v2, v2
	s_nop 0
	v_cvt_pk_bf16_f32 v2, v2, v3
	v_mul_f32_e32 v3, 0xbfb8aa3b, v6
	v_exp_f32_e32 v4, v3
	v_mul_f32_e32 v3, 0xbfb8aa3b, v7
	v_exp_f32_e32 v5, v3
	s_nop 0
	v_pk_add_f32 v[4:5], v[4:5], 1.0 op_sel_hi:[1,0]
	s_nop 0
	s_nop 0
	v_rcp_f32_e32 v3, v5
	s_nop 0
	s_nop 0
	v_rcp_f32_e32 v4, v4
	s_nop 0
	v_cvt_pk_bf16_f32 v3, v4, v3
	v_add_u32_e32 v6, 0xe800, v128
	ds_write2_b64 v6, v[0:1], v[2:3] offset0:192 offset1:194
	v_mul_f32_e32 v0, 0xbfb8aa3b, v8
	v_mul_f32_e32 v1, 0xbfb8aa3b, v9
	v_exp_f32_e32 v0, v0
	v_exp_f32_e32 v1, v1
	s_nop 0
	v_pk_add_f32 v[0:1], v[0:1], 1.0 op_sel_hi:[1,0]
	s_nop 0
	s_nop 0
	v_rcp_f32_e32 v1, v1
	s_nop 0
	s_nop 0
	v_rcp_f32_e32 v0, v0
	s_nop 0
	v_cvt_pk_bf16_f32 v0, v0, v1
	v_mul_f32_e32 v1, 0xbfb8aa3b, v10
	v_exp_f32_e32 v2, v1
	v_mul_f32_e32 v1, 0xbfb8aa3b, v11
	v_exp_f32_e32 v3, v1
	s_nop 0
	v_pk_add_f32 v[2:3], v[2:3], 1.0 op_sel_hi:[1,0]
	s_nop 0
	s_nop 0
	v_rcp_f32_e32 v1, v3
	s_nop 0
	s_nop 0
	v_rcp_f32_e32 v2, v2
	s_nop 0
	v_cvt_pk_bf16_f32 v1, v2, v1
	v_mul_f32_e32 v2, 0xbfb8aa3b, v12
	v_mul_f32_e32 v3, 0xbfb8aa3b, v13
	v_exp_f32_e32 v2, v2
	v_exp_f32_e32 v3, v3
	s_nop 0
	v_pk_add_f32 v[2:3], v[2:3], 1.0 op_sel_hi:[1,0]
	s_nop 0
	s_nop 0
	v_rcp_f32_e32 v3, v3
	s_nop 0
	s_nop 0
	v_rcp_f32_e32 v2, v2
	s_nop 0
	v_cvt_pk_bf16_f32 v2, v2, v3
	v_mul_f32_e32 v3, 0xbfb8aa3b, v14
	v_exp_f32_e32 v4, v3
	v_mul_f32_e32 v3, 0xbfb8aa3b, v15
	v_exp_f32_e32 v5, v3
	s_nop 0
	v_pk_add_f32 v[4:5], v[4:5], 1.0 op_sel_hi:[1,0]
	s_nop 0
	s_nop 0
	v_rcp_f32_e32 v3, v5
	s_nop 0
	s_nop 0
	v_rcp_f32_e32 v4, v4
	s_nop 0
	v_cvt_pk_bf16_f32 v3, v4, v3
	v_mov_b32_e32 v10, v205
	ds_write2_b64 v6, v[0:1], v[2:3] offset0:196 offset1:198
	s_waitcnt lgkmcnt(0)
	s_barrier
	v_mov_b32_e32 v5, v129
	v_lshlrev_b32_e32 v0, 4, v10
	v_and_b32_e32 v4, 0xf0, v0
	v_lshl_add_u64 v[0:1], s[4:5], 0, v[4:5]
	s_mov_b64 s[4:5], 0x26a0000
	v_ashrrev_i32_e32 v5, 4, v10
	v_lshl_add_u64 v[6:7], v[0:1], 0, s[4:5]
	v_mad_u64_u32 v[0:1], s[4:5], v5, s47, v[4:5]
	ds_read_b128 v[0:3], v0
	v_mad_i64_i32 v[8:9], s[4:5], v5, s33, v[6:7]
	s_waitcnt lgkmcnt(0)
	global_store_dwordx4 v[8:9], v[0:3], off
	s_nop 1
	v_add_u32_e32 v0, 0x100, v10
	v_ashrrev_i32_e32 v5, 4, v0
	v_mad_u64_u32 v[0:1], s[4:5], v5, s47, v[4:5]
	ds_read_b128 v[0:3], v0
	v_mad_i64_i32 v[8:9], s[4:5], v5, s33, v[6:7]
	s_waitcnt lgkmcnt(0)
	global_store_dwordx4 v[8:9], v[0:3], off
	s_nop 1
	v_add_u32_e32 v0, 0x200, v10
	v_ashrrev_i32_e32 v5, 4, v0
	v_mad_u64_u32 v[0:1], s[4:5], v5, s47, v[4:5]
	ds_read_b128 v[0:3], v0
	v_mad_i64_i32 v[8:9], s[4:5], v5, s33, v[6:7]
	s_waitcnt lgkmcnt(0)
	global_store_dwordx4 v[8:9], v[0:3], off
	s_nop 1
	v_add_u32_e32 v0, 0x300, v10
	v_ashrrev_i32_e32 v5, 4, v0
	v_mad_u64_u32 v[0:1], s[4:5], v5, s47, v[4:5]
	ds_read_b128 v[0:3], v0
	v_mad_i64_i32 v[8:9], s[4:5], v5, s33, v[6:7]
	s_waitcnt lgkmcnt(0)
	global_store_dwordx4 v[8:9], v[0:3], off
	s_nop 1
	v_add_u32_e32 v0, 0x400, v10
	v_ashrrev_i32_e32 v5, 4, v0
	v_mad_u64_u32 v[0:1], s[4:5], v5, s47, v[4:5]
	ds_read_b128 v[0:3], v0
	v_mad_i64_i32 v[8:9], s[4:5], v5, s33, v[6:7]
	s_waitcnt lgkmcnt(0)
	global_store_dwordx4 v[8:9], v[0:3], off
	s_nop 1
	v_add_u32_e32 v0, 0x500, v10
	v_ashrrev_i32_e32 v5, 4, v0
	v_mad_u64_u32 v[0:1], s[4:5], v5, s47, v[4:5]
	ds_read_b128 v[0:3], v0
	v_mad_i64_i32 v[8:9], s[4:5], v5, s33, v[6:7]
	s_waitcnt lgkmcnt(0)
	global_store_dwordx4 v[8:9], v[0:3], off
	s_nop 1
	v_add_u32_e32 v0, 0x600, v10
	v_ashrrev_i32_e32 v5, 4, v0
	v_mad_u64_u32 v[0:1], s[4:5], v5, s47, v[4:5]
	ds_read_b128 v[0:3], v0
	v_mad_i64_i32 v[8:9], s[4:5], v5, s33, v[6:7]
	s_waitcnt lgkmcnt(0)
	global_store_dwordx4 v[8:9], v[0:3], off
	s_nop 1
	v_add_u32_e32 v0, 0x700, v10
	v_ashrrev_i32_e32 v5, 4, v0
	v_mad_u64_u32 v[0:1], s[4:5], v5, s47, v[4:5]
	ds_read_b128 v[0:3], v0
	v_mad_i64_i32 v[8:9], s[4:5], v5, s33, v[6:7]
	s_waitcnt lgkmcnt(0)
	global_store_dwordx4 v[8:9], v[0:3], off
	s_nop 1
	v_add_u32_e32 v0, 0x800, v10
	v_ashrrev_i32_e32 v5, 4, v0
	v_mad_u64_u32 v[0:1], s[4:5], v5, s47, v[4:5]
	ds_read_b128 v[0:3], v0
	v_mad_i64_i32 v[8:9], s[4:5], v5, s33, v[6:7]
	s_waitcnt lgkmcnt(0)
	global_store_dwordx4 v[8:9], v[0:3], off
	s_nop 1
	v_add_u32_e32 v0, 0x900, v10
	v_ashrrev_i32_e32 v5, 4, v0
	v_mad_u64_u32 v[0:1], s[4:5], v5, s47, v[4:5]
	ds_read_b128 v[0:3], v0
	v_mad_i64_i32 v[8:9], s[4:5], v5, s33, v[6:7]
	s_waitcnt lgkmcnt(0)
	global_store_dwordx4 v[8:9], v[0:3], off
	s_nop 1
	v_add_u32_e32 v0, 0xa00, v10
	v_ashrrev_i32_e32 v5, 4, v0
	v_mad_u64_u32 v[0:1], s[4:5], v5, s47, v[4:5]
	ds_read_b128 v[0:3], v0
	v_mad_i64_i32 v[8:9], s[4:5], v5, s33, v[6:7]
	s_waitcnt lgkmcnt(0)
	global_store_dwordx4 v[8:9], v[0:3], off
	s_nop 1
	v_add_u32_e32 v0, 0xb00, v10
	v_ashrrev_i32_e32 v5, 4, v0
	v_mad_u64_u32 v[0:1], s[4:5], v5, s47, v[4:5]
	ds_read_b128 v[0:3], v0
	v_mad_i64_i32 v[8:9], s[4:5], v5, s33, v[6:7]
	s_waitcnt lgkmcnt(0)
	global_store_dwordx4 v[8:9], v[0:3], off
	s_nop 1
	v_add_u32_e32 v0, 0xc00, v10
	v_ashrrev_i32_e32 v5, 4, v0
	v_mad_u64_u32 v[0:1], s[4:5], v5, s47, v[4:5]
	ds_read_b128 v[0:3], v0
	v_mad_i64_i32 v[8:9], s[4:5], v5, s33, v[6:7]
	s_waitcnt lgkmcnt(0)
	global_store_dwordx4 v[8:9], v[0:3], off
	s_nop 1
	v_add_u32_e32 v0, 0xd00, v10
	v_ashrrev_i32_e32 v5, 4, v0
	v_mad_u64_u32 v[0:1], s[4:5], v5, s47, v[4:5]
	ds_read_b128 v[0:3], v0
	v_mad_i64_i32 v[8:9], s[4:5], v5, s33, v[6:7]
	s_waitcnt lgkmcnt(0)
	global_store_dwordx4 v[8:9], v[0:3], off
	s_nop 1
	v_add_u32_e32 v0, 0xe00, v10
	v_ashrrev_i32_e32 v5, 4, v0
	v_mad_u64_u32 v[0:1], s[4:5], v5, s47, v[4:5]
	ds_read_b128 v[0:3], v0
	v_mad_i64_i32 v[8:9], s[4:5], v5, s33, v[6:7]
	s_waitcnt lgkmcnt(0)
	global_store_dwordx4 v[8:9], v[0:3], off
	s_nop 1
	v_add_u32_e32 v0, 0xf00, v10
	v_ashrrev_i32_e32 v5, 4, v0
	v_mad_u64_u32 v[0:1], s[4:5], v5, s47, v[4:5]
	ds_read_b128 v[0:3], v0
	v_mad_i64_i32 v[4:5], s[4:5], v5, s33, v[6:7]
	s_waitcnt lgkmcnt(0)
	global_store_dwordx4 v[4:5], v[0:3], off

.LBB0_2050:
	v_mov_b32_e32 v128, v205
	s_waitcnt vmcnt(0)
	v_mov_b32_e32 v130, v205
	s_movk_i32 s2, 0xffe0
	v_and_b32_e32 v131, 31, v128
	v_ashrrev_i32_e32 v130, 2, v130
	v_lshrrev_b32_e32 v128, 2, v128
	v_lshlrev_b32_e32 v130, 1, v130
	v_and_b32_e32 v128, 8, v128
	v_and_or_b32 v128, v130, s2, v128
	v_mad_u32_u24 v128, v131, s53, v128
	v_mul_f32_e32 v130, 0xbfb8aa3b, v112
	v_mul_f32_e32 v131, 0xbfb8aa3b, v113
	v_exp_f32_e32 v130, v130
	v_exp_f32_e32 v131, v131
	s_mul_hi_i32 s2, s12, 0x248000
	s_mul_i32 s12, s12, 0x248000
	v_pk_add_f32 v[130:131], v[130:131], 1.0 op_sel_hi:[1,0]
	s_nop 0
	s_nop 0
	v_rcp_f32_e32 v132, v131
	s_nop 0
	v_mul_f32_e32 v113, v113, v132
	s_nop 0
	v_rcp_f32_e32 v131, v130
	s_nop 0
	v_mul_f32_e32 v112, v112, v131
	v_pk_mul_f32 v[112:113], v[120:121], v[112:113]
	s_nop 0
	v_cvt_pk_bf16_f32 v112, v112, v113
	v_mul_f32_e32 v113, 0xbfb8aa3b, v114
	v_exp_f32_e32 v120, v113
	v_mul_f32_e32 v113, 0xbfb8aa3b, v115
	v_exp_f32_e32 v121, v113
	s_nop 0
	v_pk_add_f32 v[120:121], v[120:121], 1.0 op_sel_hi:[1,0]
	s_nop 0
	s_nop 0
	v_rcp_f32_e32 v113, v121
	s_nop 0
	v_mul_f32_e32 v115, v115, v113
	s_nop 0
	v_rcp_f32_e32 v113, v120
	s_nop 0
	v_mul_f32_e32 v114, v114, v113
	v_pk_mul_f32 v[114:115], v[122:123], v[114:115]
	s_nop 0
	v_cvt_pk_bf16_f32 v113, v114, v115
	v_mul_f32_e32 v114, 0xbfb8aa3b, v116
	v_mul_f32_e32 v115, 0xbfb8aa3b, v117
	v_exp_f32_e32 v114, v114
	v_exp_f32_e32 v115, v115
	s_nop 0
	v_pk_add_f32 v[114:115], v[114:115], 1.0 op_sel_hi:[1,0]
	s_nop 0
	s_nop 0
	v_rcp_f32_e32 v120, v115
	s_nop 0
	v_mul_f32_e32 v115, v117, v120
	s_nop 0
	v_rcp_f32_e32 v117, v114
	s_nop 0
	v_mul_f32_e32 v114, v116, v117
	v_pk_mul_f32 v[114:115], v[124:125], v[114:115]
	s_nop 0
	v_cvt_pk_bf16_f32 v114, v114, v115
	v_mul_f32_e32 v115, 0xbfb8aa3b, v118
	v_exp_f32_e32 v116, v115
	v_mul_f32_e32 v115, 0xbfb8aa3b, v119
	v_exp_f32_e32 v117, v115
	s_nop 0
	v_pk_add_f32 v[116:117], v[116:117], 1.0 op_sel_hi:[1,0]
	s_nop 0
	s_nop 0
	v_rcp_f32_e32 v115, v117
	s_nop 0
	v_mul_f32_e32 v117, v119, v115
	s_nop 0
	v_rcp_f32_e32 v115, v116
	s_nop 0
	v_mul_f32_e32 v116, v118, v115
	v_pk_mul_f32 v[116:117], v[126:127], v[116:117]
	s_nop 0
	v_cvt_pk_bf16_f32 v115, v116, v117
	ds_write2_b64 v128, v[112:113], v[114:115] offset1:2
	v_mul_f32_e32 v112, 0xbfb8aa3b, v96
	v_mul_f32_e32 v113, 0xbfb8aa3b, v97
	v_exp_f32_e32 v112, v112
	v_exp_f32_e32 v113, v113
	s_nop 0
	v_pk_add_f32 v[112:113], v[112:113], 1.0 op_sel_hi:[1,0]
	s_nop 0
	s_nop 0
	v_rcp_f32_e32 v114, v113
	s_nop 0
	v_mul_f32_e32 v97, v97, v114
	s_nop 0
	v_rcp_f32_e32 v113, v112
	s_nop 0
	v_mul_f32_e32 v96, v96, v113
	v_pk_mul_f32 v[96:97], v[104:105], v[96:97]
	s_nop 0
	v_cvt_pk_bf16_f32 v96, v96, v97
	v_mul_f32_e32 v97, 0xbfb8aa3b, v98
	v_exp_f32_e32 v104, v97
	v_mul_f32_e32 v97, 0xbfb8aa3b, v99
	v_exp_f32_e32 v105, v97
	s_nop 0
	v_pk_add_f32 v[104:105], v[104:105], 1.0 op_sel_hi:[1,0]
	s_nop 0
	s_nop 0
	v_rcp_f32_e32 v97, v105
	s_nop 0
	v_mul_f32_e32 v99, v99, v97
	s_nop 0
	v_rcp_f32_e32 v97, v104
	s_nop 0
	v_mul_f32_e32 v98, v98, v97
	v_pk_mul_f32 v[98:99], v[106:107], v[98:99]
	s_nop 0
	v_cvt_pk_bf16_f32 v97, v98, v99
	v_mul_f32_e32 v98, 0xbfb8aa3b, v100
	v_mul_f32_e32 v99, 0xbfb8aa3b, v101
	v_exp_f32_e32 v98, v98
	v_exp_f32_e32 v99, v99
	s_nop 0
	v_pk_add_f32 v[98:99], v[98:99], 1.0 op_sel_hi:[1,0]
	s_nop 0
	s_nop 0
	v_rcp_f32_e32 v104, v99
	s_nop 0
	v_mul_f32_e32 v99, v101, v104
	s_nop 0
	v_rcp_f32_e32 v101, v98
	s_nop 0
	v_mul_f32_e32 v98, v100, v101
	v_pk_mul_f32 v[98:99], v[108:109], v[98:99]
	s_nop 0
	v_cvt_pk_bf16_f32 v98, v98, v99
	v_mul_f32_e32 v99, 0xbfb8aa3b, v102
	v_exp_f32_e32 v100, v99
	v_mul_f32_e32 v99, 0xbfb8aa3b, v103
	v_exp_f32_e32 v101, v99
	s_nop 0
	v_pk_add_f32 v[100:101], v[100:101], 1.0 op_sel_hi:[1,0]
	s_nop 0
	s_nop 0
	v_rcp_f32_e32 v99, v101
	s_nop 0
	v_mul_f32_e32 v101, v103, v99
	s_nop 0
	v_rcp_f32_e32 v99, v100
	s_nop 0
	v_mul_f32_e32 v100, v102, v99
	v_pk_mul_f32 v[100:101], v[110:111], v[100:101]
	s_nop 0
	v_cvt_pk_bf16_f32 v99, v100, v101
	v_add_u32_e32 v100, 0x1000, v128
	ds_write2_b64 v100, v[96:97], v[98:99] offset0:64 offset1:66
	v_mul_f32_e32 v96, 0xbfb8aa3b, v80
	v_mul_f32_e32 v97, 0xbfb8aa3b, v81
	v_exp_f32_e32 v96, v96
	v_exp_f32_e32 v97, v97
	s_nop 0
	v_pk_add_f32 v[96:97], v[96:97], 1.0 op_sel_hi:[1,0]
	s_nop 0
	s_nop 0
	v_rcp_f32_e32 v98, v97
	s_nop 0
	v_mul_f32_e32 v81, v81, v98
	s_nop 0
	v_rcp_f32_e32 v97, v96
	s_nop 0
	v_mul_f32_e32 v80, v80, v97
	v_pk_mul_f32 v[80:81], v[88:89], v[80:81]
	s_nop 0
	v_cvt_pk_bf16_f32 v80, v80, v81
	v_mul_f32_e32 v81, 0xbfb8aa3b, v82
	v_exp_f32_e32 v88, v81
	v_mul_f32_e32 v81, 0xbfb8aa3b, v83
	v_exp_f32_e32 v89, v81
	s_nop 0
	v_pk_add_f32 v[88:89], v[88:89], 1.0 op_sel_hi:[1,0]
	s_nop 0
	s_nop 0
	v_rcp_f32_e32 v81, v89
	s_nop 0
	v_mul_f32_e32 v83, v83, v81
	s_nop 0
	v_rcp_f32_e32 v81, v88
	s_nop 0
	v_mul_f32_e32 v82, v82, v81
	v_pk_mul_f32 v[82:83], v[90:91], v[82:83]
	s_nop 0
	v_cvt_pk_bf16_f32 v81, v82, v83
	v_mul_f32_e32 v82, 0xbfb8aa3b, v84
	v_mul_f32_e32 v83, 0xbfb8aa3b, v85
	v_exp_f32_e32 v82, v82
	v_exp_f32_e32 v83, v83
	s_nop 0
	v_pk_add_f32 v[82:83], v[82:83], 1.0 op_sel_hi:[1,0]
	s_nop 0
	s_nop 0
	v_rcp_f32_e32 v88, v83
	s_nop 0
	v_mul_f32_e32 v83, v85, v88
	s_nop 0
	v_rcp_f32_e32 v85, v82
	s_nop 0
	v_mul_f32_e32 v82, v84, v85
	v_pk_mul_f32 v[82:83], v[92:93], v[82:83]
	s_nop 0
	v_cvt_pk_bf16_f32 v82, v82, v83
	v_mul_f32_e32 v83, 0xbfb8aa3b, v86
	v_exp_f32_e32 v84, v83
	v_mul_f32_e32 v83, 0xbfb8aa3b, v87
	v_exp_f32_e32 v85, v83
	s_nop 0
	v_pk_add_f32 v[84:85], v[84:85], 1.0 op_sel_hi:[1,0]
	s_nop 0
	s_nop 0
	v_rcp_f32_e32 v83, v85
	s_nop 0
	v_mul_f32_e32 v85, v87, v83
	s_nop 0
	v_rcp_f32_e32 v83, v84
	s_nop 0
	v_mul_f32_e32 v84, v86, v83
	v_pk_mul_f32 v[84:85], v[94:95], v[84:85]
	s_nop 0
	v_cvt_pk_bf16_f32 v83, v84, v85
	v_add_u32_e32 v84, 0x2000, v128
	ds_write2_b64 v84, v[80:81], v[82:83] offset0:128 offset1:130
	v_mul_f32_e32 v80, 0xbfb8aa3b, v64
	v_mul_f32_e32 v81, 0xbfb8aa3b, v65
	v_exp_f32_e32 v80, v80
	v_exp_f32_e32 v81, v81
	s_nop 0
	v_pk_add_f32 v[80:81], v[80:81], 1.0 op_sel_hi:[1,0]
	s_nop 0
	s_nop 0
	v_rcp_f32_e32 v82, v81
	s_nop 0
	v_mul_f32_e32 v65, v65, v82
	s_nop 0
	v_rcp_f32_e32 v81, v80
	s_nop 0
	v_mul_f32_e32 v64, v64, v81
	v_pk_mul_f32 v[64:65], v[72:73], v[64:65]
	s_nop 0
	v_cvt_pk_bf16_f32 v64, v64, v65
	v_mul_f32_e32 v65, 0xbfb8aa3b, v66
	v_exp_f32_e32 v72, v65
	v_mul_f32_e32 v65, 0xbfb8aa3b, v67
	v_exp_f32_e32 v73, v65
	s_nop 0
	v_pk_add_f32 v[72:73], v[72:73], 1.0 op_sel_hi:[1,0]
	s_nop 0
	s_nop 0
	v_rcp_f32_e32 v65, v73
	s_nop 0
	v_mul_f32_e32 v67, v67, v65
	s_nop 0
	v_rcp_f32_e32 v65, v72
	s_nop 0
	v_mul_f32_e32 v66, v66, v65
	v_pk_mul_f32 v[66:67], v[74:75], v[66:67]
	s_nop 0
	v_cvt_pk_bf16_f32 v65, v66, v67
	v_mul_f32_e32 v66, 0xbfb8aa3b, v68
	v_mul_f32_e32 v67, 0xbfb8aa3b, v69
	v_exp_f32_e32 v66, v66
	v_exp_f32_e32 v67, v67
	s_nop 0
	v_pk_add_f32 v[66:67], v[66:67], 1.0 op_sel_hi:[1,0]
	s_nop 0
	s_nop 0
	v_rcp_f32_e32 v72, v67
	s_nop 0
	v_mul_f32_e32 v67, v69, v72
	s_nop 0
	v_rcp_f32_e32 v69, v66
	s_nop 0
	v_mul_f32_e32 v66, v68, v69
	v_pk_mul_f32 v[66:67], v[76:77], v[66:67]
	s_nop 0
	v_cvt_pk_bf16_f32 v66, v66, v67
	v_mul_f32_e32 v67, 0xbfb8aa3b, v70
	v_exp_f32_e32 v68, v67
	v_mul_f32_e32 v67, 0xbfb8aa3b, v71
	v_exp_f32_e32 v69, v67
	s_nop 0
	v_pk_add_f32 v[68:69], v[68:69], 1.0 op_sel_hi:[1,0]
	s_nop 0
	s_nop 0
	v_rcp_f32_e32 v67, v69
	s_nop 0
	v_mul_f32_e32 v69, v71, v67
	s_nop 0
	v_rcp_f32_e32 v67, v68
	s_nop 0
	v_mul_f32_e32 v68, v70, v67
	v_pk_mul_f32 v[68:69], v[78:79], v[68:69]
	s_nop 0
	v_cvt_pk_bf16_f32 v67, v68, v69
	v_add_u32_e32 v68, 0x3000, v128
	ds_write2_b64 v68, v[64:65], v[66:67] offset0:192 offset1:194
	v_mul_f32_e32 v64, 0xbfb8aa3b, v48
	v_mul_f32_e32 v65, 0xbfb8aa3b, v49
	v_exp_f32_e32 v64, v64
	v_exp_f32_e32 v65, v65
	s_nop 0
	v_pk_add_f32 v[64:65], v[64:65], 1.0 op_sel_hi:[1,0]
	s_nop 0
	s_nop 0
	v_rcp_f32_e32 v66, v65
	s_nop 0
	v_mul_f32_e32 v49, v49, v66
	s_nop 0
	v_rcp_f32_e32 v65, v64
	s_nop 0
	v_mul_f32_e32 v48, v48, v65
	v_pk_mul_f32 v[48:49], v[56:57], v[48:49]
	s_nop 0
	v_cvt_pk_bf16_f32 v48, v48, v49
	v_mul_f32_e32 v49, 0xbfb8aa3b, v50
	v_exp_f32_e32 v56, v49
	v_mul_f32_e32 v49, 0xbfb8aa3b, v51
	v_exp_f32_e32 v57, v49
	s_nop 0
	v_pk_add_f32 v[56:57], v[56:57], 1.0 op_sel_hi:[1,0]
	s_nop 0
	s_nop 0
	v_rcp_f32_e32 v49, v57
	s_nop 0
	v_mul_f32_e32 v51, v51, v49
	s_nop 0
	v_rcp_f32_e32 v49, v56
	s_nop 0
	v_mul_f32_e32 v50, v50, v49
	v_pk_mul_f32 v[50:51], v[58:59], v[50:51]
	s_nop 0
	v_cvt_pk_bf16_f32 v49, v50, v51
	v_mul_f32_e32 v50, 0xbfb8aa3b, v52
	v_mul_f32_e32 v51, 0xbfb8aa3b, v53
	v_exp_f32_e32 v50, v50
	v_exp_f32_e32 v51, v51
	s_nop 0
	v_pk_add_f32 v[50:51], v[50:51], 1.0 op_sel_hi:[1,0]
	s_nop 0
	s_nop 0
	v_rcp_f32_e32 v56, v51
	s_nop 0
	v_mul_f32_e32 v51, v53, v56
	s_nop 0
	v_rcp_f32_e32 v53, v50
	s_nop 0
	v_mul_f32_e32 v50, v52, v53
	v_pk_mul_f32 v[50:51], v[60:61], v[50:51]
	s_nop 0
	v_cvt_pk_bf16_f32 v50, v50, v51
	v_mul_f32_e32 v51, 0xbfb8aa3b, v54
	v_exp_f32_e32 v52, v51
	v_mul_f32_e32 v51, 0xbfb8aa3b, v55
	v_exp_f32_e32 v53, v51
	s_nop 0
	v_pk_add_f32 v[52:53], v[52:53], 1.0 op_sel_hi:[1,0]
	s_nop 0
	s_nop 0
	v_rcp_f32_e32 v51, v53
	s_nop 0
	v_mul_f32_e32 v53, v55, v51
	s_nop 0
	v_rcp_f32_e32 v51, v52
	s_nop 0
	v_mul_f32_e32 v52, v54, v51
	v_pk_mul_f32 v[52:53], v[62:63], v[52:53]
	s_nop 0
	v_cvt_pk_bf16_f32 v51, v52, v53
	v_add_u32_e32 v52, 0x4800, v128
	ds_write2_b64 v52, v[48:49], v[50:51] offset1:2
	v_mul_f32_e32 v48, 0xbfb8aa3b, v32
	v_mul_f32_e32 v49, 0xbfb8aa3b, v33
	v_exp_f32_e32 v48, v48
	v_exp_f32_e32 v49, v49
	s_nop 0
	v_pk_add_f32 v[48:49], v[48:49], 1.0 op_sel_hi:[1,0]
	s_nop 0
	s_nop 0
	v_rcp_f32_e32 v50, v49
	s_nop 0
	v_mul_f32_e32 v33, v33, v50
	s_nop 0
	v_rcp_f32_e32 v49, v48
	s_nop 0
	v_mul_f32_e32 v32, v32, v49
	v_pk_mul_f32 v[32:33], v[40:41], v[32:33]
	s_nop 0
	v_cvt_pk_bf16_f32 v32, v32, v33
	v_mul_f32_e32 v33, 0xbfb8aa3b, v34
	v_exp_f32_e32 v40, v33
	v_mul_f32_e32 v33, 0xbfb8aa3b, v35
	v_exp_f32_e32 v41, v33
	s_nop 0
	v_pk_add_f32 v[40:41], v[40:41], 1.0 op_sel_hi:[1,0]
	s_nop 0
	s_nop 0
	v_rcp_f32_e32 v33, v41
	s_nop 0
	v_mul_f32_e32 v35, v35, v33
	s_nop 0
	v_rcp_f32_e32 v33, v40
	s_nop 0
	v_mul_f32_e32 v34, v34, v33
	v_pk_mul_f32 v[34:35], v[42:43], v[34:35]
	s_nop 0
	v_cvt_pk_bf16_f32 v33, v34, v35
	v_mul_f32_e32 v34, 0xbfb8aa3b, v36
	v_mul_f32_e32 v35, 0xbfb8aa3b, v37
	v_exp_f32_e32 v34, v34
	v_exp_f32_e32 v35, v35
	s_nop 0
	v_pk_add_f32 v[34:35], v[34:35], 1.0 op_sel_hi:[1,0]
	s_nop 0
	s_nop 0
	v_rcp_f32_e32 v40, v35
	s_nop 0
	v_mul_f32_e32 v35, v37, v40
	s_nop 0
	v_rcp_f32_e32 v37, v34
	s_nop 0
	v_mul_f32_e32 v34, v36, v37
	v_pk_mul_f32 v[34:35], v[44:45], v[34:35]
	s_nop 0
	v_cvt_pk_bf16_f32 v34, v34, v35
	v_mul_f32_e32 v35, 0xbfb8aa3b, v38
	v_exp_f32_e32 v36, v35
	v_mul_f32_e32 v35, 0xbfb8aa3b, v39
	v_exp_f32_e32 v37, v35
	s_nop 0
	v_pk_add_f32 v[36:37], v[36:37], 1.0 op_sel_hi:[1,0]
	s_nop 0
	s_nop 0
	v_rcp_f32_e32 v35, v37
	s_nop 0
	v_mul_f32_e32 v37, v39, v35
	s_nop 0
	v_rcp_f32_e32 v35, v36
	s_nop 0
	v_mul_f32_e32 v36, v38, v35
	v_pk_mul_f32 v[36:37], v[46:47], v[36:37]
	s_nop 0
	v_cvt_pk_bf16_f32 v35, v36, v37
	v_add_u32_e32 v36, 0x5800, v128
	ds_write2_b64 v36, v[32:33], v[34:35] offset0:64 offset1:66
	v_mul_f32_e32 v32, 0xbfb8aa3b, v16
	v_mul_f32_e32 v33, 0xbfb8aa3b, v17
	v_exp_f32_e32 v32, v32
	v_exp_f32_e32 v33, v33
	s_nop 0
	v_pk_add_f32 v[32:33], v[32:33], 1.0 op_sel_hi:[1,0]
	s_nop 0
	s_nop 0
	v_rcp_f32_e32 v34, v33
	s_nop 0
	v_mul_f32_e32 v17, v17, v34
	s_nop 0
	v_rcp_f32_e32 v33, v32
	s_nop 0
	v_mul_f32_e32 v16, v16, v33
	v_pk_mul_f32 v[16:17], v[24:25], v[16:17]
	s_nop 0
	v_cvt_pk_bf16_f32 v16, v16, v17
	v_mul_f32_e32 v17, 0xbfb8aa3b, v18
	v_exp_f32_e32 v24, v17
	v_mul_f32_e32 v17, 0xbfb8aa3b, v19
	v_exp_f32_e32 v25, v17
	s_nop 0
	v_pk_add_f32 v[24:25], v[24:25], 1.0 op_sel_hi:[1,0]
	s_nop 0
	s_nop 0
	v_rcp_f32_e32 v17, v25
	s_nop 0
	v_mul_f32_e32 v19, v19, v17
	s_nop 0
	v_rcp_f32_e32 v17, v24
	s_nop 0
	v_mul_f32_e32 v18, v18, v17
	v_pk_mul_f32 v[18:19], v[26:27], v[18:19]
	s_nop 0
	v_cvt_pk_bf16_f32 v17, v18, v19
	v_mul_f32_e32 v18, 0xbfb8aa3b, v20
	v_mul_f32_e32 v19, 0xbfb8aa3b, v21
	v_exp_f32_e32 v18, v18
	v_exp_f32_e32 v19, v19
	s_nop 0
	v_pk_add_f32 v[18:19], v[18:19], 1.0 op_sel_hi:[1,0]
	s_nop 0
	s_nop 0
	v_rcp_f32_e32 v24, v19
	s_nop 0
	v_mul_f32_e32 v19, v21, v24
	s_nop 0
	v_rcp_f32_e32 v21, v18
	s_nop 0
	v_mul_f32_e32 v18, v20, v21
	v_pk_mul_f32 v[18:19], v[28:29], v[18:19]
	s_nop 0
	v_cvt_pk_bf16_f32 v18, v18, v19
	v_mul_f32_e32 v19, 0xbfb8aa3b, v22
	v_exp_f32_e32 v20, v19
	v_mul_f32_e32 v19, 0xbfb8aa3b, v23
	v_exp_f32_e32 v21, v19
	s_nop 0
	v_pk_add_f32 v[20:21], v[20:21], 1.0 op_sel_hi:[1,0]
	s_nop 0
	s_nop 0
	v_rcp_f32_e32 v19, v21
	s_nop 0
	v_mul_f32_e32 v21, v23, v19
	s_nop 0
	v_rcp_f32_e32 v19, v20
	s_nop 0
	v_mul_f32_e32 v20, v22, v19
	v_pk_mul_f32 v[20:21], v[30:31], v[20:21]
	s_nop 0
	v_cvt_pk_bf16_f32 v19, v20, v21
	v_add_u32_e32 v20, 0x6800, v128
	ds_write2_b64 v20, v[16:17], v[18:19] offset0:128 offset1:130
	v_mul_f32_e32 v16, 0xbfb8aa3b, v0
	v_mul_f32_e32 v17, 0xbfb8aa3b, v1
	v_exp_f32_e32 v16, v16
	v_exp_f32_e32 v17, v17
	s_nop 0
	v_pk_add_f32 v[16:17], v[16:17], 1.0 op_sel_hi:[1,0]
	s_nop 0
	s_nop 0
	v_rcp_f32_e32 v18, v17
	s_nop 0
	v_mul_f32_e32 v1, v1, v18
	s_nop 0
	v_rcp_f32_e32 v17, v16
	s_nop 0
	v_mul_f32_e32 v0, v0, v17
	v_pk_mul_f32 v[0:1], v[8:9], v[0:1]
	s_nop 0
	v_cvt_pk_bf16_f32 v0, v0, v1
	v_mul_f32_e32 v1, 0xbfb8aa3b, v2
	v_exp_f32_e32 v8, v1
	v_mul_f32_e32 v1, 0xbfb8aa3b, v3
	v_exp_f32_e32 v9, v1
	s_nop 0
	v_pk_add_f32 v[8:9], v[8:9], 1.0 op_sel_hi:[1,0]
	s_nop 0
	s_nop 0
	v_rcp_f32_e32 v1, v9
	s_nop 0
	v_mul_f32_e32 v3, v3, v1
	s_nop 0
	v_rcp_f32_e32 v1, v8
	s_nop 0
	v_mul_f32_e32 v2, v2, v1
	v_pk_mul_f32 v[2:3], v[10:11], v[2:3]
	s_nop 0
	v_cvt_pk_bf16_f32 v1, v2, v3
	v_mul_f32_e32 v2, 0xbfb8aa3b, v4
	v_mul_f32_e32 v3, 0xbfb8aa3b, v5
	v_exp_f32_e32 v2, v2
	v_exp_f32_e32 v3, v3
	s_nop 0
	v_pk_add_f32 v[2:3], v[2:3], 1.0 op_sel_hi:[1,0]
	s_nop 0
	s_nop 0
	v_rcp_f32_e32 v8, v3
	s_nop 0
	v_mul_f32_e32 v3, v5, v8
	s_nop 0
	v_rcp_f32_e32 v5, v2
	s_nop 0
	v_mul_f32_e32 v2, v4, v5
	v_pk_mul_f32 v[2:3], v[12:13], v[2:3]
	s_nop 0
	v_cvt_pk_bf16_f32 v2, v2, v3
	v_mul_f32_e32 v3, 0xbfb8aa3b, v6
	v_exp_f32_e32 v4, v3
	v_mul_f32_e32 v3, 0xbfb8aa3b, v7
	v_exp_f32_e32 v5, v3
	s_nop 0
	v_pk_add_f32 v[4:5], v[4:5], 1.0 op_sel_hi:[1,0]
	s_nop 0
	s_nop 0
	v_rcp_f32_e32 v3, v5
	s_nop 0
	v_mul_f32_e32 v5, v7, v3
	s_add_u32 s14, s19, s12
	s_addc_u32 s2, s20, s2
	s_lshl_b32 s12, s23, 6
	v_rcp_f32_e32 v3, v4
	s_nop 0
	v_mul_f32_e32 v4, v6, v3
	v_pk_mul_f32 v[4:5], v[14:15], v[4:5]
	s_ashr_i32 s13, s12, 31
	v_cvt_pk_bf16_f32 v3, v4, v5
	v_add_u32_e32 v4, 0x7800, v128
	s_lshl_b64 s[12:13], s[12:13], 1
	v_mov_b32_e32 v10, v205
	ds_write2_b64 v4, v[0:1], v[2:3] offset0:192 offset1:194
	s_waitcnt lgkmcnt(0)
	s_barrier
	s_add_u32 s12, s14, s12
	s_addc_u32 s13, s2, s13
	v_lshlrev_b32_e32 v0, 4, v10
	v_and_b32_e32 v4, 0x70, v0
	v_mov_b32_e32 v5, v129
	v_lshl_add_u64 v[6:7], s[12:13], 0, v[4:5]
	v_ashrrev_i32_e32 v5, 3, v10
	v_mad_u64_u32 v[0:1], s[12:13], v5, s53, v[4:5]
	ds_read_b128 v[0:3], v0
	v_mad_i64_i32 v[8:9], s[12:13], v5, s33, v[6:7]
	s_waitcnt lgkmcnt(0)
	global_store_dwordx4 v[8:9], v[0:3], off
	s_nop 1
	v_add_u32_e32 v0, 0x100, v10
	v_ashrrev_i32_e32 v5, 3, v0
	v_mad_u64_u32 v[0:1], s[12:13], v5, s53, v[4:5]
	ds_read_b128 v[0:3], v0
	v_mad_i64_i32 v[8:9], s[12:13], v5, s33, v[6:7]
	s_waitcnt lgkmcnt(0)
	global_store_dwordx4 v[8:9], v[0:3], off
	s_nop 1
	v_add_u32_e32 v0, 0x200, v10
	v_ashrrev_i32_e32 v5, 3, v0
	v_mad_u64_u32 v[0:1], s[12:13], v5, s53, v[4:5]
	ds_read_b128 v[0:3], v0
	v_mad_i64_i32 v[8:9], s[12:13], v5, s33, v[6:7]
	s_waitcnt lgkmcnt(0)
	global_store_dwordx4 v[8:9], v[0:3], off
	s_nop 1
	v_add_u32_e32 v0, 0x300, v10
	v_ashrrev_i32_e32 v5, 3, v0
	v_mad_u64_u32 v[0:1], s[12:13], v5, s53, v[4:5]
	ds_read_b128 v[0:3], v0
	v_mad_i64_i32 v[8:9], s[12:13], v5, s33, v[6:7]
	s_waitcnt lgkmcnt(0)
	global_store_dwordx4 v[8:9], v[0:3], off
	s_nop 1
	v_add_u32_e32 v0, 0x400, v10
	v_ashrrev_i32_e32 v5, 3, v0
	v_mad_u64_u32 v[0:1], s[12:13], v5, s53, v[4:5]
	ds_read_b128 v[0:3], v0
	v_mad_i64_i32 v[8:9], s[12:13], v5, s33, v[6:7]
	s_waitcnt lgkmcnt(0)
	global_store_dwordx4 v[8:9], v[0:3], off
	s_nop 1
	v_add_u32_e32 v0, 0x500, v10
	v_ashrrev_i32_e32 v5, 3, v0
	v_mad_u64_u32 v[0:1], s[12:13], v5, s53, v[4:5]
	ds_read_b128 v[0:3], v0
	v_mad_i64_i32 v[8:9], s[12:13], v5, s33, v[6:7]
	s_waitcnt lgkmcnt(0)
	global_store_dwordx4 v[8:9], v[0:3], off
	s_nop 1
	v_add_u32_e32 v0, 0x600, v10
	v_ashrrev_i32_e32 v5, 3, v0
	v_mad_u64_u32 v[0:1], s[12:13], v5, s53, v[4:5]
	ds_read_b128 v[0:3], v0
	v_mad_i64_i32 v[8:9], s[12:13], v5, s33, v[6:7]
	s_waitcnt lgkmcnt(0)
	global_store_dwordx4 v[8:9], v[0:3], off
	s_nop 1
	v_add_u32_e32 v0, 0x700, v10
	v_ashrrev_i32_e32 v5, 3, v0
	v_mad_u64_u32 v[0:1], s[12:13], v5, s53, v[4:5]
	ds_read_b128 v[0:3], v0
	v_mad_i64_i32 v[4:5], s[12:13], v5, s33, v[6:7]
	s_waitcnt lgkmcnt(0)
	global_store_dwordx4 v[4:5], v[0:3], off
